# GLU tiles through the hand-written GEMM (sigmoid-gate epilogue, y1 loads up front); SSD items mapped so the four q-blocks of a chunk share an XCD; compiler sp4 code removed
# speedup vs baseline: 1.3002x; 1.0079x over previous
.Lssd_entry:
	s_cmpk_ge_u32 s63, 0xc0
	s_cbranch_scc1 .Lgm_glu_entry
	v_and_b32_e32 v227, 63, v206
	v_lshrrev_b32_e32 v228, 6, v206
	v_and_b32_e32 v0, 15, v227
	v_readfirstlane_b32 s40, v228
	v_lshrrev_b32_e32 v1, 4, v227
	s_and_b32 s42, s63, 7
	s_lshr_b32 s43, s63, 3
	s_mul_i32 s42, s42, 6
	s_lshr_b32 s100, s43, 2
	s_add_u32 s42, s42, s100
	s_and_b32 s43, s43, 3
	s_lshr_b32 s41, s40, 2
	s_lshl_b32 s34, s42, 7
	s_lshl_b32 s35, s43, 5
	s_add_u32 s34, s34, s35
	s_lshl_b32 s100, s42, 4
	s_add_u32 s100, s100, s40
	s_lshl_b32 s100, s100, 9
	s_add_u32 s101, s100, 0xcae4000
	s_add_u32 s48, s96, s101
	s_addc_u32 s49, s97, 0
	s_add_u32 s101, s100, 0xca84000
	s_add_u32 s50, s96, s101
	s_addc_u32 s51, s97, 0
	v_lshrrev_b32_e32 v229, 5, v227
	v_and_b32_e32 v230, 31, v227
	v_lshlrev_b32_e32 v229, 12, v229
	v_lshl_add_u32 v229, v230, 4, v229
	s_lshl_b32 s38, s40, 11
	s_add_u32 s38, s38, 0x10000
	s_mov_b32 m0, s38
	s_nop 0
	global_load_lds_dwordx4 v229, s[48:49]
	s_add_u32 m0, s38, 0x400
	s_nop 0
	global_load_lds_dwordx4 v229, s[50:51]
	s_lshl_b32 s100, s34, 9
	s_lshl_b32 s101, s41, 8
	s_add_u32 s100, s100, s101
	s_add_u32 s100, s100, 0xbb84000
	s_add_u32 s44, s96, s100
	s_addc_u32 s45, s97, 0
	v_lshlrev_b32_e32 v230, 9, v0
	v_lshl_add_u32 v230, v1, 4, v230
	v_add_u32_e32 v231, 0x2000, v230
	global_load_dwordx4 v[4:7], v230, s[44:45]
	global_load_dwordx4 v[8:11], v230, s[44:45] offset:64
	global_load_dwordx4 v[12:15], v230, s[44:45] offset:128
	global_load_dwordx4 v[16:19], v230, s[44:45] offset:192
	global_load_dwordx4 v[20:23], v231, s[44:45]
	global_load_dwordx4 v[24:27], v231, s[44:45] offset:64
	global_load_dwordx4 v[28:31], v231, s[44:45] offset:128
	global_load_dwordx4 v[32:35], v231, s[44:45] offset:192
	s_and_b32 s100, s40, 3
	s_lshl_b32 s101, s100, 5
	s_lshl_b32 s39, s42, 7
	s_add_u32 s101, s101, s39
	s_lshl_b32 s101, s101, 9
	s_lshl_b32 s39, s41, 8
	s_add_u32 s101, s101, s39
	s_add_u32 s101, s101, 0xb884000
	s_add_u32 s46, s96, s101
	s_addc_u32 s47, s97, 0
	s_lshl_b32 s39, s41, 15
	s_lshl_b32 s100, s100, 13
	s_add_u32 s39, s39, s100
	v_and_b32_e32 v230, 15, v227
	v_add_u32_e32 v231, 0, v1
	v_xor_b32_e32 v231, v231, v230
	v_lshlrev_b32_e32 v231, 4, v231
	v_lshl_add_u32 v199, v1, 9, v231
	v_add_u32_e32 v231, 4, v1
	v_xor_b32_e32 v231, v231, v230
	v_lshlrev_b32_e32 v231, 4, v231
	v_lshl_add_u32 v200, v1, 9, v231
	v_add_u32_e32 v231, 8, v1
	v_xor_b32_e32 v231, v231, v230
	v_lshlrev_b32_e32 v231, 4, v231
	v_lshl_add_u32 v201, v1, 9, v231
	v_add_u32_e32 v231, 12, v1
	v_xor_b32_e32 v231, v231, v230
	v_lshlrev_b32_e32 v231, 4, v231
	v_lshl_add_u32 v202, v1, 9, v231
	s_add_u32 m0, s39, 0x0
	s_nop 0
	global_load_lds_dwordx4 v199, s[46:47]
	s_add_u32 s46, s46, 0x800
	s_addc_u32 s47, s47, 0
	s_add_u32 m0, s39, 0x400
	s_nop 0
	global_load_lds_dwordx4 v200, s[46:47]
	s_add_u32 s46, s46, 0x800
	s_addc_u32 s47, s47, 0
	s_add_u32 m0, s39, 0x800
	s_nop 0
	global_load_lds_dwordx4 v201, s[46:47]
	s_add_u32 s46, s46, 0x800
	s_addc_u32 s47, s47, 0
	s_add_u32 m0, s39, 0xc00
	s_nop 0
	global_load_lds_dwordx4 v202, s[46:47]
	s_add_u32 s46, s46, 0x800
	s_addc_u32 s47, s47, 0
	s_add_u32 m0, s39, 0x1000
	s_nop 0
	global_load_lds_dwordx4 v199, s[46:47]
	s_add_u32 s46, s46, 0x800
	s_addc_u32 s47, s47, 0
	s_add_u32 m0, s39, 0x1400
	s_nop 0
	global_load_lds_dwordx4 v200, s[46:47]
	s_add_u32 s46, s46, 0x800
	s_addc_u32 s47, s47, 0
	s_add_u32 m0, s39, 0x1800
	s_nop 0
	global_load_lds_dwordx4 v201, s[46:47]
	s_add_u32 s46, s46, 0x800
	s_addc_u32 s47, s47, 0
	s_add_u32 m0, s39, 0x1c00
	s_nop 0
	global_load_lds_dwordx4 v202, s[46:47]
	v_readlane_b32 s98, v237, 27
	v_readlane_b32 s99, v237, 28
	s_lshl_b32 s100, s36, 11
	s_lshl_b32 s101, s40, 8
	s_add_u32 s100, s100, s101
	s_add_u32 s98, s98, s100
	s_addc_u32 s99, s99, 0
	v_lshlrev_b32_e32 v232, 2, v0
	s_nop 0
	global_load_dword v188, v232, s[98:99]
	global_load_dword v189, v232, s[98:99] offset:64
	global_load_dword v190, v232, s[98:99] offset:128
	global_load_dword v191, v232, s[98:99] offset:192
	v_readlane_b32 s98, v237, 25
	v_readlane_b32 s99, v237, 26
	s_lshl_b32 s100, s36, 3
	s_add_u32 s100, s100, s40
	s_lshl_b32 s100, s100, 2
	s_add_u32 s98, s98, s100
	s_addc_u32 s99, s99, 0
	s_load_dword s92, s[98:99], 0x0
	s_lshl_b32 s100, s42, 3
	s_add_u32 s100, s100, s40
	s_lshl_b32 s100, s100, 14
	s_add_u32 s100, s100, 0xc184000
	s_add_u32 s50, s96, s100
	s_addc_u32 s51, s97, 0
	s_lshl_b32 s100, s42, 4
	s_add_u32 s100, s100, s40
	s_lshl_b32 s100, s100, 14
	s_add_u32 s100, s100, 0xac84000
	s_add_u32 s52, s96, s100
	s_addc_u32 s53, s97, 0
	s_add_u32 s54, s52, 0x20000
	s_addc_u32 s55, s53, 0
	s_mul_i32 s100, s34, 0x2440
	s_lshl_b32 s101, s40, 8
	s_add_u32 s100, s100, s101
	s_add_u32 s100, s100, 0x3a24000
	s_add_u32 s56, s96, s100
	s_addc_u32 s57, s97, 0
	s_lshl_b32 s100, s34, 11
	s_lshl_b32 s101, s40, 7
	s_add_u32 s100, s100, s101
	s_add_u32 s100, s100, 0x7084000
	s_add_u32 s58, s96, s100
	s_addc_u32 s59, s97, 0
	v_lshlrev_b32_e32 v232, 8, v0
	v_lshl_add_u32 v204, v1, 3, v232
	v_lshl_add_u32 v205, v1, 4, v232
	v_mul_u32_u24_e32 v197, 0x9100, v1
	v_lshl_add_u32 v197, v0, 2, v197
	v_lshlrev_b32_e32 v221, 13, v1
	v_lshl_add_u32 v221, v0, 1, v221
	global_load_dwordx2 v[68:69], v204, s[50:51]
	global_load_dwordx2 v[70:71], v204, s[50:51] offset:32
	global_load_dwordx2 v[72:73], v204, s[50:51] offset:64
	global_load_dwordx2 v[74:75], v204, s[50:51] offset:96
	global_load_dwordx2 v[76:77], v204, s[50:51] offset:128
	global_load_dwordx2 v[78:79], v204, s[50:51] offset:160
	global_load_dwordx2 v[80:81], v204, s[50:51] offset:192
	global_load_dwordx2 v[82:83], v204, s[50:51] offset:224
	s_add_u32 s50, s50, 0x1000
	s_addc_u32 s51, s51, 0
	global_load_dwordx4 v[84:87], v205, s[52:53]
	global_load_dwordx4 v[88:91], v205, s[52:53] offset:64
	global_load_dwordx4 v[92:95], v205, s[52:53] offset:128
	global_load_dwordx4 v[96:99], v205, s[52:53] offset:192
	global_load_dwordx4 v[100:103], v205, s[54:55]
	global_load_dwordx4 v[104:107], v205, s[54:55] offset:64
	global_load_dwordx4 v[108:111], v205, s[54:55] offset:128
	global_load_dwordx4 v[112:115], v205, s[54:55] offset:192
	s_add_u32 s52, s52, 0x1000
	s_addc_u32 s53, s53, 0
	s_add_u32 s54, s54, 0x1000
	s_addc_u32 s55, s55, 0
	global_load_dword v180, v197, s[56:57]
	v_add_u32_e32 v233, 0x2440, v197
	global_load_dword v181, v233, s[56:57]
	v_add_u32_e32 v233, 0x4880, v197
	global_load_dword v182, v233, s[56:57]
	v_add_u32_e32 v233, 0x6cc0, v197
	global_load_dword v183, v233, s[56:57]
	v_add_u32_e32 v233, 0x24400, v197
	global_load_dword v184, v233, s[56:57]
	v_add_u32_e32 v233, 0x26840, v197
	global_load_dword v185, v233, s[56:57]
	v_add_u32_e32 v233, 0x28c80, v197
	global_load_dword v186, v233, s[56:57]
	v_add_u32_e32 v233, 0x2b0c0, v197
	global_load_dword v187, v233, s[56:57]
	v_sub_u32_e32 v3, v0, v1
	v_sub_u32_e32 v3, v3, v1
	v_sub_u32_e32 v3, v3, v1
	v_sub_u32_e32 v3, v3, v1
	s_lshl_b32 s39, s41, 15
	v_add_u32_e32 v231, 0, v1
	v_xor_b32_e32 v231, v231, v0
	v_lshlrev_b32_e32 v231, 4, v231
	v_lshl_add_u32 v199, v0, 8, v231
	v_add_u32_e32 v231, 4, v1
	v_xor_b32_e32 v231, v231, v0
	v_lshlrev_b32_e32 v231, 4, v231
	v_lshl_add_u32 v200, v0, 8, v231
	v_add_u32_e32 v231, 8, v1
	v_xor_b32_e32 v231, v231, v0
	v_lshlrev_b32_e32 v231, 4, v231
	v_lshl_add_u32 v201, v0, 8, v231
	v_add_u32_e32 v231, 12, v1
	v_xor_b32_e32 v231, v231, v0
	v_lshlrev_b32_e32 v231, 4, v231
	v_lshl_add_u32 v202, v0, 8, v231
	v_add_u32_e32 v199, s39, v199
	v_add_u32_e32 v200, s39, v200
	v_add_u32_e32 v201, s39, v201
	v_add_u32_e32 v202, s39, v202
	v_lshl_add_u32 v203, v1, 4, s38
	s_lshl_b32 s100, s40, 13
	v_lshl_add_u32 v225, v227, 4, s100
	s_lshl_b32 s100, s40, 2
	s_add_u32 s100, s100, 0x14000
	v_lshl_add_u32 v226, v1, 7, s100
	s_lshl_b32 s39, s43, 1
	s_waitcnt vmcnt(28) lgkmcnt(0)
	v_mov_b32_e32 v224, s92
	s_barrier
	s_lshl_b32 s100, s35, 2
	s_add_u32 s100, s100, s38
	v_lshl_add_u32 v232, v0, 2, s100
	s_nop 0
	ds_read_b32 v192, v232 offset:0
	ds_read_b32 v194, v232 offset:512
	ds_read_b32 v222, v232 offset:1024
	ds_read_b32 v227, v232 offset:1536
	ds_read_b32 v193, v232 offset:64
	ds_read_b32 v195, v232 offset:576
	ds_read_b32 v223, v232 offset:1088
	ds_read_b32 v228, v232 offset:1600
	ds_read_b128 v[132:135], v199 offset:0
	ds_read_b128 v[136:139], v200 offset:0
	ds_read_b128 v[140:143], v201 offset:0
	ds_read_b128 v[144:147], v202 offset:0
	ds_read_b128 v[148:151], v199 offset:4096
	ds_read_b128 v[152:155], v200 offset:4096
	ds_read_b128 v[156:159], v201 offset:4096
	ds_read_b128 v[160:163], v202 offset:4096
	ds_read_b128 v[164:167], v203 offset:0
	ds_read_b128 v[168:171], v203 offset:512
	ds_read_b128 v[172:175], v203 offset:1024
	ds_read_b128 v[176:179], v203 offset:1536
	s_waitcnt lgkmcnt(8)
	v_add_f32_e32 v222, v222, v227
	v_add_f32_e32 v223, v223, v228
	v_mfma_f32_16x16x32_bf16 v[116:119], v[132:135], v[4:7], 0
	v_mfma_f32_16x16x32_bf16 v[120:123], v[132:135], v[20:23], 0
	v_mfma_f32_16x16x32_bf16 v[116:119], v[136:139], v[8:11], v[116:119]
	v_mfma_f32_16x16x32_bf16 v[120:123], v[136:139], v[24:27], v[120:123]
	v_mfma_f32_16x16x32_bf16 v[116:119], v[140:143], v[12:15], v[116:119]
	v_mfma_f32_16x16x32_bf16 v[120:123], v[140:143], v[28:31], v[120:123]
	v_mfma_f32_16x16x32_bf16 v[116:119], v[144:147], v[16:19], v[116:119]
	v_mfma_f32_16x16x32_bf16 v[120:123], v[144:147], v[32:35], v[120:123]
	s_waitcnt lgkmcnt(4)
	v_mfma_f32_16x16x32_bf16 v[124:127], v[148:151], v[4:7], 0
	v_mfma_f32_16x16x32_bf16 v[128:131], v[148:151], v[20:23], 0
	v_mfma_f32_16x16x32_bf16 v[124:127], v[152:155], v[8:11], v[124:127]
	v_mfma_f32_16x16x32_bf16 v[128:131], v[152:155], v[24:27], v[128:131]
	v_mfma_f32_16x16x32_bf16 v[124:127], v[156:159], v[12:15], v[124:127]
	v_mfma_f32_16x16x32_bf16 v[128:131], v[156:159], v[28:31], v[128:131]
	v_mfma_f32_16x16x32_bf16 v[124:127], v[160:163], v[16:19], v[124:127]
	v_mfma_f32_16x16x32_bf16 v[128:131], v[160:163], v[32:35], v[128:131]
	ds_read_b128 v[132:135], v199 offset:8192
	ds_read_b128 v[136:139], v200 offset:8192
	ds_read_b128 v[140:143], v201 offset:8192
	ds_read_b128 v[144:147], v202 offset:8192
	s_waitcnt lgkmcnt(4)
	s_cmp_gt_u32 s39, 0
	s_cbranch_scc1 .Lssd_f0
	s_cmp_lt_u32 s39, 0
	s_cbranch_scc1 .Lssd_b0
	v_cmp_lt_i32_e32 vcc, 0, v3
	s_nop 1
	v_cndmask_b32_e32 v230, v168, v164, vcc
	v_cndmask_b32_e32 v231, v176, v172, vcc
	v_cndmask_b32_e32 v229, v194, v192, vcc
	v_sub_f32_e32 v229, v229, v230
	v_mul_f32_e32 v229, 0x3fb8aa3b, v229
	v_exp_f32_e32 v229, v229
	v_cmp_eq_u32_e32 vcc, 0, v3
	v_mul_f32_e32 v229, v229, v231
	s_nop 0
	v_cndmask_b32_e32 v229, v229, v222, vcc
	v_cndmask_b32_e32 v230, 0, v224, vcc
	v_fma_f32 v116, v116, v229, v230
	v_cmp_lt_i32_e32 vcc, 1, v3
	s_nop 1
	v_cndmask_b32_e32 v230, v169, v165, vcc
	v_cndmask_b32_e32 v231, v177, v173, vcc
	v_cndmask_b32_e32 v229, v194, v192, vcc
	v_sub_f32_e32 v229, v229, v230
	v_mul_f32_e32 v229, 0x3fb8aa3b, v229
	v_exp_f32_e32 v229, v229
	v_cmp_eq_u32_e32 vcc, 1, v3
	v_mul_f32_e32 v229, v229, v231
	s_nop 0
	v_cndmask_b32_e32 v229, v229, v222, vcc
	v_cndmask_b32_e32 v230, 0, v224, vcc
	v_fma_f32 v117, v117, v229, v230
	v_cmp_lt_i32_e32 vcc, 2, v3
	s_nop 1
	v_cndmask_b32_e32 v230, v170, v166, vcc
	v_cndmask_b32_e32 v231, v178, v174, vcc
	v_cndmask_b32_e32 v229, v194, v192, vcc
	v_sub_f32_e32 v229, v229, v230
	v_mul_f32_e32 v229, 0x3fb8aa3b, v229
	v_exp_f32_e32 v229, v229
	v_cmp_eq_u32_e32 vcc, 2, v3
	v_mul_f32_e32 v229, v229, v231
	s_nop 0
	v_cndmask_b32_e32 v229, v229, v222, vcc
	v_cndmask_b32_e32 v230, 0, v224, vcc
	v_fma_f32 v118, v118, v229, v230
	v_cmp_lt_i32_e32 vcc, 3, v3
	s_nop 1
	v_cndmask_b32_e32 v230, v171, v167, vcc
	v_cndmask_b32_e32 v231, v179, v175, vcc
	v_cndmask_b32_e32 v229, v194, v192, vcc
	v_sub_f32_e32 v229, v229, v230
	v_mul_f32_e32 v229, 0x3fb8aa3b, v229
	v_exp_f32_e32 v229, v229
	v_cmp_eq_u32_e32 vcc, 3, v3
	v_mul_f32_e32 v229, v229, v231
	s_nop 0
	v_cndmask_b32_e32 v229, v229, v222, vcc
	v_cndmask_b32_e32 v230, 0, v224, vcc
	v_fma_f32 v119, v119, v229, v230
	s_branch .Lssd_j0

.Lssd_j15:
	v_cvt_pk_bf16_f32 v66, v128, v129
	v_cvt_pk_bf16_f32 v67, v130, v131
	s_barrier
	s_lshl_b32 s100, s35, 2
	v_add_u32_e32 v232, s100, v203
	s_nop 0
	ds_read_b128 v[140:143], v232 offset:0
	ds_read_b128 v[148:151], v232 offset:512
	ds_read_b128 v[144:147], v232 offset:64
	ds_read_b128 v[152:155], v232 offset:576
	v_mov_b32_e32 v156, 0
	v_mov_b32_e32 v157, 0
	v_mov_b32_e32 v158, 0
	v_mov_b32_e32 v159, 0
	v_mov_b32_e32 v160, 0
	v_mov_b32_e32 v161, 0
	v_mov_b32_e32 v162, 0
	v_mov_b32_e32 v163, 0
	s_waitcnt lgkmcnt(0)
	v_mul_f32_e32 v140, 0x3fb8aa3b, v140
	v_mul_f32_e32 v141, 0x3fb8aa3b, v141
	v_mul_f32_e32 v142, 0x3fb8aa3b, v142
	v_mul_f32_e32 v143, 0x3fb8aa3b, v143
	v_mul_f32_e32 v144, 0x3fb8aa3b, v144
	v_mul_f32_e32 v145, 0x3fb8aa3b, v145
	v_mul_f32_e32 v146, 0x3fb8aa3b, v146
	v_mul_f32_e32 v147, 0x3fb8aa3b, v147
	v_exp_f32_e32 v140, v140
	v_exp_f32_e32 v141, v141
	v_exp_f32_e32 v142, v142
	v_exp_f32_e32 v143, v143
	v_exp_f32_e32 v144, v144
	v_exp_f32_e32 v145, v145
	v_exp_f32_e32 v146, v146
	v_exp_f32_e32 v147, v147
	v_mul_f32_e32 v148, 0x3fb8aa3b, v148
	v_mul_f32_e32 v149, 0x3fb8aa3b, v149
	v_mul_f32_e32 v150, 0x3fb8aa3b, v150
	v_mul_f32_e32 v151, 0x3fb8aa3b, v151
	v_mul_f32_e32 v152, 0x3fb8aa3b, v152
	v_mul_f32_e32 v153, 0x3fb8aa3b, v153
	v_mul_f32_e32 v154, 0x3fb8aa3b, v154
	v_mul_f32_e32 v155, 0x3fb8aa3b, v155
	v_exp_f32_e32 v148, v148
	v_exp_f32_e32 v149, v149
	v_exp_f32_e32 v150, v150
	v_exp_f32_e32 v151, v151
	v_exp_f32_e32 v152, v152
	v_exp_f32_e32 v153, v153
	v_exp_f32_e32 v154, v154
	v_exp_f32_e32 v155, v155
	s_waitcnt vmcnt(16)
	v_mfma_f32_16x16x32_bf16 v[116:119], v[36:39], v[68:71], 0
	v_mfma_f32_16x16x32_bf16 v[120:123], v[52:55], v[68:71], 0
	v_mfma_f32_16x16x32_bf16 v[116:119], v[40:43], v[72:75], v[116:119]
	v_mfma_f32_16x16x32_bf16 v[120:123], v[56:59], v[72:75], v[120:123]
	v_mfma_f32_16x16x32_bf16 v[116:119], v[44:47], v[76:79], v[116:119]
	v_mfma_f32_16x16x32_bf16 v[120:123], v[60:63], v[76:79], v[120:123]
	v_mfma_f32_16x16x32_bf16 v[116:119], v[48:51], v[80:83], v[116:119]
	v_mfma_f32_16x16x32_bf16 v[120:123], v[64:67], v[80:83], v[120:123]
	global_load_dwordx2 v[68:69], v204, s[50:51]
	global_load_dwordx2 v[70:71], v204, s[50:51] offset:32
	global_load_dwordx2 v[72:73], v204, s[50:51] offset:64
	global_load_dwordx2 v[74:75], v204, s[50:51] offset:96
	global_load_dwordx2 v[76:77], v204, s[50:51] offset:128
	global_load_dwordx2 v[78:79], v204, s[50:51] offset:160
	global_load_dwordx2 v[80:81], v204, s[50:51] offset:192
	global_load_dwordx2 v[82:83], v204, s[50:51] offset:224
	s_add_u32 s50, s50, 0x1000
	s_addc_u32 s51, s51, 0
	s_waitcnt vmcnt(16)
	v_mfma_f32_16x16x32_bf16 v[124:127], v[4:7], v[84:87], 0
	v_mfma_f32_16x16x32_bf16 v[132:135], v[4:7], v[100:103], 0
	v_mfma_f32_16x16x32_bf16 v[128:131], v[20:23], v[84:87], 0
	v_mfma_f32_16x16x32_bf16 v[136:139], v[20:23], v[100:103], 0
	v_mfma_f32_16x16x32_bf16 v[124:127], v[8:11], v[88:91], v[124:127]
	v_mfma_f32_16x16x32_bf16 v[132:135], v[8:11], v[104:107], v[132:135]
	v_mfma_f32_16x16x32_bf16 v[128:131], v[24:27], v[88:91], v[128:131]
	v_mfma_f32_16x16x32_bf16 v[136:139], v[24:27], v[104:107], v[136:139]
	v_mfma_f32_16x16x32_bf16 v[124:127], v[12:15], v[92:95], v[124:127]
	v_mfma_f32_16x16x32_bf16 v[132:135], v[12:15], v[108:111], v[132:135]
	v_mfma_f32_16x16x32_bf16 v[128:131], v[28:31], v[92:95], v[128:131]
	v_mfma_f32_16x16x32_bf16 v[136:139], v[28:31], v[108:111], v[136:139]
	v_mfma_f32_16x16x32_bf16 v[124:127], v[16:19], v[96:99], v[124:127]
	v_mfma_f32_16x16x32_bf16 v[132:135], v[16:19], v[112:115], v[132:135]
	v_mfma_f32_16x16x32_bf16 v[128:131], v[32:35], v[96:99], v[128:131]
	v_mfma_f32_16x16x32_bf16 v[136:139], v[32:35], v[112:115], v[136:139]
	global_load_dwordx4 v[84:87], v205, s[52:53]
	global_load_dwordx4 v[88:91], v205, s[52:53] offset:64
	global_load_dwordx4 v[92:95], v205, s[52:53] offset:128
	global_load_dwordx4 v[96:99], v205, s[52:53] offset:192
	global_load_dwordx4 v[100:103], v205, s[54:55]
	global_load_dwordx4 v[104:107], v205, s[54:55] offset:64
	global_load_dwordx4 v[108:111], v205, s[54:55] offset:128
	global_load_dwordx4 v[112:115], v205, s[54:55] offset:192
	s_add_u32 s52, s52, 0x1000
	s_addc_u32 s53, s53, 0
	s_add_u32 s54, s54, 0x1000
	s_addc_u32 s55, s55, 0
	global_load_dword v172, v197, s[56:57] offset:64
	v_add_u32_e32 v233, 0x2440, v197
	global_load_dword v173, v233, s[56:57] offset:64
	v_add_u32_e32 v233, 0x4880, v197
	global_load_dword v174, v233, s[56:57] offset:64
	v_add_u32_e32 v233, 0x6cc0, v197
	global_load_dword v175, v233, s[56:57] offset:64
	v_add_u32_e32 v233, 0x24400, v197
	global_load_dword v176, v233, s[56:57] offset:64
	v_add_u32_e32 v233, 0x26840, v197
	global_load_dword v177, v233, s[56:57] offset:64
	v_add_u32_e32 v233, 0x28c80, v197
	global_load_dword v178, v233, s[56:57] offset:64
	v_add_u32_e32 v233, 0x2b0c0, v197
	global_load_dword v179, v233, s[56:57] offset:64
	s_waitcnt vmcnt(24)
	s_nop 7
	v_fma_f32 v164, v140, v124, v116
	v_fma_f32 v165, v141, v125, v117
	v_fma_f32 v166, v142, v126, v118
	v_fma_f32 v167, v143, v127, v119
	v_fma_f32 v164, v148, v132, v164
	v_fma_f32 v165, v149, v133, v165
	v_fma_f32 v166, v150, v134, v166
	v_fma_f32 v167, v151, v135, v167
	v_mul_f32_e32 v227, 0xbfb8aa3b, v180
	v_mul_f32_e32 v228, 0xbfb8aa3b, v181
	v_mul_f32_e32 v229, 0xbfb8aa3b, v182
	v_mul_f32_e32 v230, 0xbfb8aa3b, v183
	v_exp_f32_e32 v227, v227
	v_exp_f32_e32 v228, v228
	v_exp_f32_e32 v229, v229
	v_exp_f32_e32 v230, v230
	s_nop 0
	v_add_f32_e32 v227, 1.0, v227
	v_add_f32_e32 v228, 1.0, v228
	v_add_f32_e32 v229, 1.0, v229
	v_add_f32_e32 v230, 1.0, v230
	v_div_scale_f32 v231, s[100:101], v227, v227, v180
	v_rcp_f32_e32 v232, v231
	s_nop 0
	v_fma_f32 v233, -v231, v232, 1.0
	v_fmac_f32_e32 v232, v233, v232
	v_div_scale_f32 v233, vcc, v180, v227, v180
	v_mul_f32_e32 v192, v233, v232
	v_fma_f32 v193, -v231, v192, v233
	v_fmac_f32_e32 v192, v193, v232
	v_fma_f32 v231, -v231, v192, v233
	v_div_fmas_f32 v231, v231, v232, v192
	v_div_fixup_f32 v227, v231, v227, v180
	v_mul_f32_e32 v164, v164, v227
	v_fmac_f32_e32 v156, v164, v164
	v_div_scale_f32 v231, s[100:101], v228, v228, v181
	v_rcp_f32_e32 v232, v231
	s_nop 0
	v_fma_f32 v233, -v231, v232, 1.0
	v_fmac_f32_e32 v232, v233, v232
	v_div_scale_f32 v233, vcc, v181, v228, v181
	v_mul_f32_e32 v192, v233, v232
	v_fma_f32 v193, -v231, v192, v233
	v_fmac_f32_e32 v192, v193, v232
	v_fma_f32 v231, -v231, v192, v233
	v_div_fmas_f32 v231, v231, v232, v192
	v_div_fixup_f32 v228, v231, v228, v181
	v_mul_f32_e32 v165, v165, v228
	v_fmac_f32_e32 v157, v165, v165
	v_div_scale_f32 v231, s[100:101], v229, v229, v182
	v_rcp_f32_e32 v232, v231
	s_nop 0
	v_fma_f32 v233, -v231, v232, 1.0
	v_fmac_f32_e32 v232, v233, v232
	v_div_scale_f32 v233, vcc, v182, v229, v182
	v_mul_f32_e32 v192, v233, v232
	v_fma_f32 v193, -v231, v192, v233
	v_fmac_f32_e32 v192, v193, v232
	v_fma_f32 v231, -v231, v192, v233
	v_div_fmas_f32 v231, v231, v232, v192
	v_div_fixup_f32 v229, v231, v229, v182
	v_mul_f32_e32 v166, v166, v229
	v_fmac_f32_e32 v158, v166, v166
	v_div_scale_f32 v231, s[100:101], v230, v230, v183
	v_rcp_f32_e32 v232, v231
	s_nop 0
	v_fma_f32 v233, -v231, v232, 1.0
	v_fmac_f32_e32 v232, v233, v232
	v_div_scale_f32 v233, vcc, v183, v230, v183
	v_mul_f32_e32 v192, v233, v232
	v_fma_f32 v193, -v231, v192, v233
	v_fmac_f32_e32 v192, v193, v232
	v_fma_f32 v231, -v231, v192, v233
	v_div_fmas_f32 v231, v231, v232, v192
	v_div_fixup_f32 v230, v231, v230, v183
	v_mul_f32_e32 v167, v167, v230
	v_fmac_f32_e32 v159, v167, v167
	ds_write_b128 v225, v[164:167] offset:0
	v_fma_f32 v168, v144, v128, v120
	v_fma_f32 v169, v145, v129, v121
	v_fma_f32 v170, v146, v130, v122
	v_fma_f32 v171, v147, v131, v123
	v_fma_f32 v168, v152, v136, v168
	v_fma_f32 v169, v153, v137, v169
	v_fma_f32 v170, v154, v138, v170
	v_fma_f32 v171, v155, v139, v171
	v_mul_f32_e32 v227, 0xbfb8aa3b, v184
	v_mul_f32_e32 v228, 0xbfb8aa3b, v185
	v_mul_f32_e32 v229, 0xbfb8aa3b, v186
	v_mul_f32_e32 v230, 0xbfb8aa3b, v187
	v_exp_f32_e32 v227, v227
	v_exp_f32_e32 v228, v228
	v_exp_f32_e32 v229, v229
	v_exp_f32_e32 v230, v230
	s_nop 0
	v_add_f32_e32 v227, 1.0, v227
	v_add_f32_e32 v228, 1.0, v228
	v_add_f32_e32 v229, 1.0, v229
	v_add_f32_e32 v230, 1.0, v230
	v_div_scale_f32 v231, s[100:101], v227, v227, v184
	v_rcp_f32_e32 v232, v231
	s_nop 0
	v_fma_f32 v233, -v231, v232, 1.0
	v_fmac_f32_e32 v232, v233, v232
	v_div_scale_f32 v233, vcc, v184, v227, v184
	v_mul_f32_e32 v192, v233, v232
	v_fma_f32 v193, -v231, v192, v233
	v_fmac_f32_e32 v192, v193, v232
	v_fma_f32 v231, -v231, v192, v233
	v_div_fmas_f32 v231, v231, v232, v192
	v_div_fixup_f32 v227, v231, v227, v184
	v_mul_f32_e32 v168, v168, v227
	v_fmac_f32_e32 v160, v168, v168
	v_div_scale_f32 v231, s[100:101], v228, v228, v185
	v_rcp_f32_e32 v232, v231
	s_nop 0
	v_fma_f32 v233, -v231, v232, 1.0
	v_fmac_f32_e32 v232, v233, v232
	v_div_scale_f32 v233, vcc, v185, v228, v185
	v_mul_f32_e32 v192, v233, v232
	v_fma_f32 v193, -v231, v192, v233
	v_fmac_f32_e32 v192, v193, v232
	v_fma_f32 v231, -v231, v192, v233
	v_div_fmas_f32 v231, v231, v232, v192
	v_div_fixup_f32 v228, v231, v228, v185
	v_mul_f32_e32 v169, v169, v228
	v_fmac_f32_e32 v161, v169, v169
	v_div_scale_f32 v231, s[100:101], v229, v229, v186
	v_rcp_f32_e32 v232, v231
	s_nop 0
	v_fma_f32 v233, -v231, v232, 1.0
	v_fmac_f32_e32 v232, v233, v232
	v_div_scale_f32 v233, vcc, v186, v229, v186
	v_mul_f32_e32 v192, v233, v232
	v_fma_f32 v193, -v231, v192, v233
	v_fmac_f32_e32 v192, v193, v232
	v_fma_f32 v231, -v231, v192, v233
	v_div_fmas_f32 v231, v231, v232, v192
	v_div_fixup_f32 v229, v231, v229, v186
	v_mul_f32_e32 v170, v170, v229
	v_fmac_f32_e32 v162, v170, v170
	v_div_scale_f32 v231, s[100:101], v230, v230, v187
	v_rcp_f32_e32 v232, v231
	s_nop 0
	v_fma_f32 v233, -v231, v232, 1.0
	v_fmac_f32_e32 v232, v233, v232
	v_div_scale_f32 v233, vcc, v187, v230, v187
	v_mul_f32_e32 v192, v233, v232
	v_fma_f32 v193, -v231, v192, v233
	v_fmac_f32_e32 v192, v193, v232
	v_fma_f32 v231, -v231, v192, v233
	v_div_fmas_f32 v231, v231, v232, v192
	v_div_fixup_f32 v230, v231, v230, v187
	v_mul_f32_e32 v171, v171, v230
	v_fmac_f32_e32 v163, v171, v171
	ds_write_b128 v225, v[168:171] offset:1024
	s_waitcnt vmcnt(16)
	v_mfma_f32_16x16x32_bf16 v[116:119], v[36:39], v[68:71], 0
	v_mfma_f32_16x16x32_bf16 v[120:123], v[52:55], v[68:71], 0
	v_mfma_f32_16x16x32_bf16 v[116:119], v[40:43], v[72:75], v[116:119]
	v_mfma_f32_16x16x32_bf16 v[120:123], v[56:59], v[72:75], v[120:123]
	v_mfma_f32_16x16x32_bf16 v[116:119], v[44:47], v[76:79], v[116:119]
	v_mfma_f32_16x16x32_bf16 v[120:123], v[60:63], v[76:79], v[120:123]
	v_mfma_f32_16x16x32_bf16 v[116:119], v[48:51], v[80:83], v[116:119]
	v_mfma_f32_16x16x32_bf16 v[120:123], v[64:67], v[80:83], v[120:123]
	global_load_dwordx2 v[68:69], v204, s[50:51]
	global_load_dwordx2 v[70:71], v204, s[50:51] offset:32
	global_load_dwordx2 v[72:73], v204, s[50:51] offset:64
	global_load_dwordx2 v[74:75], v204, s[50:51] offset:96
	global_load_dwordx2 v[76:77], v204, s[50:51] offset:128
	global_load_dwordx2 v[78:79], v204, s[50:51] offset:160
	global_load_dwordx2 v[80:81], v204, s[50:51] offset:192
	global_load_dwordx2 v[82:83], v204, s[50:51] offset:224
	s_add_u32 s50, s50, 0x1000
	s_addc_u32 s51, s51, 0
	s_waitcnt vmcnt(16)
	v_mfma_f32_16x16x32_bf16 v[124:127], v[4:7], v[84:87], 0
	v_mfma_f32_16x16x32_bf16 v[132:135], v[4:7], v[100:103], 0
	v_mfma_f32_16x16x32_bf16 v[128:131], v[20:23], v[84:87], 0
	v_mfma_f32_16x16x32_bf16 v[136:139], v[20:23], v[100:103], 0
	v_mfma_f32_16x16x32_bf16 v[124:127], v[8:11], v[88:91], v[124:127]
	v_mfma_f32_16x16x32_bf16 v[132:135], v[8:11], v[104:107], v[132:135]
	v_mfma_f32_16x16x32_bf16 v[128:131], v[24:27], v[88:91], v[128:131]
	v_mfma_f32_16x16x32_bf16 v[136:139], v[24:27], v[104:107], v[136:139]
	v_mfma_f32_16x16x32_bf16 v[124:127], v[12:15], v[92:95], v[124:127]
	v_mfma_f32_16x16x32_bf16 v[132:135], v[12:15], v[108:111], v[132:135]
	v_mfma_f32_16x16x32_bf16 v[128:131], v[28:31], v[92:95], v[128:131]
	v_mfma_f32_16x16x32_bf16 v[136:139], v[28:31], v[108:111], v[136:139]
	v_mfma_f32_16x16x32_bf16 v[124:127], v[16:19], v[96:99], v[124:127]
	v_mfma_f32_16x16x32_bf16 v[132:135], v[16:19], v[112:115], v[132:135]
	v_mfma_f32_16x16x32_bf16 v[128:131], v[32:35], v[96:99], v[128:131]
	v_mfma_f32_16x16x32_bf16 v[136:139], v[32:35], v[112:115], v[136:139]
	global_load_dwordx4 v[84:87], v205, s[52:53]
	global_load_dwordx4 v[88:91], v205, s[52:53] offset:64
	global_load_dwordx4 v[92:95], v205, s[52:53] offset:128
	global_load_dwordx4 v[96:99], v205, s[52:53] offset:192
	global_load_dwordx4 v[100:103], v205, s[54:55]
	global_load_dwordx4 v[104:107], v205, s[54:55] offset:64
	global_load_dwordx4 v[108:111], v205, s[54:55] offset:128
	global_load_dwordx4 v[112:115], v205, s[54:55] offset:192
	s_add_u32 s52, s52, 0x1000
	s_addc_u32 s53, s53, 0
	s_add_u32 s54, s54, 0x1000
	s_addc_u32 s55, s55, 0
	global_load_dword v180, v197, s[56:57] offset:128
	v_add_u32_e32 v233, 0x2440, v197
	global_load_dword v181, v233, s[56:57] offset:128
	v_add_u32_e32 v233, 0x4880, v197
	global_load_dword v182, v233, s[56:57] offset:128
	v_add_u32_e32 v233, 0x6cc0, v197
	global_load_dword v183, v233, s[56:57] offset:128
	v_add_u32_e32 v233, 0x24400, v197
	global_load_dword v184, v233, s[56:57] offset:128
	v_add_u32_e32 v233, 0x26840, v197
	global_load_dword v185, v233, s[56:57] offset:128
	v_add_u32_e32 v233, 0x28c80, v197
	global_load_dword v186, v233, s[56:57] offset:128
	v_add_u32_e32 v233, 0x2b0c0, v197
	global_load_dword v187, v233, s[56:57] offset:128
	s_waitcnt vmcnt(24)
	s_nop 7
	v_fma_f32 v164, v140, v124, v116
	v_fma_f32 v165, v141, v125, v117
	v_fma_f32 v166, v142, v126, v118
	v_fma_f32 v167, v143, v127, v119
	v_fma_f32 v164, v148, v132, v164
	v_fma_f32 v165, v149, v133, v165
	v_fma_f32 v166, v150, v134, v166
	v_fma_f32 v167, v151, v135, v167
	v_mul_f32_e32 v227, 0xbfb8aa3b, v172
	v_mul_f32_e32 v228, 0xbfb8aa3b, v173
	v_mul_f32_e32 v229, 0xbfb8aa3b, v174
	v_mul_f32_e32 v230, 0xbfb8aa3b, v175
	v_exp_f32_e32 v227, v227
	v_exp_f32_e32 v228, v228
	v_exp_f32_e32 v229, v229
	v_exp_f32_e32 v230, v230
	s_nop 0
	v_add_f32_e32 v227, 1.0, v227
	v_add_f32_e32 v228, 1.0, v228
	v_add_f32_e32 v229, 1.0, v229
	v_add_f32_e32 v230, 1.0, v230
	v_div_scale_f32 v231, s[100:101], v227, v227, v172
	v_rcp_f32_e32 v232, v231
	s_nop 0
	v_fma_f32 v233, -v231, v232, 1.0
	v_fmac_f32_e32 v232, v233, v232
	v_div_scale_f32 v233, vcc, v172, v227, v172
	v_mul_f32_e32 v192, v233, v232
	v_fma_f32 v193, -v231, v192, v233
	v_fmac_f32_e32 v192, v193, v232
	v_fma_f32 v231, -v231, v192, v233
	v_div_fmas_f32 v231, v231, v232, v192
	v_div_fixup_f32 v227, v231, v227, v172
	v_mul_f32_e32 v164, v164, v227
	v_fmac_f32_e32 v156, v164, v164
	v_div_scale_f32 v231, s[100:101], v228, v228, v173
	v_rcp_f32_e32 v232, v231
	s_nop 0
	v_fma_f32 v233, -v231, v232, 1.0
	v_fmac_f32_e32 v232, v233, v232
	v_div_scale_f32 v233, vcc, v173, v228, v173
	v_mul_f32_e32 v192, v233, v232
	v_fma_f32 v193, -v231, v192, v233
	v_fmac_f32_e32 v192, v193, v232
	v_fma_f32 v231, -v231, v192, v233
	v_div_fmas_f32 v231, v231, v232, v192
	v_div_fixup_f32 v228, v231, v228, v173
	v_mul_f32_e32 v165, v165, v228
	v_fmac_f32_e32 v157, v165, v165
	v_div_scale_f32 v231, s[100:101], v229, v229, v174
	v_rcp_f32_e32 v232, v231
	s_nop 0
	v_fma_f32 v233, -v231, v232, 1.0
	v_fmac_f32_e32 v232, v233, v232
	v_div_scale_f32 v233, vcc, v174, v229, v174
	v_mul_f32_e32 v192, v233, v232
	v_fma_f32 v193, -v231, v192, v233
	v_fmac_f32_e32 v192, v193, v232
	v_fma_f32 v231, -v231, v192, v233
	v_div_fmas_f32 v231, v231, v232, v192
	v_div_fixup_f32 v229, v231, v229, v174
	v_mul_f32_e32 v166, v166, v229
	v_fmac_f32_e32 v158, v166, v166
	v_div_scale_f32 v231, s[100:101], v230, v230, v175
	v_rcp_f32_e32 v232, v231
	s_nop 0
	v_fma_f32 v233, -v231, v232, 1.0
	v_fmac_f32_e32 v232, v233, v232
	v_div_scale_f32 v233, vcc, v175, v230, v175
	v_mul_f32_e32 v192, v233, v232
	v_fma_f32 v193, -v231, v192, v233
	v_fmac_f32_e32 v192, v193, v232
	v_fma_f32 v231, -v231, v192, v233
	v_div_fmas_f32 v231, v231, v232, v192
	v_div_fixup_f32 v230, v231, v230, v175
	v_mul_f32_e32 v167, v167, v230
	v_fmac_f32_e32 v159, v167, v167
	ds_write_b128 v225, v[164:167] offset:2048
	v_fma_f32 v168, v144, v128, v120
	v_fma_f32 v169, v145, v129, v121
	v_fma_f32 v170, v146, v130, v122
	v_fma_f32 v171, v147, v131, v123
	v_fma_f32 v168, v152, v136, v168
	v_fma_f32 v169, v153, v137, v169
	v_fma_f32 v170, v154, v138, v170
	v_fma_f32 v171, v155, v139, v171
	v_mul_f32_e32 v227, 0xbfb8aa3b, v176
	v_mul_f32_e32 v228, 0xbfb8aa3b, v177
	v_mul_f32_e32 v229, 0xbfb8aa3b, v178
	v_mul_f32_e32 v230, 0xbfb8aa3b, v179
	v_exp_f32_e32 v227, v227
	v_exp_f32_e32 v228, v228
	v_exp_f32_e32 v229, v229
	v_exp_f32_e32 v230, v230
	s_nop 0
	v_add_f32_e32 v227, 1.0, v227
	v_add_f32_e32 v228, 1.0, v228
	v_add_f32_e32 v229, 1.0, v229
	v_add_f32_e32 v230, 1.0, v230
	v_div_scale_f32 v231, s[100:101], v227, v227, v176
	v_rcp_f32_e32 v232, v231
	s_nop 0
	v_fma_f32 v233, -v231, v232, 1.0
	v_fmac_f32_e32 v232, v233, v232
	v_div_scale_f32 v233, vcc, v176, v227, v176
	v_mul_f32_e32 v192, v233, v232
	v_fma_f32 v193, -v231, v192, v233
	v_fmac_f32_e32 v192, v193, v232
	v_fma_f32 v231, -v231, v192, v233
	v_div_fmas_f32 v231, v231, v232, v192
	v_div_fixup_f32 v227, v231, v227, v176
	v_mul_f32_e32 v168, v168, v227
	v_fmac_f32_e32 v160, v168, v168
	v_div_scale_f32 v231, s[100:101], v228, v228, v177
	v_rcp_f32_e32 v232, v231
	s_nop 0
	v_fma_f32 v233, -v231, v232, 1.0
	v_fmac_f32_e32 v232, v233, v232
	v_div_scale_f32 v233, vcc, v177, v228, v177
	v_mul_f32_e32 v192, v233, v232
	v_fma_f32 v193, -v231, v192, v233
	v_fmac_f32_e32 v192, v193, v232
	v_fma_f32 v231, -v231, v192, v233
	v_div_fmas_f32 v231, v231, v232, v192
	v_div_fixup_f32 v228, v231, v228, v177
	v_mul_f32_e32 v169, v169, v228
	v_fmac_f32_e32 v161, v169, v169
	v_div_scale_f32 v231, s[100:101], v229, v229, v178
	v_rcp_f32_e32 v232, v231
	s_nop 0
	v_fma_f32 v233, -v231, v232, 1.0
	v_fmac_f32_e32 v232, v233, v232
	v_div_scale_f32 v233, vcc, v178, v229, v178
	v_mul_f32_e32 v192, v233, v232
	v_fma_f32 v193, -v231, v192, v233
	v_fmac_f32_e32 v192, v193, v232
	v_fma_f32 v231, -v231, v192, v233
	v_div_fmas_f32 v231, v231, v232, v192
	v_div_fixup_f32 v229, v231, v229, v178
	v_mul_f32_e32 v170, v170, v229
	v_fmac_f32_e32 v162, v170, v170
	v_div_scale_f32 v231, s[100:101], v230, v230, v179
	v_rcp_f32_e32 v232, v231
	s_nop 0
	v_fma_f32 v233, -v231, v232, 1.0
	v_fmac_f32_e32 v232, v233, v232
	v_div_scale_f32 v233, vcc, v179, v230, v179
	v_mul_f32_e32 v192, v233, v232
	v_fma_f32 v193, -v231, v192, v233
	v_fmac_f32_e32 v192, v193, v232
	v_fma_f32 v231, -v231, v192, v233
	v_div_fmas_f32 v231, v231, v232, v192
	v_div_fixup_f32 v230, v231, v230, v179
	v_mul_f32_e32 v171, v171, v230
	v_fmac_f32_e32 v163, v171, v171
	ds_write_b128 v225, v[168:171] offset:3072
	s_waitcnt vmcnt(16)
	v_mfma_f32_16x16x32_bf16 v[116:119], v[36:39], v[68:71], 0
	v_mfma_f32_16x16x32_bf16 v[120:123], v[52:55], v[68:71], 0
	v_mfma_f32_16x16x32_bf16 v[116:119], v[40:43], v[72:75], v[116:119]
	v_mfma_f32_16x16x32_bf16 v[120:123], v[56:59], v[72:75], v[120:123]
	v_mfma_f32_16x16x32_bf16 v[116:119], v[44:47], v[76:79], v[116:119]
	v_mfma_f32_16x16x32_bf16 v[120:123], v[60:63], v[76:79], v[120:123]
	v_mfma_f32_16x16x32_bf16 v[116:119], v[48:51], v[80:83], v[116:119]
	v_mfma_f32_16x16x32_bf16 v[120:123], v[64:67], v[80:83], v[120:123]
	global_load_dwordx2 v[68:69], v204, s[50:51]
	global_load_dwordx2 v[70:71], v204, s[50:51] offset:32
	global_load_dwordx2 v[72:73], v204, s[50:51] offset:64
	global_load_dwordx2 v[74:75], v204, s[50:51] offset:96
	global_load_dwordx2 v[76:77], v204, s[50:51] offset:128
	global_load_dwordx2 v[78:79], v204, s[50:51] offset:160
	global_load_dwordx2 v[80:81], v204, s[50:51] offset:192
	global_load_dwordx2 v[82:83], v204, s[50:51] offset:224
	s_add_u32 s50, s50, 0x1000
	s_addc_u32 s51, s51, 0
	s_waitcnt vmcnt(16)
	v_mfma_f32_16x16x32_bf16 v[124:127], v[4:7], v[84:87], 0
	v_mfma_f32_16x16x32_bf16 v[132:135], v[4:7], v[100:103], 0
	v_mfma_f32_16x16x32_bf16 v[128:131], v[20:23], v[84:87], 0
	v_mfma_f32_16x16x32_bf16 v[136:139], v[20:23], v[100:103], 0
	v_mfma_f32_16x16x32_bf16 v[124:127], v[8:11], v[88:91], v[124:127]
	v_mfma_f32_16x16x32_bf16 v[132:135], v[8:11], v[104:107], v[132:135]
	v_mfma_f32_16x16x32_bf16 v[128:131], v[24:27], v[88:91], v[128:131]
	v_mfma_f32_16x16x32_bf16 v[136:139], v[24:27], v[104:107], v[136:139]
	v_mfma_f32_16x16x32_bf16 v[124:127], v[12:15], v[92:95], v[124:127]
	v_mfma_f32_16x16x32_bf16 v[132:135], v[12:15], v[108:111], v[132:135]
	v_mfma_f32_16x16x32_bf16 v[128:131], v[28:31], v[92:95], v[128:131]
	v_mfma_f32_16x16x32_bf16 v[136:139], v[28:31], v[108:111], v[136:139]
	v_mfma_f32_16x16x32_bf16 v[124:127], v[16:19], v[96:99], v[124:127]
	v_mfma_f32_16x16x32_bf16 v[132:135], v[16:19], v[112:115], v[132:135]
	v_mfma_f32_16x16x32_bf16 v[128:131], v[32:35], v[96:99], v[128:131]
	v_mfma_f32_16x16x32_bf16 v[136:139], v[32:35], v[112:115], v[136:139]
	global_load_dwordx4 v[84:87], v205, s[52:53]
	global_load_dwordx4 v[88:91], v205, s[52:53] offset:64
	global_load_dwordx4 v[92:95], v205, s[52:53] offset:128
	global_load_dwordx4 v[96:99], v205, s[52:53] offset:192
	global_load_dwordx4 v[100:103], v205, s[54:55]
	global_load_dwordx4 v[104:107], v205, s[54:55] offset:64
	global_load_dwordx4 v[108:111], v205, s[54:55] offset:128
	global_load_dwordx4 v[112:115], v205, s[54:55] offset:192
	s_add_u32 s52, s52, 0x1000
	s_addc_u32 s53, s53, 0
	s_add_u32 s54, s54, 0x1000
	s_addc_u32 s55, s55, 0
	global_load_dword v172, v197, s[56:57] offset:192
	v_add_u32_e32 v233, 0x2440, v197
	global_load_dword v173, v233, s[56:57] offset:192
	v_add_u32_e32 v233, 0x4880, v197
	global_load_dword v174, v233, s[56:57] offset:192
	v_add_u32_e32 v233, 0x6cc0, v197
	global_load_dword v175, v233, s[56:57] offset:192
	v_add_u32_e32 v233, 0x24400, v197
	global_load_dword v176, v233, s[56:57] offset:192
	v_add_u32_e32 v233, 0x26840, v197
	global_load_dword v177, v233, s[56:57] offset:192
	v_add_u32_e32 v233, 0x28c80, v197
	global_load_dword v178, v233, s[56:57] offset:192
	v_add_u32_e32 v233, 0x2b0c0, v197
	global_load_dword v179, v233, s[56:57] offset:192
	s_waitcnt vmcnt(24)
	s_nop 7
	v_fma_f32 v164, v140, v124, v116
	v_fma_f32 v165, v141, v125, v117
	v_fma_f32 v166, v142, v126, v118
	v_fma_f32 v167, v143, v127, v119
	v_fma_f32 v164, v148, v132, v164
	v_fma_f32 v165, v149, v133, v165
	v_fma_f32 v166, v150, v134, v166
	v_fma_f32 v167, v151, v135, v167
	v_mul_f32_e32 v227, 0xbfb8aa3b, v180
	v_mul_f32_e32 v228, 0xbfb8aa3b, v181
	v_mul_f32_e32 v229, 0xbfb8aa3b, v182
	v_mul_f32_e32 v230, 0xbfb8aa3b, v183
	v_exp_f32_e32 v227, v227
	v_exp_f32_e32 v228, v228
	v_exp_f32_e32 v229, v229
	v_exp_f32_e32 v230, v230
	s_nop 0
	v_add_f32_e32 v227, 1.0, v227
	v_add_f32_e32 v228, 1.0, v228
	v_add_f32_e32 v229, 1.0, v229
	v_add_f32_e32 v230, 1.0, v230
	v_div_scale_f32 v231, s[100:101], v227, v227, v180
	v_rcp_f32_e32 v232, v231
	s_nop 0
	v_fma_f32 v233, -v231, v232, 1.0
	v_fmac_f32_e32 v232, v233, v232
	v_div_scale_f32 v233, vcc, v180, v227, v180
	v_mul_f32_e32 v192, v233, v232
	v_fma_f32 v193, -v231, v192, v233
	v_fmac_f32_e32 v192, v193, v232
	v_fma_f32 v231, -v231, v192, v233
	v_div_fmas_f32 v231, v231, v232, v192
	v_div_fixup_f32 v227, v231, v227, v180
	v_mul_f32_e32 v164, v164, v227
	v_fmac_f32_e32 v156, v164, v164
	v_div_scale_f32 v231, s[100:101], v228, v228, v181
	v_rcp_f32_e32 v232, v231
	s_nop 0
	v_fma_f32 v233, -v231, v232, 1.0
	v_fmac_f32_e32 v232, v233, v232
	v_div_scale_f32 v233, vcc, v181, v228, v181
	v_mul_f32_e32 v192, v233, v232
	v_fma_f32 v193, -v231, v192, v233
	v_fmac_f32_e32 v192, v193, v232
	v_fma_f32 v231, -v231, v192, v233
	v_div_fmas_f32 v231, v231, v232, v192
	v_div_fixup_f32 v228, v231, v228, v181
	v_mul_f32_e32 v165, v165, v228
	v_fmac_f32_e32 v157, v165, v165
	v_div_scale_f32 v231, s[100:101], v229, v229, v182
	v_rcp_f32_e32 v232, v231
	s_nop 0
	v_fma_f32 v233, -v231, v232, 1.0
	v_fmac_f32_e32 v232, v233, v232
	v_div_scale_f32 v233, vcc, v182, v229, v182
	v_mul_f32_e32 v192, v233, v232
	v_fma_f32 v193, -v231, v192, v233
	v_fmac_f32_e32 v192, v193, v232
	v_fma_f32 v231, -v231, v192, v233
	v_div_fmas_f32 v231, v231, v232, v192
	v_div_fixup_f32 v229, v231, v229, v182
	v_mul_f32_e32 v166, v166, v229
	v_fmac_f32_e32 v158, v166, v166
	v_div_scale_f32 v231, s[100:101], v230, v230, v183
	v_rcp_f32_e32 v232, v231
	s_nop 0
	v_fma_f32 v233, -v231, v232, 1.0
	v_fmac_f32_e32 v232, v233, v232
	v_div_scale_f32 v233, vcc, v183, v230, v183
	v_mul_f32_e32 v192, v233, v232
	v_fma_f32 v193, -v231, v192, v233
	v_fmac_f32_e32 v192, v193, v232
	v_fma_f32 v231, -v231, v192, v233
	v_div_fmas_f32 v231, v231, v232, v192
	v_div_fixup_f32 v230, v231, v230, v183
	v_mul_f32_e32 v167, v167, v230
	v_fmac_f32_e32 v159, v167, v167
	ds_write_b128 v225, v[164:167] offset:4096
	v_fma_f32 v168, v144, v128, v120
	v_fma_f32 v169, v145, v129, v121
	v_fma_f32 v170, v146, v130, v122
	v_fma_f32 v171, v147, v131, v123
	v_fma_f32 v168, v152, v136, v168
	v_fma_f32 v169, v153, v137, v169
	v_fma_f32 v170, v154, v138, v170
	v_fma_f32 v171, v155, v139, v171
	v_mul_f32_e32 v227, 0xbfb8aa3b, v184
	v_mul_f32_e32 v228, 0xbfb8aa3b, v185
	v_mul_f32_e32 v229, 0xbfb8aa3b, v186
	v_mul_f32_e32 v230, 0xbfb8aa3b, v187
	v_exp_f32_e32 v227, v227
	v_exp_f32_e32 v228, v228
	v_exp_f32_e32 v229, v229
	v_exp_f32_e32 v230, v230
	s_nop 0
	v_add_f32_e32 v227, 1.0, v227
	v_add_f32_e32 v228, 1.0, v228
	v_add_f32_e32 v229, 1.0, v229
	v_add_f32_e32 v230, 1.0, v230
	v_div_scale_f32 v231, s[100:101], v227, v227, v184
	v_rcp_f32_e32 v232, v231
	s_nop 0
	v_fma_f32 v233, -v231, v232, 1.0
	v_fmac_f32_e32 v232, v233, v232
	v_div_scale_f32 v233, vcc, v184, v227, v184
	v_mul_f32_e32 v192, v233, v232
	v_fma_f32 v193, -v231, v192, v233
	v_fmac_f32_e32 v192, v193, v232
	v_fma_f32 v231, -v231, v192, v233
	v_div_fmas_f32 v231, v231, v232, v192
	v_div_fixup_f32 v227, v231, v227, v184
	v_mul_f32_e32 v168, v168, v227
	v_fmac_f32_e32 v160, v168, v168
	v_div_scale_f32 v231, s[100:101], v228, v228, v185
	v_rcp_f32_e32 v232, v231
	s_nop 0
	v_fma_f32 v233, -v231, v232, 1.0
	v_fmac_f32_e32 v232, v233, v232
	v_div_scale_f32 v233, vcc, v185, v228, v185
	v_mul_f32_e32 v192, v233, v232
	v_fma_f32 v193, -v231, v192, v233
	v_fmac_f32_e32 v192, v193, v232
	v_fma_f32 v231, -v231, v192, v233
	v_div_fmas_f32 v231, v231, v232, v192
	v_div_fixup_f32 v228, v231, v228, v185
	v_mul_f32_e32 v169, v169, v228
	v_fmac_f32_e32 v161, v169, v169
	v_div_scale_f32 v231, s[100:101], v229, v229, v186
	v_rcp_f32_e32 v232, v231
	s_nop 0
	v_fma_f32 v233, -v231, v232, 1.0
	v_fmac_f32_e32 v232, v233, v232
	v_div_scale_f32 v233, vcc, v186, v229, v186
	v_mul_f32_e32 v192, v233, v232
	v_fma_f32 v193, -v231, v192, v233
	v_fmac_f32_e32 v192, v193, v232
	v_fma_f32 v231, -v231, v192, v233
	v_div_fmas_f32 v231, v231, v232, v192
	v_div_fixup_f32 v229, v231, v229, v186
	v_mul_f32_e32 v170, v170, v229
	v_fmac_f32_e32 v162, v170, v170
	v_div_scale_f32 v231, s[100:101], v230, v230, v187
	v_rcp_f32_e32 v232, v231
	s_nop 0
	v_fma_f32 v233, -v231, v232, 1.0
	v_fmac_f32_e32 v232, v233, v232
	v_div_scale_f32 v233, vcc, v187, v230, v187
	v_mul_f32_e32 v192, v233, v232
	v_fma_f32 v193, -v231, v192, v233
	v_fmac_f32_e32 v192, v193, v232
	v_fma_f32 v231, -v231, v192, v233
	v_div_fmas_f32 v231, v231, v232, v192
	v_div_fixup_f32 v230, v231, v230, v187
	v_mul_f32_e32 v171, v171, v230
	v_fmac_f32_e32 v163, v171, v171
	ds_write_b128 v225, v[168:171] offset:5120
	s_waitcnt vmcnt(16)
	v_mfma_f32_16x16x32_bf16 v[116:119], v[36:39], v[68:71], 0
	v_mfma_f32_16x16x32_bf16 v[120:123], v[52:55], v[68:71], 0
	v_mfma_f32_16x16x32_bf16 v[116:119], v[40:43], v[72:75], v[116:119]
	v_mfma_f32_16x16x32_bf16 v[120:123], v[56:59], v[72:75], v[120:123]
	v_mfma_f32_16x16x32_bf16 v[116:119], v[44:47], v[76:79], v[116:119]
	v_mfma_f32_16x16x32_bf16 v[120:123], v[60:63], v[76:79], v[120:123]
	v_mfma_f32_16x16x32_bf16 v[116:119], v[48:51], v[80:83], v[116:119]
	v_mfma_f32_16x16x32_bf16 v[120:123], v[64:67], v[80:83], v[120:123]
	s_waitcnt vmcnt(8)
	v_mfma_f32_16x16x32_bf16 v[124:127], v[4:7], v[84:87], 0
	v_mfma_f32_16x16x32_bf16 v[132:135], v[4:7], v[100:103], 0
	v_mfma_f32_16x16x32_bf16 v[128:131], v[20:23], v[84:87], 0
	v_mfma_f32_16x16x32_bf16 v[136:139], v[20:23], v[100:103], 0
	v_mfma_f32_16x16x32_bf16 v[124:127], v[8:11], v[88:91], v[124:127]
	v_mfma_f32_16x16x32_bf16 v[132:135], v[8:11], v[104:107], v[132:135]
	v_mfma_f32_16x16x32_bf16 v[128:131], v[24:27], v[88:91], v[128:131]
	v_mfma_f32_16x16x32_bf16 v[136:139], v[24:27], v[104:107], v[136:139]
	v_mfma_f32_16x16x32_bf16 v[124:127], v[12:15], v[92:95], v[124:127]
	v_mfma_f32_16x16x32_bf16 v[132:135], v[12:15], v[108:111], v[132:135]
	v_mfma_f32_16x16x32_bf16 v[128:131], v[28:31], v[92:95], v[128:131]
	v_mfma_f32_16x16x32_bf16 v[136:139], v[28:31], v[108:111], v[136:139]
	v_mfma_f32_16x16x32_bf16 v[124:127], v[16:19], v[96:99], v[124:127]
	v_mfma_f32_16x16x32_bf16 v[132:135], v[16:19], v[112:115], v[132:135]
	v_mfma_f32_16x16x32_bf16 v[128:131], v[32:35], v[96:99], v[128:131]
	v_mfma_f32_16x16x32_bf16 v[136:139], v[32:35], v[112:115], v[136:139]
	s_waitcnt vmcnt(0)
	s_nop 7
	v_fma_f32 v164, v140, v124, v116
	v_fma_f32 v165, v141, v125, v117
	v_fma_f32 v166, v142, v126, v118
	v_fma_f32 v167, v143, v127, v119
	v_fma_f32 v164, v148, v132, v164
	v_fma_f32 v165, v149, v133, v165
	v_fma_f32 v166, v150, v134, v166
	v_fma_f32 v167, v151, v135, v167
	v_mul_f32_e32 v227, 0xbfb8aa3b, v172
	v_mul_f32_e32 v228, 0xbfb8aa3b, v173
	v_mul_f32_e32 v229, 0xbfb8aa3b, v174
	v_mul_f32_e32 v230, 0xbfb8aa3b, v175
	v_exp_f32_e32 v227, v227
	v_exp_f32_e32 v228, v228
	v_exp_f32_e32 v229, v229
	v_exp_f32_e32 v230, v230
	s_nop 0
	v_add_f32_e32 v227, 1.0, v227
	v_add_f32_e32 v228, 1.0, v228
	v_add_f32_e32 v229, 1.0, v229
	v_add_f32_e32 v230, 1.0, v230
	v_div_scale_f32 v231, s[100:101], v227, v227, v172
	v_rcp_f32_e32 v232, v231
	s_nop 0
	v_fma_f32 v233, -v231, v232, 1.0
	v_fmac_f32_e32 v232, v233, v232
	v_div_scale_f32 v233, vcc, v172, v227, v172
	v_mul_f32_e32 v192, v233, v232
	v_fma_f32 v193, -v231, v192, v233
	v_fmac_f32_e32 v192, v193, v232
	v_fma_f32 v231, -v231, v192, v233
	v_div_fmas_f32 v231, v231, v232, v192
	v_div_fixup_f32 v227, v231, v227, v172
	v_mul_f32_e32 v164, v164, v227
	v_fmac_f32_e32 v156, v164, v164
	v_div_scale_f32 v231, s[100:101], v228, v228, v173
	v_rcp_f32_e32 v232, v231
	s_nop 0
	v_fma_f32 v233, -v231, v232, 1.0
	v_fmac_f32_e32 v232, v233, v232
	v_div_scale_f32 v233, vcc, v173, v228, v173
	v_mul_f32_e32 v192, v233, v232
	v_fma_f32 v193, -v231, v192, v233
	v_fmac_f32_e32 v192, v193, v232
	v_fma_f32 v231, -v231, v192, v233
	v_div_fmas_f32 v231, v231, v232, v192
	v_div_fixup_f32 v228, v231, v228, v173
	v_mul_f32_e32 v165, v165, v228
	v_fmac_f32_e32 v157, v165, v165
	v_div_scale_f32 v231, s[100:101], v229, v229, v174
	v_rcp_f32_e32 v232, v231
	s_nop 0
	v_fma_f32 v233, -v231, v232, 1.0
	v_fmac_f32_e32 v232, v233, v232
	v_div_scale_f32 v233, vcc, v174, v229, v174
	v_mul_f32_e32 v192, v233, v232
	v_fma_f32 v193, -v231, v192, v233
	v_fmac_f32_e32 v192, v193, v232
	v_fma_f32 v231, -v231, v192, v233
	v_div_fmas_f32 v231, v231, v232, v192
	v_div_fixup_f32 v229, v231, v229, v174
	v_mul_f32_e32 v166, v166, v229
	v_fmac_f32_e32 v158, v166, v166
	v_div_scale_f32 v231, s[100:101], v230, v230, v175
	v_rcp_f32_e32 v232, v231
	s_nop 0
	v_fma_f32 v233, -v231, v232, 1.0
	v_fmac_f32_e32 v232, v233, v232
	v_div_scale_f32 v233, vcc, v175, v230, v175
	v_mul_f32_e32 v192, v233, v232
	v_fma_f32 v193, -v231, v192, v233
	v_fmac_f32_e32 v192, v193, v232
	v_fma_f32 v231, -v231, v192, v233
	v_div_fmas_f32 v231, v231, v232, v192
	v_div_fixup_f32 v230, v231, v230, v175
	v_mul_f32_e32 v167, v167, v230
	v_fmac_f32_e32 v159, v167, v167
	ds_write_b128 v225, v[164:167] offset:6144
	v_fma_f32 v168, v144, v128, v120
	v_fma_f32 v169, v145, v129, v121
	v_fma_f32 v170, v146, v130, v122
	v_fma_f32 v171, v147, v131, v123
	v_fma_f32 v168, v152, v136, v168
	v_fma_f32 v169, v153, v137, v169
	v_fma_f32 v170, v154, v138, v170
	v_fma_f32 v171, v155, v139, v171
	v_mul_f32_e32 v227, 0xbfb8aa3b, v176
	v_mul_f32_e32 v228, 0xbfb8aa3b, v177
	v_mul_f32_e32 v229, 0xbfb8aa3b, v178
	v_mul_f32_e32 v230, 0xbfb8aa3b, v179
	v_exp_f32_e32 v227, v227
	v_exp_f32_e32 v228, v228
	v_exp_f32_e32 v229, v229
	v_exp_f32_e32 v230, v230
	s_nop 0
	v_add_f32_e32 v227, 1.0, v227
	v_add_f32_e32 v228, 1.0, v228
	v_add_f32_e32 v229, 1.0, v229
	v_add_f32_e32 v230, 1.0, v230
	v_div_scale_f32 v231, s[100:101], v227, v227, v176
	v_rcp_f32_e32 v232, v231
	s_nop 0
	v_fma_f32 v233, -v231, v232, 1.0
	v_fmac_f32_e32 v232, v233, v232
	v_div_scale_f32 v233, vcc, v176, v227, v176
	v_mul_f32_e32 v192, v233, v232
	v_fma_f32 v193, -v231, v192, v233
	v_fmac_f32_e32 v192, v193, v232
	v_fma_f32 v231, -v231, v192, v233
	v_div_fmas_f32 v231, v231, v232, v192
	v_div_fixup_f32 v227, v231, v227, v176
	v_mul_f32_e32 v168, v168, v227
	v_fmac_f32_e32 v160, v168, v168
	v_div_scale_f32 v231, s[100:101], v228, v228, v177
	v_rcp_f32_e32 v232, v231
	s_nop 0
	v_fma_f32 v233, -v231, v232, 1.0
	v_fmac_f32_e32 v232, v233, v232
	v_div_scale_f32 v233, vcc, v177, v228, v177
	v_mul_f32_e32 v192, v233, v232
	v_fma_f32 v193, -v231, v192, v233
	v_fmac_f32_e32 v192, v193, v232
	v_fma_f32 v231, -v231, v192, v233
	v_div_fmas_f32 v231, v231, v232, v192
	v_div_fixup_f32 v228, v231, v228, v177
	v_mul_f32_e32 v169, v169, v228
	v_fmac_f32_e32 v161, v169, v169
	v_div_scale_f32 v231, s[100:101], v229, v229, v178
	v_rcp_f32_e32 v232, v231
	s_nop 0
	v_fma_f32 v233, -v231, v232, 1.0
	v_fmac_f32_e32 v232, v233, v232
	v_div_scale_f32 v233, vcc, v178, v229, v178
	v_mul_f32_e32 v192, v233, v232
	v_fma_f32 v193, -v231, v192, v233
	v_fmac_f32_e32 v192, v193, v232
	v_fma_f32 v231, -v231, v192, v233
	v_div_fmas_f32 v231, v231, v232, v192
	v_div_fixup_f32 v229, v231, v229, v178
	v_mul_f32_e32 v170, v170, v229
	v_fmac_f32_e32 v162, v170, v170
	v_div_scale_f32 v231, s[100:101], v230, v230, v179
	v_rcp_f32_e32 v232, v231
	s_nop 0
	v_fma_f32 v233, -v231, v232, 1.0
	v_fmac_f32_e32 v232, v233, v232
	v_div_scale_f32 v233, vcc, v179, v230, v179
	v_mul_f32_e32 v192, v233, v232
	v_fma_f32 v193, -v231, v192, v233
	v_fmac_f32_e32 v192, v193, v232
	v_fma_f32 v231, -v231, v192, v233
	v_div_fmas_f32 v231, v231, v232, v192
	v_div_fixup_f32 v230, v231, v230, v179
	v_mul_f32_e32 v171, v171, v230
	v_fmac_f32_e32 v163, v171, v171
	ds_write_b128 v225, v[168:171] offset:7168
	v_add_f32_dpp v156, v156, v156 row_ror:1 row_mask:0xf bank_mask:0xf
	v_add_f32_dpp v157, v157, v157 row_ror:1 row_mask:0xf bank_mask:0xf
	v_add_f32_dpp v158, v158, v158 row_ror:1 row_mask:0xf bank_mask:0xf
	v_add_f32_dpp v159, v159, v159 row_ror:1 row_mask:0xf bank_mask:0xf
	v_add_f32_dpp v160, v160, v160 row_ror:1 row_mask:0xf bank_mask:0xf
	v_add_f32_dpp v161, v161, v161 row_ror:1 row_mask:0xf bank_mask:0xf
	v_add_f32_dpp v162, v162, v162 row_ror:1 row_mask:0xf bank_mask:0xf
	v_add_f32_dpp v163, v163, v163 row_ror:1 row_mask:0xf bank_mask:0xf
	s_nop 1
	v_add_f32_dpp v156, v156, v156 row_ror:2 row_mask:0xf bank_mask:0xf
	v_add_f32_dpp v157, v157, v157 row_ror:2 row_mask:0xf bank_mask:0xf
	v_add_f32_dpp v158, v158, v158 row_ror:2 row_mask:0xf bank_mask:0xf
	v_add_f32_dpp v159, v159, v159 row_ror:2 row_mask:0xf bank_mask:0xf
	v_add_f32_dpp v160, v160, v160 row_ror:2 row_mask:0xf bank_mask:0xf
	v_add_f32_dpp v161, v161, v161 row_ror:2 row_mask:0xf bank_mask:0xf
	v_add_f32_dpp v162, v162, v162 row_ror:2 row_mask:0xf bank_mask:0xf
	v_add_f32_dpp v163, v163, v163 row_ror:2 row_mask:0xf bank_mask:0xf
	s_nop 1
	v_add_f32_dpp v156, v156, v156 row_ror:4 row_mask:0xf bank_mask:0xf
	v_add_f32_dpp v157, v157, v157 row_ror:4 row_mask:0xf bank_mask:0xf
	v_add_f32_dpp v158, v158, v158 row_ror:4 row_mask:0xf bank_mask:0xf
	v_add_f32_dpp v159, v159, v159 row_ror:4 row_mask:0xf bank_mask:0xf
	v_add_f32_dpp v160, v160, v160 row_ror:4 row_mask:0xf bank_mask:0xf
	v_add_f32_dpp v161, v161, v161 row_ror:4 row_mask:0xf bank_mask:0xf
	v_add_f32_dpp v162, v162, v162 row_ror:4 row_mask:0xf bank_mask:0xf
	v_add_f32_dpp v163, v163, v163 row_ror:4 row_mask:0xf bank_mask:0xf
	s_nop 1
	v_add_f32_dpp v156, v156, v156 row_ror:8 row_mask:0xf bank_mask:0xf
	v_add_f32_dpp v157, v157, v157 row_ror:8 row_mask:0xf bank_mask:0xf
	v_add_f32_dpp v158, v158, v158 row_ror:8 row_mask:0xf bank_mask:0xf
	v_add_f32_dpp v159, v159, v159 row_ror:8 row_mask:0xf bank_mask:0xf
	v_add_f32_dpp v160, v160, v160 row_ror:8 row_mask:0xf bank_mask:0xf
	v_add_f32_dpp v161, v161, v161 row_ror:8 row_mask:0xf bank_mask:0xf
	v_add_f32_dpp v162, v162, v162 row_ror:8 row_mask:0xf bank_mask:0xf
	v_add_f32_dpp v163, v163, v163 row_ror:8 row_mask:0xf bank_mask:0xf
	s_nop 1
	v_cmp_eq_u32_e32 vcc, 0, v0
	s_and_saveexec_b64 s[100:101], vcc
	ds_write_b32 v226, v156 offset:0
	ds_write_b32 v226, v157 offset:32
	ds_write_b32 v226, v158 offset:64
	ds_write_b32 v226, v159 offset:96
	ds_write_b32 v226, v160 offset:512
	ds_write_b32 v226, v161 offset:544
	ds_write_b32 v226, v162 offset:576
	ds_write_b32 v226, v163 offset:608
	s_mov_b64 exec, s[100:101]
	s_waitcnt lgkmcnt(0)
	s_barrier
	s_lshl_b32 s100, s40, 2
	v_subrev_u32_e32 v232, s100, v226
	ds_read_b128 v[116:119], v232 offset:0
	ds_read_b128 v[120:123], v232 offset:16
	ds_read_b128 v[124:127], v232 offset:32
	ds_read_b128 v[128:131], v232 offset:48
	ds_read_b128 v[132:135], v232 offset:64
	ds_read_b128 v[136:139], v232 offset:80
	ds_read_b128 v[140:143], v232 offset:96
	ds_read_b128 v[144:147], v232 offset:112
	s_waitcnt lgkmcnt(0)
	v_add_f32_e32 v116, v116, v117
	v_add_f32_e32 v116, v116, v118
	v_add_f32_e32 v116, v116, v119
	v_add_f32_e32 v116, v116, v120
	v_add_f32_e32 v116, v116, v121
	v_add_f32_e32 v116, v116, v122
	v_add_f32_e32 v116, v116, v123
	v_add_f32_e32 v124, v124, v125
	v_add_f32_e32 v124, v124, v126
	v_add_f32_e32 v124, v124, v127
	v_add_f32_e32 v124, v124, v128
	v_add_f32_e32 v124, v124, v129
	v_add_f32_e32 v124, v124, v130
	v_add_f32_e32 v124, v124, v131
	v_add_f32_e32 v132, v132, v133
	v_add_f32_e32 v132, v132, v134
	v_add_f32_e32 v132, v132, v135
	v_add_f32_e32 v132, v132, v136
	v_add_f32_e32 v132, v132, v137
	v_add_f32_e32 v132, v132, v138
	v_add_f32_e32 v132, v132, v139
	v_add_f32_e32 v140, v140, v141
	v_add_f32_e32 v140, v140, v142
	v_add_f32_e32 v140, v140, v143
	v_add_f32_e32 v140, v140, v144
	v_add_f32_e32 v140, v140, v145
	v_add_f32_e32 v140, v140, v146
	v_add_f32_e32 v140, v140, v147
	v_mov_b32_e32 v233, 0x358637bd
	v_mov_b32_e32 v231, 0x3b000000
	v_fma_f32 v156, v116, v231, v233
	v_fma_f32 v157, v124, v231, v233
	v_fma_f32 v158, v132, v231, v233
	v_fma_f32 v159, v140, v231, v233
	v_rsq_f32_e32 v156, v156
	v_rsq_f32_e32 v157, v157
	v_rsq_f32_e32 v158, v158
	v_rsq_f32_e32 v159, v159
	ds_read_b128 v[116:119], v232 offset:512
	ds_read_b128 v[120:123], v232 offset:528
	ds_read_b128 v[124:127], v232 offset:544
	ds_read_b128 v[128:131], v232 offset:560
	ds_read_b128 v[132:135], v232 offset:576
	ds_read_b128 v[136:139], v232 offset:592
	ds_read_b128 v[140:143], v232 offset:608
	ds_read_b128 v[144:147], v232 offset:624
	s_waitcnt lgkmcnt(0)
	v_add_f32_e32 v116, v116, v117
	v_add_f32_e32 v116, v116, v118
	v_add_f32_e32 v116, v116, v119
	v_add_f32_e32 v116, v116, v120
	v_add_f32_e32 v116, v116, v121
	v_add_f32_e32 v116, v116, v122
	v_add_f32_e32 v116, v116, v123
	v_add_f32_e32 v124, v124, v125
	v_add_f32_e32 v124, v124, v126
	v_add_f32_e32 v124, v124, v127
	v_add_f32_e32 v124, v124, v128
	v_add_f32_e32 v124, v124, v129
	v_add_f32_e32 v124, v124, v130
	v_add_f32_e32 v124, v124, v131
	v_add_f32_e32 v132, v132, v133
	v_add_f32_e32 v132, v132, v134
	v_add_f32_e32 v132, v132, v135
	v_add_f32_e32 v132, v132, v136
	v_add_f32_e32 v132, v132, v137
	v_add_f32_e32 v132, v132, v138
	v_add_f32_e32 v132, v132, v139
	v_add_f32_e32 v140, v140, v141
	v_add_f32_e32 v140, v140, v142
	v_add_f32_e32 v140, v140, v143
	v_add_f32_e32 v140, v140, v144
	v_add_f32_e32 v140, v140, v145
	v_add_f32_e32 v140, v140, v146
	v_add_f32_e32 v140, v140, v147
	v_mov_b32_e32 v233, 0x358637bd
	v_mov_b32_e32 v231, 0x3b000000
	v_fma_f32 v160, v116, v231, v233
	v_fma_f32 v161, v124, v231, v233
	v_fma_f32 v162, v132, v231, v233
	v_fma_f32 v163, v140, v231, v233
	v_rsq_f32_e32 v160, v160
	v_rsq_f32_e32 v161, v161
	v_rsq_f32_e32 v162, v162
	v_rsq_f32_e32 v163, v163
	v_mov_b32_e32 v132, v221
	v_add_u32_e32 v133, 0x800, v221
	v_add_u32_e32 v134, 0x1000, v221
	v_add_u32_e32 v135, 0x1800, v221
	v_add_u32_e32 v136, 0x8000, v221
	v_add_u32_e32 v137, 0x8800, v221
	v_add_u32_e32 v138, 0x9000, v221
	v_add_u32_e32 v139, 0x9800, v221
	ds_read_b128 v[116:119], v225 offset:0
	ds_read_b128 v[120:123], v225 offset:1024
	s_waitcnt lgkmcnt(1)
	v_mul_f32_e32 v116, v116, v156
	v_mul_f32_e32 v116, v188, v116
	v_bfe_u32 v227, v116, 16, 1
	v_add3_u32 v116, v116, v227, s27
	global_store_short_d16_hi v132, v116, s[58:59]
	v_mul_f32_e32 v117, v117, v157
	v_mul_f32_e32 v117, v188, v117
	v_bfe_u32 v228, v117, 16, 1
	v_add3_u32 v117, v117, v228, s27
	global_store_short_d16_hi v133, v117, s[58:59]
	v_mul_f32_e32 v118, v118, v158
	v_mul_f32_e32 v118, v188, v118
	v_bfe_u32 v229, v118, 16, 1
	v_add3_u32 v118, v118, v229, s27
	global_store_short_d16_hi v134, v118, s[58:59]
	v_mul_f32_e32 v119, v119, v159
	v_mul_f32_e32 v119, v188, v119
	v_bfe_u32 v230, v119, 16, 1
	v_add3_u32 v119, v119, v230, s27
	global_store_short_d16_hi v135, v119, s[58:59]
	s_waitcnt lgkmcnt(0)
	v_mul_f32_e32 v120, v120, v160
	v_mul_f32_e32 v120, v188, v120
	v_bfe_u32 v227, v120, 16, 1
	v_add3_u32 v120, v120, v227, s27
	global_store_short_d16_hi v136, v120, s[58:59]
	v_mul_f32_e32 v121, v121, v161
	v_mul_f32_e32 v121, v188, v121
	v_bfe_u32 v228, v121, 16, 1
	v_add3_u32 v121, v121, v228, s27
	global_store_short_d16_hi v137, v121, s[58:59]
	v_mul_f32_e32 v122, v122, v162
	v_mul_f32_e32 v122, v188, v122
	v_bfe_u32 v229, v122, 16, 1
	v_add3_u32 v122, v122, v229, s27
	global_store_short_d16_hi v138, v122, s[58:59]
	v_mul_f32_e32 v123, v123, v163
	v_mul_f32_e32 v123, v188, v123
	v_bfe_u32 v230, v123, 16, 1
	v_add3_u32 v123, v123, v230, s27
	global_store_short_d16_hi v139, v123, s[58:59]
	s_nop 0
	ds_read_b128 v[116:119], v225 offset:2048
	ds_read_b128 v[120:123], v225 offset:3072
	s_waitcnt lgkmcnt(1)
	v_mul_f32_e32 v116, v116, v156
	v_mul_f32_e32 v116, v189, v116
	v_bfe_u32 v227, v116, 16, 1
	v_add3_u32 v116, v116, v227, s27
	global_store_short_d16_hi v132, v116, s[58:59] offset:32
	v_mul_f32_e32 v117, v117, v157
	v_mul_f32_e32 v117, v189, v117
	v_bfe_u32 v228, v117, 16, 1
	v_add3_u32 v117, v117, v228, s27
	global_store_short_d16_hi v133, v117, s[58:59] offset:32
	v_mul_f32_e32 v118, v118, v158
	v_mul_f32_e32 v118, v189, v118
	v_bfe_u32 v229, v118, 16, 1
	v_add3_u32 v118, v118, v229, s27
	global_store_short_d16_hi v134, v118, s[58:59] offset:32
	v_mul_f32_e32 v119, v119, v159
	v_mul_f32_e32 v119, v189, v119
	v_bfe_u32 v230, v119, 16, 1
	v_add3_u32 v119, v119, v230, s27
	global_store_short_d16_hi v135, v119, s[58:59] offset:32
	s_waitcnt lgkmcnt(0)
	v_mul_f32_e32 v120, v120, v160
	v_mul_f32_e32 v120, v189, v120
	v_bfe_u32 v227, v120, 16, 1
	v_add3_u32 v120, v120, v227, s27
	global_store_short_d16_hi v136, v120, s[58:59] offset:32
	v_mul_f32_e32 v121, v121, v161
	v_mul_f32_e32 v121, v189, v121
	v_bfe_u32 v228, v121, 16, 1
	v_add3_u32 v121, v121, v228, s27
	global_store_short_d16_hi v137, v121, s[58:59] offset:32
	v_mul_f32_e32 v122, v122, v162
	v_mul_f32_e32 v122, v189, v122
	v_bfe_u32 v229, v122, 16, 1
	v_add3_u32 v122, v122, v229, s27
	global_store_short_d16_hi v138, v122, s[58:59] offset:32
	v_mul_f32_e32 v123, v123, v163
	v_mul_f32_e32 v123, v189, v123
	v_bfe_u32 v230, v123, 16, 1
	v_add3_u32 v123, v123, v230, s27
	global_store_short_d16_hi v139, v123, s[58:59] offset:32
	s_nop 0
	ds_read_b128 v[116:119], v225 offset:4096
	ds_read_b128 v[120:123], v225 offset:5120
	s_waitcnt lgkmcnt(1)
	v_mul_f32_e32 v116, v116, v156
	v_mul_f32_e32 v116, v190, v116
	v_bfe_u32 v227, v116, 16, 1
	v_add3_u32 v116, v116, v227, s27
	global_store_short_d16_hi v132, v116, s[58:59] offset:64
	v_mul_f32_e32 v117, v117, v157
	v_mul_f32_e32 v117, v190, v117
	v_bfe_u32 v228, v117, 16, 1
	v_add3_u32 v117, v117, v228, s27
	global_store_short_d16_hi v133, v117, s[58:59] offset:64
	v_mul_f32_e32 v118, v118, v158
	v_mul_f32_e32 v118, v190, v118
	v_bfe_u32 v229, v118, 16, 1
	v_add3_u32 v118, v118, v229, s27
	global_store_short_d16_hi v134, v118, s[58:59] offset:64
	v_mul_f32_e32 v119, v119, v159
	v_mul_f32_e32 v119, v190, v119
	v_bfe_u32 v230, v119, 16, 1
	v_add3_u32 v119, v119, v230, s27
	global_store_short_d16_hi v135, v119, s[58:59] offset:64
	s_waitcnt lgkmcnt(0)
	v_mul_f32_e32 v120, v120, v160
	v_mul_f32_e32 v120, v190, v120
	v_bfe_u32 v227, v120, 16, 1
	v_add3_u32 v120, v120, v227, s27
	global_store_short_d16_hi v136, v120, s[58:59] offset:64
	v_mul_f32_e32 v121, v121, v161
	v_mul_f32_e32 v121, v190, v121
	v_bfe_u32 v228, v121, 16, 1
	v_add3_u32 v121, v121, v228, s27
	global_store_short_d16_hi v137, v121, s[58:59] offset:64
	v_mul_f32_e32 v122, v122, v162
	v_mul_f32_e32 v122, v190, v122
	v_bfe_u32 v229, v122, 16, 1
	v_add3_u32 v122, v122, v229, s27
	global_store_short_d16_hi v138, v122, s[58:59] offset:64
	v_mul_f32_e32 v123, v123, v163
	v_mul_f32_e32 v123, v190, v123
	v_bfe_u32 v230, v123, 16, 1
	v_add3_u32 v123, v123, v230, s27
	global_store_short_d16_hi v139, v123, s[58:59] offset:64
	s_nop 0
	ds_read_b128 v[116:119], v225 offset:6144
	ds_read_b128 v[120:123], v225 offset:7168
	s_waitcnt lgkmcnt(1)
	v_mul_f32_e32 v116, v116, v156
	v_mul_f32_e32 v116, v191, v116
	v_bfe_u32 v227, v116, 16, 1
	v_add3_u32 v116, v116, v227, s27
	global_store_short_d16_hi v132, v116, s[58:59] offset:96
	v_mul_f32_e32 v117, v117, v157
	v_mul_f32_e32 v117, v191, v117
	v_bfe_u32 v228, v117, 16, 1
	v_add3_u32 v117, v117, v228, s27
	global_store_short_d16_hi v133, v117, s[58:59] offset:96
	v_mul_f32_e32 v118, v118, v158
	v_mul_f32_e32 v118, v191, v118
	v_bfe_u32 v229, v118, 16, 1
	v_add3_u32 v118, v118, v229, s27
	global_store_short_d16_hi v134, v118, s[58:59] offset:96
	v_mul_f32_e32 v119, v119, v159
	v_mul_f32_e32 v119, v191, v119
	v_bfe_u32 v230, v119, 16, 1
	v_add3_u32 v119, v119, v230, s27
	global_store_short_d16_hi v135, v119, s[58:59] offset:96
	s_waitcnt lgkmcnt(0)
	v_mul_f32_e32 v120, v120, v160
	v_mul_f32_e32 v120, v191, v120
	v_bfe_u32 v227, v120, 16, 1
	v_add3_u32 v120, v120, v227, s27
	global_store_short_d16_hi v136, v120, s[58:59] offset:96
	v_mul_f32_e32 v121, v121, v161
	v_mul_f32_e32 v121, v191, v121
	v_bfe_u32 v228, v121, 16, 1
	v_add3_u32 v121, v121, v228, s27
	global_store_short_d16_hi v137, v121, s[58:59] offset:96
	v_mul_f32_e32 v122, v122, v162
	v_mul_f32_e32 v122, v191, v122
	v_bfe_u32 v229, v122, 16, 1
	v_add3_u32 v122, v122, v229, s27
	global_store_short_d16_hi v138, v122, s[58:59] offset:96
	v_mul_f32_e32 v123, v123, v163
	v_mul_f32_e32 v123, v191, v123
	v_bfe_u32 v230, v123, 16, 1
	v_add3_u32 v123, v123, v230, s27
	global_store_short_d16_hi v139, v123, s[58:59] offset:96
	s_nop 0
	s_waitcnt vmcnt(0) lgkmcnt(0)
	s_branch .LBB0_854
.Lgm_glu_entry:
	s_add_u32 s56, s96, 0x7084600
	s_addc_u32 s57, s97, 0
	s_add_u32 s98, s96, 0xcea4000
	s_addc_u32 s99, s97, 0
	v_readlane_b32 s100, v237, 53
	v_readlane_b32 s101, v237, 54
	s_lshl_b32 s4, s36, 10
	s_add_u32 s100, s100, s4
	s_addc_u32 s101, s101, 0
	s_movk_i32 s52, 0x40
	s_sub_u32 s53, s63, 0xc0
	s_movk_i32 s54, 0x40
	s_cmp_ge_u32 s53, s54
	s_cbranch_scc1 .Lgm_glu_exit
	s_mov_b32 s30, 0
	s_mov_b32 s4, s53
.Lgm_glu_cnt:
	s_add_u32 s30, s30, 4
	s_add_u32 s4, s4, s52
	s_cmp_lt_u32 s4, s54
	s_cbranch_scc1 .Lgm_glu_cnt
	s_add_u32 s48, s96, 0xcea4000
	s_addc_u32 s49, s97, 0
	s_mul_i32 s4, s36, 0x20000
	s_add_u32 s50, s96, 0x2d80000
	s_addc_u32 s51, s97, 0
	s_add_u32 s50, s50, s4
	s_addc_u32 s51, s51, 0
	v_and_b32_e32 v0, 63, v206
	v_lshrrev_b32_e32 v1, 6, v206
	s_mov_b32 s31, 0
	v_readfirstlane_b32 s42, v1
	s_nop 0
	s_cmp_ge_u32 s42, 4
	s_cbranch_scc1 .Lgm_glu_compute
	v_lshrrev_b32_e32 v3, 3, v0
	v_and_b32_e32 v4, 7, v0
	v_xor_b32_e32 v4, v4, v3
	v_lshl_add_u32 v3, v1, 3, v3
	v_lshlrev_b32_e32 v3, 9, v3
	v_lshl_add_u32 v180, v4, 4, v3
	v_add_u32_e32 v181, 0x4000, v180
	v_add_u32_e32 v182, 0x8000, v180
	v_add_u32_e32 v183, 0xc000, v180
	v_add_u32_e32 v184, 0x10000, v180
	v_add_u32_e32 v185, 0x14000, v180
	s_lshl_b32 s42, s42, 10
	s_mov_b32 s38, s53
	s_mov_b32 s39, 0
	s_mov_b32 s41, s42
	s_and_b32 s4, s38, 31
	s_mul_i32 s4, s4, 0x18000
	s_add_u32 s44, s48, s4
	s_addc_u32 s45, s49, 0
	s_lshr_b32 s4, s38, 5
	s_mul_i32 s4, s4, 0x10000
	s_add_u32 s46, s50, s4
	s_addc_u32 s47, s51, 0
	s_add_u32 m0, s41, 0x0
	s_nop 0
	global_load_lds_dwordx4 v180, s[44:45]
	s_add_u32 m0, s41, 0x1000
	s_nop 0
	global_load_lds_dwordx4 v181, s[44:45]
	s_add_u32 m0, s41, 0x2000
	s_nop 0
	global_load_lds_dwordx4 v182, s[44:45]
	s_add_u32 m0, s41, 0x3000
	s_nop 0
	global_load_lds_dwordx4 v183, s[44:45]
	s_add_u32 m0, s41, 0x4000
	s_nop 0
	global_load_lds_dwordx4 v184, s[44:45]
	s_add_u32 m0, s41, 0x5000
	s_nop 0
	global_load_lds_dwordx4 v185, s[44:45]
	s_add_u32 m0, s41, 0x6000
	s_nop 0
	global_load_lds_dwordx4 v180, s[46:47]
	s_add_u32 m0, s41, 0x7000
	s_nop 0
	global_load_lds_dwordx4 v181, s[46:47]
	s_add_u32 m0, s41, 0x8000
	s_nop 0
	global_load_lds_dwordx4 v182, s[46:47]
	s_add_u32 m0, s41, 0x9000
	s_nop 0
	global_load_lds_dwordx4 v183, s[46:47]
	s_add_u32 s39, s39, 1
	s_add_u32 s44, s44, 0x80
	s_addc_u32 s45, s45, 0
	s_add_u32 s46, s46, 0x80
	s_addc_u32 s47, s47, 0
	s_cmp_lt_u32 s39, 4
	s_cbranch_scc1 .Lgm_glu_dadv1
	s_mov_b32 s39, 0
	s_add_u32 s4, s38, s52
	s_cmp_lt_u32 s4, s54
	s_cselect_b32 s38, s4, s38
	s_and_b32 s4, s38, 31
	s_mul_i32 s4, s4, 0x18000
	s_add_u32 s44, s48, s4
	s_addc_u32 s45, s49, 0
	s_lshr_b32 s4, s38, 5
	s_mul_i32 s4, s4, 0x10000
	s_add_u32 s46, s50, s4
	s_addc_u32 s47, s51, 0
.Lgm_glu_dadv1:
	s_add_u32 s41, s41, 0xa000
	s_sub_u32 s4, s41, 0x1e000
	s_cmp_ge_u32 s41, 0x1e000
	s_cselect_b32 s41, s4, s41
	s_add_u32 m0, s41, 0x0
	s_nop 0
	global_load_lds_dwordx4 v180, s[44:45]
	s_add_u32 m0, s41, 0x1000
	s_nop 0
	global_load_lds_dwordx4 v181, s[44:45]
	s_add_u32 m0, s41, 0x2000
	s_nop 0
	global_load_lds_dwordx4 v182, s[44:45]
	s_add_u32 m0, s41, 0x3000
	s_nop 0
	global_load_lds_dwordx4 v183, s[44:45]
	s_add_u32 m0, s41, 0x4000
	s_nop 0
	global_load_lds_dwordx4 v184, s[44:45]
	s_add_u32 m0, s41, 0x5000
	s_nop 0
	global_load_lds_dwordx4 v185, s[44:45]
	s_add_u32 m0, s41, 0x6000
	s_nop 0
	global_load_lds_dwordx4 v180, s[46:47]
	s_add_u32 m0, s41, 0x7000
	s_nop 0
	global_load_lds_dwordx4 v181, s[46:47]
	s_add_u32 m0, s41, 0x8000
	s_nop 0
	global_load_lds_dwordx4 v182, s[46:47]
	s_add_u32 m0, s41, 0x9000
	s_nop 0
	global_load_lds_dwordx4 v183, s[46:47]
	s_add_u32 s39, s39, 1
	s_add_u32 s44, s44, 0x80
	s_addc_u32 s45, s45, 0
	s_add_u32 s46, s46, 0x80
	s_addc_u32 s47, s47, 0
	s_cmp_lt_u32 s39, 4
	s_cbranch_scc1 .Lgm_glu_dadv2
	s_mov_b32 s39, 0
	s_add_u32 s4, s38, s52
	s_cmp_lt_u32 s4, s54
	s_cselect_b32 s38, s4, s38
	s_and_b32 s4, s38, 31
	s_mul_i32 s4, s4, 0x18000
	s_add_u32 s44, s48, s4
	s_addc_u32 s45, s49, 0
	s_lshr_b32 s4, s38, 5
	s_mul_i32 s4, s4, 0x10000
	s_add_u32 s46, s50, s4
	s_addc_u32 s47, s51, 0

.Lgm_glu_ld_loop:
	s_barrier
	s_add_u32 m0, s41, 0x0
	s_nop 0
	global_load_lds_dwordx4 v180, s[44:45]
	s_add_u32 m0, s41, 0x1000
	s_nop 0
	global_load_lds_dwordx4 v181, s[44:45]
	s_add_u32 m0, s41, 0x2000
	s_nop 0
	global_load_lds_dwordx4 v182, s[44:45]
	s_add_u32 m0, s41, 0x3000
	s_nop 0
	global_load_lds_dwordx4 v183, s[44:45]
	s_add_u32 m0, s41, 0x4000
	s_nop 0
	global_load_lds_dwordx4 v184, s[44:45]
	s_add_u32 m0, s41, 0x5000
	s_nop 0
	global_load_lds_dwordx4 v185, s[44:45]
	s_add_u32 m0, s41, 0x6000
	s_nop 0
	global_load_lds_dwordx4 v180, s[46:47]
	s_add_u32 m0, s41, 0x7000
	s_nop 0
	global_load_lds_dwordx4 v181, s[46:47]
	s_add_u32 m0, s41, 0x8000
	s_nop 0
	global_load_lds_dwordx4 v182, s[46:47]
	s_add_u32 m0, s41, 0x9000
	s_nop 0
	global_load_lds_dwordx4 v183, s[46:47]
	s_add_u32 s39, s39, 1
	s_add_u32 s44, s44, 0x80
	s_addc_u32 s45, s45, 0
	s_add_u32 s46, s46, 0x80
	s_addc_u32 s47, s47, 0
	s_cmp_lt_u32 s39, 4
	s_cbranch_scc1 .Lgm_glu_dadv3
	s_mov_b32 s39, 0
	s_add_u32 s4, s38, s52
	s_cmp_lt_u32 s4, s54
	s_cselect_b32 s38, s4, s38
	s_and_b32 s4, s38, 31
	s_mul_i32 s4, s4, 0x18000
	s_add_u32 s44, s48, s4
	s_addc_u32 s45, s49, 0
	s_lshr_b32 s4, s38, 5
	s_mul_i32 s4, s4, 0x10000
	s_add_u32 s46, s50, s4
	s_addc_u32 s47, s51, 0

.Lgm_glu_compute:
	v_and_b32_e32 v1, 3, v1
	v_and_b32_e32 v194, 15, v0
	v_lshrrev_b32_e32 v195, 4, v0
	v_and_b32_e32 v3, 7, v194
	v_xor_b32_e32 v3, v3, v195
	v_lshlrev_b32_e32 v3, 4, v3
	v_lshrrev_b32_e32 v176, 1, v1
	v_and_b32_e32 v177, 1, v1
	v_mul_u32_u24_e32 v178, 96, v176
	v_add_u32_e32 v179, v178, v194
	v_lshl_add_u32 v199, v179, 7, v3
	v_xor_b32_e32 v200, 64, v199
	v_lshl_add_u32 v179, v177, 6, v194
	v_lshl_add_u32 v201, v179, 7, v3
	v_add_u32_e32 v201, 0x6000, v201
	v_xor_b32_e32 v202, 64, v201
	s_sub_u32 s42, s42, 4
	s_mul_i32 s5, s42, 4352
	s_add_u32 s5, s5, 0x1e000
	v_mul_u32_u24_e32 v3, 1088, v195
	v_lshl_add_u32 v3, v194, 2, v3
	v_add_u32_e32 v203, s5, v3
	v_mul_u32_u24_e32 v3, 272, v195
	v_lshl_add_u32 v3, v194, 4, v3
	v_add_u32_e32 v204, s5, v3
	v_add_u32_e32 v190, v178, v195
	v_lshlrev_b32_e32 v3, 6, v177
	v_lshl_add_u32 v3, v194, 2, v3
	s_mov_b32 s4, 0x800
	v_mul_lo_u32 v205, v190, s4
	v_lshl_add_u32 v205, v3, 1, v205
	v_lshlrev_b32_e32 v191, 2, v3
	v_mov_b32_e32 v193, v3
	v_mov_b32_e32 v4, 0
	v_mov_b32_e32 v5, 0
	v_mov_b32_e32 v6, 0
	v_mov_b32_e32 v7, 0
	v_mov_b32_e32 v8, 0
	v_mov_b32_e32 v9, 0
	v_mov_b32_e32 v10, 0
	v_mov_b32_e32 v11, 0
	v_mov_b32_e32 v12, 0
	v_mov_b32_e32 v13, 0
	v_mov_b32_e32 v14, 0
	v_mov_b32_e32 v15, 0
	v_mov_b32_e32 v16, 0
	v_mov_b32_e32 v17, 0
	v_mov_b32_e32 v18, 0
	v_mov_b32_e32 v19, 0
	v_mov_b32_e32 v20, 0
	v_mov_b32_e32 v21, 0
	v_mov_b32_e32 v22, 0
	v_mov_b32_e32 v23, 0
	v_mov_b32_e32 v24, 0
	v_mov_b32_e32 v25, 0
	v_mov_b32_e32 v26, 0
	v_mov_b32_e32 v27, 0
	v_mov_b32_e32 v28, 0
	v_mov_b32_e32 v29, 0
	v_mov_b32_e32 v30, 0
	v_mov_b32_e32 v31, 0
	v_mov_b32_e32 v32, 0
	v_mov_b32_e32 v33, 0
	v_mov_b32_e32 v34, 0
	v_mov_b32_e32 v35, 0
	v_mov_b32_e32 v36, 0
	v_mov_b32_e32 v37, 0
	v_mov_b32_e32 v38, 0
	v_mov_b32_e32 v39, 0
	v_mov_b32_e32 v40, 0
	v_mov_b32_e32 v41, 0
	v_mov_b32_e32 v42, 0
	v_mov_b32_e32 v43, 0
	v_mov_b32_e32 v44, 0
	v_mov_b32_e32 v45, 0
	v_mov_b32_e32 v46, 0
	v_mov_b32_e32 v47, 0
	v_mov_b32_e32 v48, 0
	v_mov_b32_e32 v49, 0
	v_mov_b32_e32 v50, 0
	v_mov_b32_e32 v51, 0
	v_mov_b32_e32 v52, 0
	v_mov_b32_e32 v53, 0
	v_mov_b32_e32 v54, 0
	v_mov_b32_e32 v55, 0
	v_mov_b32_e32 v56, 0
	v_mov_b32_e32 v57, 0
	v_mov_b32_e32 v58, 0
	v_mov_b32_e32 v59, 0
	v_mov_b32_e32 v60, 0
	v_mov_b32_e32 v61, 0
	v_mov_b32_e32 v62, 0
	v_mov_b32_e32 v63, 0
	v_mov_b32_e32 v64, 0
	v_mov_b32_e32 v65, 0
	v_mov_b32_e32 v66, 0
	v_mov_b32_e32 v67, 0
	v_mov_b32_e32 v68, 0
	v_mov_b32_e32 v69, 0
	v_mov_b32_e32 v70, 0
	v_mov_b32_e32 v71, 0
	v_mov_b32_e32 v72, 0
	v_mov_b32_e32 v73, 0
	v_mov_b32_e32 v74, 0
	v_mov_b32_e32 v75, 0
	v_mov_b32_e32 v76, 0
	v_mov_b32_e32 v77, 0
	v_mov_b32_e32 v78, 0
	v_mov_b32_e32 v79, 0
	v_mov_b32_e32 v80, 0
	v_mov_b32_e32 v81, 0
	v_mov_b32_e32 v82, 0
	v_mov_b32_e32 v83, 0
	v_mov_b32_e32 v84, 0
	v_mov_b32_e32 v85, 0
	v_mov_b32_e32 v86, 0
	v_mov_b32_e32 v87, 0
	v_mov_b32_e32 v88, 0
	v_mov_b32_e32 v89, 0
	v_mov_b32_e32 v90, 0
	v_mov_b32_e32 v91, 0
	v_mov_b32_e32 v92, 0
	v_mov_b32_e32 v93, 0
	v_mov_b32_e32 v94, 0
	v_mov_b32_e32 v95, 0
	v_mov_b32_e32 v96, 0
	v_mov_b32_e32 v97, 0
	v_mov_b32_e32 v98, 0
	v_mov_b32_e32 v99, 0
	s_mov_b32 s34, 0
	s_mov_b32 s35, s53
	s_mov_b32 s40, 0

.Lgm_glu_join:
	s_waitcnt lgkmcnt(13)
	v_mfma_f32_16x16x32_bf16 v[4:7], v[100:103], v[124:127], v[4:7]
	v_mfma_f32_16x16x32_bf16 v[20:23], v[104:107], v[124:127], v[20:23]
	v_mfma_f32_16x16x32_bf16 v[36:39], v[108:111], v[124:127], v[36:39]
	v_mfma_f32_16x16x32_bf16 v[52:55], v[112:115], v[124:127], v[52:55]
	v_mfma_f32_16x16x32_bf16 v[68:71], v[116:119], v[124:127], v[68:71]
	v_mfma_f32_16x16x32_bf16 v[84:87], v[120:123], v[124:127], v[84:87]
	s_waitcnt lgkmcnt(12)
	v_mfma_f32_16x16x32_bf16 v[8:11], v[100:103], v[128:131], v[8:11]
	v_mfma_f32_16x16x32_bf16 v[24:27], v[104:107], v[128:131], v[24:27]
	v_mfma_f32_16x16x32_bf16 v[40:43], v[108:111], v[128:131], v[40:43]
	v_mfma_f32_16x16x32_bf16 v[56:59], v[112:115], v[128:131], v[56:59]
	v_mfma_f32_16x16x32_bf16 v[72:75], v[116:119], v[128:131], v[72:75]
	v_mfma_f32_16x16x32_bf16 v[88:91], v[120:123], v[128:131], v[88:91]
	s_waitcnt lgkmcnt(11)
	v_mfma_f32_16x16x32_bf16 v[12:15], v[100:103], v[132:135], v[12:15]
	v_mfma_f32_16x16x32_bf16 v[28:31], v[104:107], v[132:135], v[28:31]
	v_mfma_f32_16x16x32_bf16 v[44:47], v[108:111], v[132:135], v[44:47]
	v_mfma_f32_16x16x32_bf16 v[60:63], v[112:115], v[132:135], v[60:63]
	v_mfma_f32_16x16x32_bf16 v[76:79], v[116:119], v[132:135], v[76:79]
	v_mfma_f32_16x16x32_bf16 v[92:95], v[120:123], v[132:135], v[92:95]
	s_waitcnt lgkmcnt(10)
	v_mfma_f32_16x16x32_bf16 v[16:19], v[100:103], v[136:139], v[16:19]
	v_mfma_f32_16x16x32_bf16 v[32:35], v[104:107], v[136:139], v[32:35]
	v_mfma_f32_16x16x32_bf16 v[48:51], v[108:111], v[136:139], v[48:51]
	v_mfma_f32_16x16x32_bf16 v[64:67], v[112:115], v[136:139], v[64:67]
	v_mfma_f32_16x16x32_bf16 v[80:83], v[116:119], v[136:139], v[80:83]
	v_mfma_f32_16x16x32_bf16 v[96:99], v[120:123], v[136:139], v[96:99]
	s_waitcnt lgkmcnt(0)
	s_add_u32 s34, s34, 1
	s_add_u32 s31, s31, 1
	s_cmp_lt_u32 s34, 4
	s_cbranch_scc1 .Lgm_glu_rot
	v_mfma_f32_16x16x32_bf16 v[4:7], v[140:143], v[164:167], v[4:7]
	v_mfma_f32_16x16x32_bf16 v[20:23], v[144:147], v[164:167], v[20:23]
	v_mfma_f32_16x16x32_bf16 v[36:39], v[148:151], v[164:167], v[36:39]
	v_mfma_f32_16x16x32_bf16 v[52:55], v[152:155], v[164:167], v[52:55]
	v_mfma_f32_16x16x32_bf16 v[68:71], v[156:159], v[164:167], v[68:71]
	v_mfma_f32_16x16x32_bf16 v[84:87], v[160:163], v[164:167], v[84:87]
	v_mfma_f32_16x16x32_bf16 v[8:11], v[140:143], v[168:171], v[8:11]
	v_mfma_f32_16x16x32_bf16 v[24:27], v[144:147], v[168:171], v[24:27]
	v_mfma_f32_16x16x32_bf16 v[40:43], v[148:151], v[168:171], v[40:43]
	v_mfma_f32_16x16x32_bf16 v[56:59], v[152:155], v[168:171], v[56:59]
	v_mfma_f32_16x16x32_bf16 v[72:75], v[156:159], v[168:171], v[72:75]
	v_mfma_f32_16x16x32_bf16 v[88:91], v[160:163], v[168:171], v[88:91]
	v_mfma_f32_16x16x32_bf16 v[12:15], v[140:143], v[172:175], v[12:15]
	v_mfma_f32_16x16x32_bf16 v[28:31], v[144:147], v[172:175], v[28:31]
	v_mfma_f32_16x16x32_bf16 v[44:47], v[148:151], v[172:175], v[44:47]
	v_mfma_f32_16x16x32_bf16 v[60:63], v[152:155], v[172:175], v[60:63]
	v_mfma_f32_16x16x32_bf16 v[76:79], v[156:159], v[172:175], v[76:79]
	v_mfma_f32_16x16x32_bf16 v[92:95], v[160:163], v[172:175], v[92:95]
	v_mfma_f32_16x16x32_bf16 v[16:19], v[140:143], v[176:179], v[16:19]
	v_mfma_f32_16x16x32_bf16 v[32:35], v[144:147], v[176:179], v[32:35]
	v_mfma_f32_16x16x32_bf16 v[48:51], v[148:151], v[176:179], v[48:51]
	v_mfma_f32_16x16x32_bf16 v[64:67], v[152:155], v[176:179], v[64:67]
	v_mfma_f32_16x16x32_bf16 v[80:83], v[156:159], v[176:179], v[80:83]
	v_mfma_f32_16x16x32_bf16 v[96:99], v[160:163], v[176:179], v[96:99]
	s_and_b32 s6, s35, 31
	s_mul_i32 s6, s6, 192
	s_lshr_b32 s7, s35, 5
	s_lshl_b32 s7, s7, 7
	s_nop 7
	s_mul_i32 s4, s6, 0x800
	s_lshl_b32 s5, s7, 1
	s_add_u32 s4, s4, s5
	v_add_u32_e32 v197, s4, v205
	v_lshl_add_u32 v195, s7, 2, v191
	global_load_dwordx4 v[148:151], v195, s[100:101]
	s_lshl_b32 s4, s6, 9
	s_add_u32 s4, s4, s5
	v_lshlrev_b32_e32 v194, 9, v190
	v_lshl_add_u32 v194, v193, 1, v194
	v_add_u32_e32 v194, s4, v194
	global_load_dwordx2 v[100:101], v194, s[98:99]
	v_add_u32_e32 v194, 0x800, v194
	global_load_dwordx2 v[102:103], v194, s[98:99]
	v_add_u32_e32 v194, 0x800, v194
	global_load_dwordx2 v[104:105], v194, s[98:99]
	v_add_u32_e32 v194, 0x800, v194
	global_load_dwordx2 v[106:107], v194, s[98:99]
	v_add_u32_e32 v194, 0x800, v194
	global_load_dwordx2 v[108:109], v194, s[98:99]
	v_add_u32_e32 v194, 0x800, v194
	global_load_dwordx2 v[110:111], v194, s[98:99]
	v_add_u32_e32 v194, 0x800, v194
	global_load_dwordx2 v[112:113], v194, s[98:99]
	v_add_u32_e32 v194, 0x800, v194
	global_load_dwordx2 v[114:115], v194, s[98:99]
	v_add_u32_e32 v194, 0x800, v194
	global_load_dwordx2 v[116:117], v194, s[98:99]
	v_add_u32_e32 v194, 0x800, v194
	global_load_dwordx2 v[118:119], v194, s[98:99]
	v_add_u32_e32 v194, 0x800, v194
	global_load_dwordx2 v[120:121], v194, s[98:99]
	v_add_u32_e32 v194, 0x800, v194
	global_load_dwordx2 v[122:123], v194, s[98:99]
	v_add_u32_e32 v194, 0x800, v194
	global_load_dwordx2 v[124:125], v194, s[98:99]
	v_add_u32_e32 v194, 0x800, v194
	global_load_dwordx2 v[126:127], v194, s[98:99]
	v_add_u32_e32 v194, 0x800, v194
	global_load_dwordx2 v[128:129], v194, s[98:99]
	v_add_u32_e32 v194, 0x800, v194
	global_load_dwordx2 v[130:131], v194, s[98:99]
	v_add_u32_e32 v194, 0x800, v194
	global_load_dwordx2 v[132:133], v194, s[98:99]
	v_add_u32_e32 v194, 0x800, v194
	global_load_dwordx2 v[134:135], v194, s[98:99]
	v_add_u32_e32 v194, 0x800, v194
	global_load_dwordx2 v[136:137], v194, s[98:99]
	v_add_u32_e32 v194, 0x800, v194
	global_load_dwordx2 v[138:139], v194, s[98:99]
	v_add_u32_e32 v194, 0x800, v194
	global_load_dwordx2 v[140:141], v194, s[98:99]
	v_add_u32_e32 v194, 0x800, v194
	global_load_dwordx2 v[142:143], v194, s[98:99]
	v_add_u32_e32 v194, 0x800, v194
	global_load_dwordx2 v[144:145], v194, s[98:99]
	v_add_u32_e32 v194, 0x800, v194
	global_load_dwordx2 v[146:147], v194, s[98:99]
	ds_write_b32 v203, v4 offset:0
	ds_write_b32 v203, v5 offset:272
	ds_write_b32 v203, v6 offset:544
	ds_write_b32 v203, v7 offset:816
	ds_write_b32 v203, v8 offset:64
	ds_write_b32 v203, v9 offset:336
	ds_write_b32 v203, v10 offset:608
	ds_write_b32 v203, v11 offset:880
	ds_write_b32 v203, v12 offset:128
	ds_write_b32 v203, v13 offset:400
	ds_write_b32 v203, v14 offset:672
	ds_write_b32 v203, v15 offset:944
	ds_write_b32 v203, v16 offset:192
	ds_write_b32 v203, v17 offset:464
	ds_write_b32 v203, v18 offset:736
	ds_write_b32 v203, v19 offset:1008
	s_waitcnt lgkmcnt(0)
	ds_read_b128 v[156:159], v204 offset:0
	ds_read_b128 v[160:163], v204 offset:1088
	ds_read_b128 v[164:167], v204 offset:2176
	ds_read_b128 v[168:171], v204 offset:3264
	s_waitcnt vmcnt(23)
	s_waitcnt lgkmcnt(3)
	v_add_f32_e32 v156, v156, v148
	v_add_f32_e32 v157, v157, v149
	v_add_f32_e32 v158, v158, v150
	v_add_f32_e32 v159, v159, v151
	v_mul_f32_e32 v156, 0xbfb8aa3b, v156
	v_mul_f32_e32 v157, 0xbfb8aa3b, v157
	v_mul_f32_e32 v158, 0xbfb8aa3b, v158
	v_mul_f32_e32 v159, 0xbfb8aa3b, v159
	v_exp_f32_e32 v156, v156
	v_exp_f32_e32 v157, v157
	v_exp_f32_e32 v158, v158
	v_exp_f32_e32 v159, v159
	v_lshlrev_b32_e32 v172, 16, v100
	v_and_b32_e32 v173, s28, v100
	v_lshlrev_b32_e32 v174, 16, v101
	v_and_b32_e32 v175, s28, v101
	v_add_f32_e32 v156, 1.0, v156
	v_add_f32_e32 v157, 1.0, v157
	v_add_f32_e32 v158, 1.0, v158
	v_add_f32_e32 v159, 1.0, v159
	v_div_scale_f32 v0, vcc, v156, v156, 1.0
	v_rcp_f32_e32 v1, v0
	s_nop 0
	v_fma_f32 v3, -v0, v1, 1.0
	v_fmac_f32_e32 v1, v3, v1
	v_div_scale_f32 v3, vcc, 1.0, v156, 1.0
	v_mul_f32_e32 v152, v3, v1
	v_fma_f32 v153, -v0, v152, v3
	v_fmac_f32_e32 v152, v153, v1
	v_fma_f32 v0, -v0, v152, v3
	v_div_fmas_f32 v0, v0, v1, v152
	v_div_fixup_f32 v156, v0, v156, 1.0
	v_mul_f32_e32 v156, v156, v172
	v_div_scale_f32 v0, vcc, v157, v157, 1.0
	v_rcp_f32_e32 v1, v0
	s_nop 0
	v_fma_f32 v3, -v0, v1, 1.0
	v_fmac_f32_e32 v1, v3, v1
	v_div_scale_f32 v3, vcc, 1.0, v157, 1.0
	v_mul_f32_e32 v152, v3, v1
	v_fma_f32 v153, -v0, v152, v3
	v_fmac_f32_e32 v152, v153, v1
	v_fma_f32 v0, -v0, v152, v3
	v_div_fmas_f32 v0, v0, v1, v152
	v_div_fixup_f32 v157, v0, v157, 1.0
	v_mul_f32_e32 v157, v157, v173
	v_div_scale_f32 v0, vcc, v158, v158, 1.0
	v_rcp_f32_e32 v1, v0
	s_nop 0
	v_fma_f32 v3, -v0, v1, 1.0
	v_fmac_f32_e32 v1, v3, v1
	v_div_scale_f32 v3, vcc, 1.0, v158, 1.0
	v_mul_f32_e32 v152, v3, v1
	v_fma_f32 v153, -v0, v152, v3
	v_fmac_f32_e32 v152, v153, v1
	v_fma_f32 v0, -v0, v152, v3
	v_div_fmas_f32 v0, v0, v1, v152
	v_div_fixup_f32 v158, v0, v158, 1.0
	v_mul_f32_e32 v158, v158, v174
	v_div_scale_f32 v0, vcc, v159, v159, 1.0
	v_rcp_f32_e32 v1, v0
	s_nop 0
	v_fma_f32 v3, -v0, v1, 1.0
	v_fmac_f32_e32 v1, v3, v1
	v_div_scale_f32 v3, vcc, 1.0, v159, 1.0
	v_mul_f32_e32 v152, v3, v1
	v_fma_f32 v153, -v0, v152, v3
	v_fmac_f32_e32 v152, v153, v1
	v_fma_f32 v0, -v0, v152, v3
	v_div_fmas_f32 v0, v0, v1, v152
	v_div_fixup_f32 v159, v0, v159, 1.0
	v_mul_f32_e32 v159, v159, v175
	v_cvt_pk_bf16_f32 v176, v156, v157
	v_cvt_pk_bf16_f32 v177, v158, v159
	global_store_dwordx2 v197, v[176:177], s[56:57] sc0 sc1
	v_add_u32_e32 v197, 0x2000, v197
	s_waitcnt vmcnt(23)
	s_waitcnt lgkmcnt(2)
	v_add_f32_e32 v160, v160, v148
	v_add_f32_e32 v161, v161, v149
	v_add_f32_e32 v162, v162, v150
	v_add_f32_e32 v163, v163, v151
	v_mul_f32_e32 v160, 0xbfb8aa3b, v160
	v_mul_f32_e32 v161, 0xbfb8aa3b, v161
	v_mul_f32_e32 v162, 0xbfb8aa3b, v162
	v_mul_f32_e32 v163, 0xbfb8aa3b, v163
	v_exp_f32_e32 v160, v160
	v_exp_f32_e32 v161, v161
	v_exp_f32_e32 v162, v162
	v_exp_f32_e32 v163, v163
	v_lshlrev_b32_e32 v172, 16, v102
	v_and_b32_e32 v173, s28, v102
	v_lshlrev_b32_e32 v174, 16, v103
	v_and_b32_e32 v175, s28, v103
	v_add_f32_e32 v160, 1.0, v160
	v_add_f32_e32 v161, 1.0, v161
	v_add_f32_e32 v162, 1.0, v162
	v_add_f32_e32 v163, 1.0, v163
	v_div_scale_f32 v0, vcc, v160, v160, 1.0
	v_rcp_f32_e32 v1, v0
	s_nop 0
	v_fma_f32 v3, -v0, v1, 1.0
	v_fmac_f32_e32 v1, v3, v1
	v_div_scale_f32 v3, vcc, 1.0, v160, 1.0
	v_mul_f32_e32 v152, v3, v1
	v_fma_f32 v153, -v0, v152, v3
	v_fmac_f32_e32 v152, v153, v1
	v_fma_f32 v0, -v0, v152, v3
	v_div_fmas_f32 v0, v0, v1, v152
	v_div_fixup_f32 v160, v0, v160, 1.0
	v_mul_f32_e32 v160, v160, v172
	v_div_scale_f32 v0, vcc, v161, v161, 1.0
	v_rcp_f32_e32 v1, v0
	s_nop 0
	v_fma_f32 v3, -v0, v1, 1.0
	v_fmac_f32_e32 v1, v3, v1
	v_div_scale_f32 v3, vcc, 1.0, v161, 1.0
	v_mul_f32_e32 v152, v3, v1
	v_fma_f32 v153, -v0, v152, v3
	v_fmac_f32_e32 v152, v153, v1
	v_fma_f32 v0, -v0, v152, v3
	v_div_fmas_f32 v0, v0, v1, v152
	v_div_fixup_f32 v161, v0, v161, 1.0
	v_mul_f32_e32 v161, v161, v173
	v_div_scale_f32 v0, vcc, v162, v162, 1.0
	v_rcp_f32_e32 v1, v0
	s_nop 0
	v_fma_f32 v3, -v0, v1, 1.0
	v_fmac_f32_e32 v1, v3, v1
	v_div_scale_f32 v3, vcc, 1.0, v162, 1.0
	v_mul_f32_e32 v152, v3, v1
	v_fma_f32 v153, -v0, v152, v3
	v_fmac_f32_e32 v152, v153, v1
	v_fma_f32 v0, -v0, v152, v3
	v_div_fmas_f32 v0, v0, v1, v152
	v_div_fixup_f32 v162, v0, v162, 1.0
	v_mul_f32_e32 v162, v162, v174
	v_div_scale_f32 v0, vcc, v163, v163, 1.0
	v_rcp_f32_e32 v1, v0
	s_nop 0
	v_fma_f32 v3, -v0, v1, 1.0
	v_fmac_f32_e32 v1, v3, v1
	v_div_scale_f32 v3, vcc, 1.0, v163, 1.0
	v_mul_f32_e32 v152, v3, v1
	v_fma_f32 v153, -v0, v152, v3
	v_fmac_f32_e32 v152, v153, v1
	v_fma_f32 v0, -v0, v152, v3
	v_div_fmas_f32 v0, v0, v1, v152
	v_div_fixup_f32 v163, v0, v163, 1.0
	v_mul_f32_e32 v163, v163, v175
	v_cvt_pk_bf16_f32 v178, v160, v161
	v_cvt_pk_bf16_f32 v179, v162, v163
	global_store_dwordx2 v197, v[178:179], s[56:57] sc0 sc1
	v_add_u32_e32 v197, 0x2000, v197
	s_waitcnt vmcnt(23)
	s_waitcnt lgkmcnt(1)
	v_add_f32_e32 v164, v164, v148
	v_add_f32_e32 v165, v165, v149
	v_add_f32_e32 v166, v166, v150
	v_add_f32_e32 v167, v167, v151
	v_mul_f32_e32 v164, 0xbfb8aa3b, v164
	v_mul_f32_e32 v165, 0xbfb8aa3b, v165
	v_mul_f32_e32 v166, 0xbfb8aa3b, v166
	v_mul_f32_e32 v167, 0xbfb8aa3b, v167
	v_exp_f32_e32 v164, v164
	v_exp_f32_e32 v165, v165
	v_exp_f32_e32 v166, v166
	v_exp_f32_e32 v167, v167
	v_lshlrev_b32_e32 v172, 16, v104
	v_and_b32_e32 v173, s28, v104
	v_lshlrev_b32_e32 v174, 16, v105
	v_and_b32_e32 v175, s28, v105
	v_add_f32_e32 v164, 1.0, v164
	v_add_f32_e32 v165, 1.0, v165
	v_add_f32_e32 v166, 1.0, v166
	v_add_f32_e32 v167, 1.0, v167
	v_div_scale_f32 v0, vcc, v164, v164, 1.0
	v_rcp_f32_e32 v1, v0
	s_nop 0
	v_fma_f32 v3, -v0, v1, 1.0
	v_fmac_f32_e32 v1, v3, v1
	v_div_scale_f32 v3, vcc, 1.0, v164, 1.0
	v_mul_f32_e32 v152, v3, v1
	v_fma_f32 v153, -v0, v152, v3
	v_fmac_f32_e32 v152, v153, v1
	v_fma_f32 v0, -v0, v152, v3
	v_div_fmas_f32 v0, v0, v1, v152
	v_div_fixup_f32 v164, v0, v164, 1.0
	v_mul_f32_e32 v164, v164, v172
	v_div_scale_f32 v0, vcc, v165, v165, 1.0
	v_rcp_f32_e32 v1, v0
	s_nop 0
	v_fma_f32 v3, -v0, v1, 1.0
	v_fmac_f32_e32 v1, v3, v1
	v_div_scale_f32 v3, vcc, 1.0, v165, 1.0
	v_mul_f32_e32 v152, v3, v1
	v_fma_f32 v153, -v0, v152, v3
	v_fmac_f32_e32 v152, v153, v1
	v_fma_f32 v0, -v0, v152, v3
	v_div_fmas_f32 v0, v0, v1, v152
	v_div_fixup_f32 v165, v0, v165, 1.0
	v_mul_f32_e32 v165, v165, v173
	v_div_scale_f32 v0, vcc, v166, v166, 1.0
	v_rcp_f32_e32 v1, v0
	s_nop 0
	v_fma_f32 v3, -v0, v1, 1.0
	v_fmac_f32_e32 v1, v3, v1
	v_div_scale_f32 v3, vcc, 1.0, v166, 1.0
	v_mul_f32_e32 v152, v3, v1
	v_fma_f32 v153, -v0, v152, v3
	v_fmac_f32_e32 v152, v153, v1
	v_fma_f32 v0, -v0, v152, v3
	v_div_fmas_f32 v0, v0, v1, v152
	v_div_fixup_f32 v166, v0, v166, 1.0
	v_mul_f32_e32 v166, v166, v174
	v_div_scale_f32 v0, vcc, v167, v167, 1.0
	v_rcp_f32_e32 v1, v0
	s_nop 0
	v_fma_f32 v3, -v0, v1, 1.0
	v_fmac_f32_e32 v1, v3, v1
	v_div_scale_f32 v3, vcc, 1.0, v167, 1.0
	v_mul_f32_e32 v152, v3, v1
	v_fma_f32 v153, -v0, v152, v3
	v_fmac_f32_e32 v152, v153, v1
	v_fma_f32 v0, -v0, v152, v3
	v_div_fmas_f32 v0, v0, v1, v152
	v_div_fixup_f32 v167, v0, v167, 1.0
	v_mul_f32_e32 v167, v167, v175
	v_cvt_pk_bf16_f32 v176, v164, v165
	v_cvt_pk_bf16_f32 v177, v166, v167
	global_store_dwordx2 v197, v[176:177], s[56:57] sc0 sc1
	v_add_u32_e32 v197, 0x2000, v197
	s_waitcnt vmcnt(23)
	s_waitcnt lgkmcnt(0)
	v_add_f32_e32 v168, v168, v148
	v_add_f32_e32 v169, v169, v149
	v_add_f32_e32 v170, v170, v150
	v_add_f32_e32 v171, v171, v151
	v_mul_f32_e32 v168, 0xbfb8aa3b, v168
	v_mul_f32_e32 v169, 0xbfb8aa3b, v169
	v_mul_f32_e32 v170, 0xbfb8aa3b, v170
	v_mul_f32_e32 v171, 0xbfb8aa3b, v171
	v_exp_f32_e32 v168, v168
	v_exp_f32_e32 v169, v169
	v_exp_f32_e32 v170, v170
	v_exp_f32_e32 v171, v171
	v_lshlrev_b32_e32 v172, 16, v106
	v_and_b32_e32 v173, s28, v106
	v_lshlrev_b32_e32 v174, 16, v107
	v_and_b32_e32 v175, s28, v107
	v_add_f32_e32 v168, 1.0, v168
	v_add_f32_e32 v169, 1.0, v169
	v_add_f32_e32 v170, 1.0, v170
	v_add_f32_e32 v171, 1.0, v171
	v_div_scale_f32 v0, vcc, v168, v168, 1.0
	v_rcp_f32_e32 v1, v0
	s_nop 0
	v_fma_f32 v3, -v0, v1, 1.0
	v_fmac_f32_e32 v1, v3, v1
	v_div_scale_f32 v3, vcc, 1.0, v168, 1.0
	v_mul_f32_e32 v152, v3, v1
	v_fma_f32 v153, -v0, v152, v3
	v_fmac_f32_e32 v152, v153, v1
	v_fma_f32 v0, -v0, v152, v3
	v_div_fmas_f32 v0, v0, v1, v152
	v_div_fixup_f32 v168, v0, v168, 1.0
	v_mul_f32_e32 v168, v168, v172
	v_div_scale_f32 v0, vcc, v169, v169, 1.0
	v_rcp_f32_e32 v1, v0
	s_nop 0
	v_fma_f32 v3, -v0, v1, 1.0
	v_fmac_f32_e32 v1, v3, v1
	v_div_scale_f32 v3, vcc, 1.0, v169, 1.0
	v_mul_f32_e32 v152, v3, v1
	v_fma_f32 v153, -v0, v152, v3
	v_fmac_f32_e32 v152, v153, v1
	v_fma_f32 v0, -v0, v152, v3
	v_div_fmas_f32 v0, v0, v1, v152
	v_div_fixup_f32 v169, v0, v169, 1.0
	v_mul_f32_e32 v169, v169, v173
	v_div_scale_f32 v0, vcc, v170, v170, 1.0
	v_rcp_f32_e32 v1, v0
	s_nop 0
	v_fma_f32 v3, -v0, v1, 1.0
	v_fmac_f32_e32 v1, v3, v1
	v_div_scale_f32 v3, vcc, 1.0, v170, 1.0
	v_mul_f32_e32 v152, v3, v1
	v_fma_f32 v153, -v0, v152, v3
	v_fmac_f32_e32 v152, v153, v1
	v_fma_f32 v0, -v0, v152, v3
	v_div_fmas_f32 v0, v0, v1, v152
	v_div_fixup_f32 v170, v0, v170, 1.0
	v_mul_f32_e32 v170, v170, v174
	v_div_scale_f32 v0, vcc, v171, v171, 1.0
	v_rcp_f32_e32 v1, v0
	s_nop 0
	v_fma_f32 v3, -v0, v1, 1.0
	v_fmac_f32_e32 v1, v3, v1
	v_div_scale_f32 v3, vcc, 1.0, v171, 1.0
	v_mul_f32_e32 v152, v3, v1
	v_fma_f32 v153, -v0, v152, v3
	v_fmac_f32_e32 v152, v153, v1
	v_fma_f32 v0, -v0, v152, v3
	v_div_fmas_f32 v0, v0, v1, v152
	v_div_fixup_f32 v171, v0, v171, 1.0
	v_mul_f32_e32 v171, v171, v175
	v_cvt_pk_bf16_f32 v178, v168, v169
	v_cvt_pk_bf16_f32 v179, v170, v171
	global_store_dwordx2 v197, v[178:179], s[56:57] sc0 sc1
	v_add_u32_e32 v197, 0x2000, v197
	ds_write_b32 v203, v20 offset:0
	ds_write_b32 v203, v21 offset:272
	ds_write_b32 v203, v22 offset:544
	ds_write_b32 v203, v23 offset:816
	ds_write_b32 v203, v24 offset:64
	ds_write_b32 v203, v25 offset:336
	ds_write_b32 v203, v26 offset:608
	ds_write_b32 v203, v27 offset:880
	ds_write_b32 v203, v28 offset:128
	ds_write_b32 v203, v29 offset:400
	ds_write_b32 v203, v30 offset:672
	ds_write_b32 v203, v31 offset:944
	ds_write_b32 v203, v32 offset:192
	ds_write_b32 v203, v33 offset:464
	ds_write_b32 v203, v34 offset:736
	ds_write_b32 v203, v35 offset:1008
	s_waitcnt lgkmcnt(0)
	ds_read_b128 v[156:159], v204 offset:0
	ds_read_b128 v[160:163], v204 offset:1088
	ds_read_b128 v[164:167], v204 offset:2176
	ds_read_b128 v[168:171], v204 offset:3264
	s_waitcnt vmcnt(23)
	s_waitcnt lgkmcnt(3)
	v_add_f32_e32 v156, v156, v148
	v_add_f32_e32 v157, v157, v149
	v_add_f32_e32 v158, v158, v150
	v_add_f32_e32 v159, v159, v151
	v_mul_f32_e32 v156, 0xbfb8aa3b, v156
	v_mul_f32_e32 v157, 0xbfb8aa3b, v157
	v_mul_f32_e32 v158, 0xbfb8aa3b, v158
	v_mul_f32_e32 v159, 0xbfb8aa3b, v159
	v_exp_f32_e32 v156, v156
	v_exp_f32_e32 v157, v157
	v_exp_f32_e32 v158, v158
	v_exp_f32_e32 v159, v159
	v_lshlrev_b32_e32 v172, 16, v108
	v_and_b32_e32 v173, s28, v108
	v_lshlrev_b32_e32 v174, 16, v109
	v_and_b32_e32 v175, s28, v109
	v_add_f32_e32 v156, 1.0, v156
	v_add_f32_e32 v157, 1.0, v157
	v_add_f32_e32 v158, 1.0, v158
	v_add_f32_e32 v159, 1.0, v159
	v_div_scale_f32 v0, vcc, v156, v156, 1.0
	v_rcp_f32_e32 v1, v0
	s_nop 0
	v_fma_f32 v3, -v0, v1, 1.0
	v_fmac_f32_e32 v1, v3, v1
	v_div_scale_f32 v3, vcc, 1.0, v156, 1.0
	v_mul_f32_e32 v152, v3, v1
	v_fma_f32 v153, -v0, v152, v3
	v_fmac_f32_e32 v152, v153, v1
	v_fma_f32 v0, -v0, v152, v3
	v_div_fmas_f32 v0, v0, v1, v152
	v_div_fixup_f32 v156, v0, v156, 1.0
	v_mul_f32_e32 v156, v156, v172
	v_div_scale_f32 v0, vcc, v157, v157, 1.0
	v_rcp_f32_e32 v1, v0
	s_nop 0
	v_fma_f32 v3, -v0, v1, 1.0
	v_fmac_f32_e32 v1, v3, v1
	v_div_scale_f32 v3, vcc, 1.0, v157, 1.0
	v_mul_f32_e32 v152, v3, v1
	v_fma_f32 v153, -v0, v152, v3
	v_fmac_f32_e32 v152, v153, v1
	v_fma_f32 v0, -v0, v152, v3
	v_div_fmas_f32 v0, v0, v1, v152
	v_div_fixup_f32 v157, v0, v157, 1.0
	v_mul_f32_e32 v157, v157, v173
	v_div_scale_f32 v0, vcc, v158, v158, 1.0
	v_rcp_f32_e32 v1, v0
	s_nop 0
	v_fma_f32 v3, -v0, v1, 1.0
	v_fmac_f32_e32 v1, v3, v1
	v_div_scale_f32 v3, vcc, 1.0, v158, 1.0
	v_mul_f32_e32 v152, v3, v1
	v_fma_f32 v153, -v0, v152, v3
	v_fmac_f32_e32 v152, v153, v1
	v_fma_f32 v0, -v0, v152, v3
	v_div_fmas_f32 v0, v0, v1, v152
	v_div_fixup_f32 v158, v0, v158, 1.0
	v_mul_f32_e32 v158, v158, v174
	v_div_scale_f32 v0, vcc, v159, v159, 1.0
	v_rcp_f32_e32 v1, v0
	s_nop 0
	v_fma_f32 v3, -v0, v1, 1.0
	v_fmac_f32_e32 v1, v3, v1
	v_div_scale_f32 v3, vcc, 1.0, v159, 1.0
	v_mul_f32_e32 v152, v3, v1
	v_fma_f32 v153, -v0, v152, v3
	v_fmac_f32_e32 v152, v153, v1
	v_fma_f32 v0, -v0, v152, v3
	v_div_fmas_f32 v0, v0, v1, v152
	v_div_fixup_f32 v159, v0, v159, 1.0
	v_mul_f32_e32 v159, v159, v175
	v_cvt_pk_bf16_f32 v176, v156, v157
	v_cvt_pk_bf16_f32 v177, v158, v159
	global_store_dwordx2 v197, v[176:177], s[56:57] sc0 sc1
	v_add_u32_e32 v197, 0x2000, v197
	s_waitcnt vmcnt(23)
	s_waitcnt lgkmcnt(2)
	v_add_f32_e32 v160, v160, v148
	v_add_f32_e32 v161, v161, v149
	v_add_f32_e32 v162, v162, v150
	v_add_f32_e32 v163, v163, v151
	v_mul_f32_e32 v160, 0xbfb8aa3b, v160
	v_mul_f32_e32 v161, 0xbfb8aa3b, v161
	v_mul_f32_e32 v162, 0xbfb8aa3b, v162
	v_mul_f32_e32 v163, 0xbfb8aa3b, v163
	v_exp_f32_e32 v160, v160
	v_exp_f32_e32 v161, v161
	v_exp_f32_e32 v162, v162
	v_exp_f32_e32 v163, v163
	v_lshlrev_b32_e32 v172, 16, v110
	v_and_b32_e32 v173, s28, v110
	v_lshlrev_b32_e32 v174, 16, v111
	v_and_b32_e32 v175, s28, v111
	v_add_f32_e32 v160, 1.0, v160
	v_add_f32_e32 v161, 1.0, v161
	v_add_f32_e32 v162, 1.0, v162
	v_add_f32_e32 v163, 1.0, v163
	v_div_scale_f32 v0, vcc, v160, v160, 1.0
	v_rcp_f32_e32 v1, v0
	s_nop 0
	v_fma_f32 v3, -v0, v1, 1.0
	v_fmac_f32_e32 v1, v3, v1
	v_div_scale_f32 v3, vcc, 1.0, v160, 1.0
	v_mul_f32_e32 v152, v3, v1
	v_fma_f32 v153, -v0, v152, v3
	v_fmac_f32_e32 v152, v153, v1
	v_fma_f32 v0, -v0, v152, v3
	v_div_fmas_f32 v0, v0, v1, v152
	v_div_fixup_f32 v160, v0, v160, 1.0
	v_mul_f32_e32 v160, v160, v172
	v_div_scale_f32 v0, vcc, v161, v161, 1.0
	v_rcp_f32_e32 v1, v0
	s_nop 0
	v_fma_f32 v3, -v0, v1, 1.0
	v_fmac_f32_e32 v1, v3, v1
	v_div_scale_f32 v3, vcc, 1.0, v161, 1.0
	v_mul_f32_e32 v152, v3, v1
	v_fma_f32 v153, -v0, v152, v3
	v_fmac_f32_e32 v152, v153, v1
	v_fma_f32 v0, -v0, v152, v3
	v_div_fmas_f32 v0, v0, v1, v152
	v_div_fixup_f32 v161, v0, v161, 1.0
	v_mul_f32_e32 v161, v161, v173
	v_div_scale_f32 v0, vcc, v162, v162, 1.0
	v_rcp_f32_e32 v1, v0
	s_nop 0
	v_fma_f32 v3, -v0, v1, 1.0
	v_fmac_f32_e32 v1, v3, v1
	v_div_scale_f32 v3, vcc, 1.0, v162, 1.0
	v_mul_f32_e32 v152, v3, v1
	v_fma_f32 v153, -v0, v152, v3
	v_fmac_f32_e32 v152, v153, v1
	v_fma_f32 v0, -v0, v152, v3
	v_div_fmas_f32 v0, v0, v1, v152
	v_div_fixup_f32 v162, v0, v162, 1.0
	v_mul_f32_e32 v162, v162, v174
	v_div_scale_f32 v0, vcc, v163, v163, 1.0
	v_rcp_f32_e32 v1, v0
	s_nop 0
	v_fma_f32 v3, -v0, v1, 1.0
	v_fmac_f32_e32 v1, v3, v1
	v_div_scale_f32 v3, vcc, 1.0, v163, 1.0
	v_mul_f32_e32 v152, v3, v1
	v_fma_f32 v153, -v0, v152, v3
	v_fmac_f32_e32 v152, v153, v1
	v_fma_f32 v0, -v0, v152, v3
	v_div_fmas_f32 v0, v0, v1, v152
	v_div_fixup_f32 v163, v0, v163, 1.0
	v_mul_f32_e32 v163, v163, v175
	v_cvt_pk_bf16_f32 v178, v160, v161
	v_cvt_pk_bf16_f32 v179, v162, v163
	global_store_dwordx2 v197, v[178:179], s[56:57] sc0 sc1
	v_add_u32_e32 v197, 0x2000, v197
	s_waitcnt vmcnt(23)
	s_waitcnt lgkmcnt(1)
	v_add_f32_e32 v164, v164, v148
	v_add_f32_e32 v165, v165, v149
	v_add_f32_e32 v166, v166, v150
	v_add_f32_e32 v167, v167, v151
	v_mul_f32_e32 v164, 0xbfb8aa3b, v164
	v_mul_f32_e32 v165, 0xbfb8aa3b, v165
	v_mul_f32_e32 v166, 0xbfb8aa3b, v166
	v_mul_f32_e32 v167, 0xbfb8aa3b, v167
	v_exp_f32_e32 v164, v164
	v_exp_f32_e32 v165, v165
	v_exp_f32_e32 v166, v166
	v_exp_f32_e32 v167, v167
	v_lshlrev_b32_e32 v172, 16, v112
	v_and_b32_e32 v173, s28, v112
	v_lshlrev_b32_e32 v174, 16, v113
	v_and_b32_e32 v175, s28, v113
	v_add_f32_e32 v164, 1.0, v164
	v_add_f32_e32 v165, 1.0, v165
	v_add_f32_e32 v166, 1.0, v166
	v_add_f32_e32 v167, 1.0, v167
	v_div_scale_f32 v0, vcc, v164, v164, 1.0
	v_rcp_f32_e32 v1, v0
	s_nop 0
	v_fma_f32 v3, -v0, v1, 1.0
	v_fmac_f32_e32 v1, v3, v1
	v_div_scale_f32 v3, vcc, 1.0, v164, 1.0
	v_mul_f32_e32 v152, v3, v1
	v_fma_f32 v153, -v0, v152, v3
	v_fmac_f32_e32 v152, v153, v1
	v_fma_f32 v0, -v0, v152, v3
	v_div_fmas_f32 v0, v0, v1, v152
	v_div_fixup_f32 v164, v0, v164, 1.0
	v_mul_f32_e32 v164, v164, v172
	v_div_scale_f32 v0, vcc, v165, v165, 1.0
	v_rcp_f32_e32 v1, v0
	s_nop 0
	v_fma_f32 v3, -v0, v1, 1.0
	v_fmac_f32_e32 v1, v3, v1
	v_div_scale_f32 v3, vcc, 1.0, v165, 1.0
	v_mul_f32_e32 v152, v3, v1
	v_fma_f32 v153, -v0, v152, v3
	v_fmac_f32_e32 v152, v153, v1
	v_fma_f32 v0, -v0, v152, v3
	v_div_fmas_f32 v0, v0, v1, v152
	v_div_fixup_f32 v165, v0, v165, 1.0
	v_mul_f32_e32 v165, v165, v173
	v_div_scale_f32 v0, vcc, v166, v166, 1.0
	v_rcp_f32_e32 v1, v0
	s_nop 0
	v_fma_f32 v3, -v0, v1, 1.0
	v_fmac_f32_e32 v1, v3, v1
	v_div_scale_f32 v3, vcc, 1.0, v166, 1.0
	v_mul_f32_e32 v152, v3, v1
	v_fma_f32 v153, -v0, v152, v3
	v_fmac_f32_e32 v152, v153, v1
	v_fma_f32 v0, -v0, v152, v3
	v_div_fmas_f32 v0, v0, v1, v152
	v_div_fixup_f32 v166, v0, v166, 1.0
	v_mul_f32_e32 v166, v166, v174
	v_div_scale_f32 v0, vcc, v167, v167, 1.0
	v_rcp_f32_e32 v1, v0
	s_nop 0
	v_fma_f32 v3, -v0, v1, 1.0
	v_fmac_f32_e32 v1, v3, v1
	v_div_scale_f32 v3, vcc, 1.0, v167, 1.0
	v_mul_f32_e32 v152, v3, v1
	v_fma_f32 v153, -v0, v152, v3
	v_fmac_f32_e32 v152, v153, v1
	v_fma_f32 v0, -v0, v152, v3
	v_div_fmas_f32 v0, v0, v1, v152
	v_div_fixup_f32 v167, v0, v167, 1.0
	v_mul_f32_e32 v167, v167, v175
	v_cvt_pk_bf16_f32 v176, v164, v165
	v_cvt_pk_bf16_f32 v177, v166, v167
	global_store_dwordx2 v197, v[176:177], s[56:57] sc0 sc1
	v_add_u32_e32 v197, 0x2000, v197
	s_waitcnt vmcnt(23)
	s_waitcnt lgkmcnt(0)
	v_add_f32_e32 v168, v168, v148
	v_add_f32_e32 v169, v169, v149
	v_add_f32_e32 v170, v170, v150
	v_add_f32_e32 v171, v171, v151
	v_mul_f32_e32 v168, 0xbfb8aa3b, v168
	v_mul_f32_e32 v169, 0xbfb8aa3b, v169
	v_mul_f32_e32 v170, 0xbfb8aa3b, v170
	v_mul_f32_e32 v171, 0xbfb8aa3b, v171
	v_exp_f32_e32 v168, v168
	v_exp_f32_e32 v169, v169
	v_exp_f32_e32 v170, v170
	v_exp_f32_e32 v171, v171
	v_lshlrev_b32_e32 v172, 16, v114
	v_and_b32_e32 v173, s28, v114
	v_lshlrev_b32_e32 v174, 16, v115
	v_and_b32_e32 v175, s28, v115
	v_add_f32_e32 v168, 1.0, v168
	v_add_f32_e32 v169, 1.0, v169
	v_add_f32_e32 v170, 1.0, v170
	v_add_f32_e32 v171, 1.0, v171
	v_div_scale_f32 v0, vcc, v168, v168, 1.0
	v_rcp_f32_e32 v1, v0
	s_nop 0
	v_fma_f32 v3, -v0, v1, 1.0
	v_fmac_f32_e32 v1, v3, v1
	v_div_scale_f32 v3, vcc, 1.0, v168, 1.0
	v_mul_f32_e32 v152, v3, v1
	v_fma_f32 v153, -v0, v152, v3
	v_fmac_f32_e32 v152, v153, v1
	v_fma_f32 v0, -v0, v152, v3
	v_div_fmas_f32 v0, v0, v1, v152
	v_div_fixup_f32 v168, v0, v168, 1.0
	v_mul_f32_e32 v168, v168, v172
	v_div_scale_f32 v0, vcc, v169, v169, 1.0
	v_rcp_f32_e32 v1, v0
	s_nop 0
	v_fma_f32 v3, -v0, v1, 1.0
	v_fmac_f32_e32 v1, v3, v1
	v_div_scale_f32 v3, vcc, 1.0, v169, 1.0
	v_mul_f32_e32 v152, v3, v1
	v_fma_f32 v153, -v0, v152, v3
	v_fmac_f32_e32 v152, v153, v1
	v_fma_f32 v0, -v0, v152, v3
	v_div_fmas_f32 v0, v0, v1, v152
	v_div_fixup_f32 v169, v0, v169, 1.0
	v_mul_f32_e32 v169, v169, v173
	v_div_scale_f32 v0, vcc, v170, v170, 1.0
	v_rcp_f32_e32 v1, v0
	s_nop 0
	v_fma_f32 v3, -v0, v1, 1.0
	v_fmac_f32_e32 v1, v3, v1
	v_div_scale_f32 v3, vcc, 1.0, v170, 1.0
	v_mul_f32_e32 v152, v3, v1
	v_fma_f32 v153, -v0, v152, v3
	v_fmac_f32_e32 v152, v153, v1
	v_fma_f32 v0, -v0, v152, v3
	v_div_fmas_f32 v0, v0, v1, v152
	v_div_fixup_f32 v170, v0, v170, 1.0
	v_mul_f32_e32 v170, v170, v174
	v_div_scale_f32 v0, vcc, v171, v171, 1.0
	v_rcp_f32_e32 v1, v0
	s_nop 0
	v_fma_f32 v3, -v0, v1, 1.0
	v_fmac_f32_e32 v1, v3, v1
	v_div_scale_f32 v3, vcc, 1.0, v171, 1.0
	v_mul_f32_e32 v152, v3, v1
	v_fma_f32 v153, -v0, v152, v3
	v_fmac_f32_e32 v152, v153, v1
	v_fma_f32 v0, -v0, v152, v3
	v_div_fmas_f32 v0, v0, v1, v152
	v_div_fixup_f32 v171, v0, v171, 1.0
	v_mul_f32_e32 v171, v171, v175
	v_cvt_pk_bf16_f32 v178, v168, v169
	v_cvt_pk_bf16_f32 v179, v170, v171
	global_store_dwordx2 v197, v[178:179], s[56:57] sc0 sc1
	v_add_u32_e32 v197, 0x2000, v197
	ds_write_b32 v203, v36 offset:0
	ds_write_b32 v203, v37 offset:272
	ds_write_b32 v203, v38 offset:544
	ds_write_b32 v203, v39 offset:816
	ds_write_b32 v203, v40 offset:64
	ds_write_b32 v203, v41 offset:336
	ds_write_b32 v203, v42 offset:608
	ds_write_b32 v203, v43 offset:880
	ds_write_b32 v203, v44 offset:128
	ds_write_b32 v203, v45 offset:400
	ds_write_b32 v203, v46 offset:672
	ds_write_b32 v203, v47 offset:944
	ds_write_b32 v203, v48 offset:192
	ds_write_b32 v203, v49 offset:464
	ds_write_b32 v203, v50 offset:736
	ds_write_b32 v203, v51 offset:1008
	s_waitcnt lgkmcnt(0)
	ds_read_b128 v[156:159], v204 offset:0
	ds_read_b128 v[160:163], v204 offset:1088
	ds_read_b128 v[164:167], v204 offset:2176
	ds_read_b128 v[168:171], v204 offset:3264
	s_waitcnt vmcnt(23)
	s_waitcnt lgkmcnt(3)
	v_add_f32_e32 v156, v156, v148
	v_add_f32_e32 v157, v157, v149
	v_add_f32_e32 v158, v158, v150
	v_add_f32_e32 v159, v159, v151
	v_mul_f32_e32 v156, 0xbfb8aa3b, v156
	v_mul_f32_e32 v157, 0xbfb8aa3b, v157
	v_mul_f32_e32 v158, 0xbfb8aa3b, v158
	v_mul_f32_e32 v159, 0xbfb8aa3b, v159
	v_exp_f32_e32 v156, v156
	v_exp_f32_e32 v157, v157
	v_exp_f32_e32 v158, v158
	v_exp_f32_e32 v159, v159
	v_lshlrev_b32_e32 v172, 16, v116
	v_and_b32_e32 v173, s28, v116
	v_lshlrev_b32_e32 v174, 16, v117
	v_and_b32_e32 v175, s28, v117
	v_add_f32_e32 v156, 1.0, v156
	v_add_f32_e32 v157, 1.0, v157
	v_add_f32_e32 v158, 1.0, v158
	v_add_f32_e32 v159, 1.0, v159
	v_div_scale_f32 v0, vcc, v156, v156, 1.0
	v_rcp_f32_e32 v1, v0
	s_nop 0
	v_fma_f32 v3, -v0, v1, 1.0
	v_fmac_f32_e32 v1, v3, v1
	v_div_scale_f32 v3, vcc, 1.0, v156, 1.0
	v_mul_f32_e32 v152, v3, v1
	v_fma_f32 v153, -v0, v152, v3
	v_fmac_f32_e32 v152, v153, v1
	v_fma_f32 v0, -v0, v152, v3
	v_div_fmas_f32 v0, v0, v1, v152
	v_div_fixup_f32 v156, v0, v156, 1.0
	v_mul_f32_e32 v156, v156, v172
	v_div_scale_f32 v0, vcc, v157, v157, 1.0
	v_rcp_f32_e32 v1, v0
	s_nop 0
	v_fma_f32 v3, -v0, v1, 1.0
	v_fmac_f32_e32 v1, v3, v1
	v_div_scale_f32 v3, vcc, 1.0, v157, 1.0
	v_mul_f32_e32 v152, v3, v1
	v_fma_f32 v153, -v0, v152, v3
	v_fmac_f32_e32 v152, v153, v1
	v_fma_f32 v0, -v0, v152, v3
	v_div_fmas_f32 v0, v0, v1, v152
	v_div_fixup_f32 v157, v0, v157, 1.0
	v_mul_f32_e32 v157, v157, v173
	v_div_scale_f32 v0, vcc, v158, v158, 1.0
	v_rcp_f32_e32 v1, v0
	s_nop 0
	v_fma_f32 v3, -v0, v1, 1.0
	v_fmac_f32_e32 v1, v3, v1
	v_div_scale_f32 v3, vcc, 1.0, v158, 1.0
	v_mul_f32_e32 v152, v3, v1
	v_fma_f32 v153, -v0, v152, v3
	v_fmac_f32_e32 v152, v153, v1
	v_fma_f32 v0, -v0, v152, v3
	v_div_fmas_f32 v0, v0, v1, v152
	v_div_fixup_f32 v158, v0, v158, 1.0
	v_mul_f32_e32 v158, v158, v174
	v_div_scale_f32 v0, vcc, v159, v159, 1.0
	v_rcp_f32_e32 v1, v0
	s_nop 0
	v_fma_f32 v3, -v0, v1, 1.0
	v_fmac_f32_e32 v1, v3, v1
	v_div_scale_f32 v3, vcc, 1.0, v159, 1.0
	v_mul_f32_e32 v152, v3, v1
	v_fma_f32 v153, -v0, v152, v3
	v_fmac_f32_e32 v152, v153, v1
	v_fma_f32 v0, -v0, v152, v3
	v_div_fmas_f32 v0, v0, v1, v152
	v_div_fixup_f32 v159, v0, v159, 1.0
	v_mul_f32_e32 v159, v159, v175
	v_cvt_pk_bf16_f32 v176, v156, v157
	v_cvt_pk_bf16_f32 v177, v158, v159
	global_store_dwordx2 v197, v[176:177], s[56:57] sc0 sc1
	v_add_u32_e32 v197, 0x2000, v197
	s_waitcnt vmcnt(23)
	s_waitcnt lgkmcnt(2)
	v_add_f32_e32 v160, v160, v148
	v_add_f32_e32 v161, v161, v149
	v_add_f32_e32 v162, v162, v150
	v_add_f32_e32 v163, v163, v151
	v_mul_f32_e32 v160, 0xbfb8aa3b, v160
	v_mul_f32_e32 v161, 0xbfb8aa3b, v161
	v_mul_f32_e32 v162, 0xbfb8aa3b, v162
	v_mul_f32_e32 v163, 0xbfb8aa3b, v163
	v_exp_f32_e32 v160, v160
	v_exp_f32_e32 v161, v161
	v_exp_f32_e32 v162, v162
	v_exp_f32_e32 v163, v163
	v_lshlrev_b32_e32 v172, 16, v118
	v_and_b32_e32 v173, s28, v118
	v_lshlrev_b32_e32 v174, 16, v119
	v_and_b32_e32 v175, s28, v119
	v_add_f32_e32 v160, 1.0, v160
	v_add_f32_e32 v161, 1.0, v161
	v_add_f32_e32 v162, 1.0, v162
	v_add_f32_e32 v163, 1.0, v163
	v_div_scale_f32 v0, vcc, v160, v160, 1.0
	v_rcp_f32_e32 v1, v0
	s_nop 0
	v_fma_f32 v3, -v0, v1, 1.0
	v_fmac_f32_e32 v1, v3, v1
	v_div_scale_f32 v3, vcc, 1.0, v160, 1.0
	v_mul_f32_e32 v152, v3, v1
	v_fma_f32 v153, -v0, v152, v3
	v_fmac_f32_e32 v152, v153, v1
	v_fma_f32 v0, -v0, v152, v3
	v_div_fmas_f32 v0, v0, v1, v152
	v_div_fixup_f32 v160, v0, v160, 1.0
	v_mul_f32_e32 v160, v160, v172
	v_div_scale_f32 v0, vcc, v161, v161, 1.0
	v_rcp_f32_e32 v1, v0
	s_nop 0
	v_fma_f32 v3, -v0, v1, 1.0
	v_fmac_f32_e32 v1, v3, v1
	v_div_scale_f32 v3, vcc, 1.0, v161, 1.0
	v_mul_f32_e32 v152, v3, v1
	v_fma_f32 v153, -v0, v152, v3
	v_fmac_f32_e32 v152, v153, v1
	v_fma_f32 v0, -v0, v152, v3
	v_div_fmas_f32 v0, v0, v1, v152
	v_div_fixup_f32 v161, v0, v161, 1.0
	v_mul_f32_e32 v161, v161, v173
	v_div_scale_f32 v0, vcc, v162, v162, 1.0
	v_rcp_f32_e32 v1, v0
	s_nop 0
	v_fma_f32 v3, -v0, v1, 1.0
	v_fmac_f32_e32 v1, v3, v1
	v_div_scale_f32 v3, vcc, 1.0, v162, 1.0
	v_mul_f32_e32 v152, v3, v1
	v_fma_f32 v153, -v0, v152, v3
	v_fmac_f32_e32 v152, v153, v1
	v_fma_f32 v0, -v0, v152, v3
	v_div_fmas_f32 v0, v0, v1, v152
	v_div_fixup_f32 v162, v0, v162, 1.0
	v_mul_f32_e32 v162, v162, v174
	v_div_scale_f32 v0, vcc, v163, v163, 1.0
	v_rcp_f32_e32 v1, v0
	s_nop 0
	v_fma_f32 v3, -v0, v1, 1.0
	v_fmac_f32_e32 v1, v3, v1
	v_div_scale_f32 v3, vcc, 1.0, v163, 1.0
	v_mul_f32_e32 v152, v3, v1
	v_fma_f32 v153, -v0, v152, v3
	v_fmac_f32_e32 v152, v153, v1
	v_fma_f32 v0, -v0, v152, v3
	v_div_fmas_f32 v0, v0, v1, v152
	v_div_fixup_f32 v163, v0, v163, 1.0
	v_mul_f32_e32 v163, v163, v175
	v_cvt_pk_bf16_f32 v178, v160, v161
	v_cvt_pk_bf16_f32 v179, v162, v163
	global_store_dwordx2 v197, v[178:179], s[56:57] sc0 sc1
	v_add_u32_e32 v197, 0x2000, v197
	s_waitcnt vmcnt(23)
	s_waitcnt lgkmcnt(1)
	v_add_f32_e32 v164, v164, v148
	v_add_f32_e32 v165, v165, v149
	v_add_f32_e32 v166, v166, v150
	v_add_f32_e32 v167, v167, v151
	v_mul_f32_e32 v164, 0xbfb8aa3b, v164
	v_mul_f32_e32 v165, 0xbfb8aa3b, v165
	v_mul_f32_e32 v166, 0xbfb8aa3b, v166
	v_mul_f32_e32 v167, 0xbfb8aa3b, v167
	v_exp_f32_e32 v164, v164
	v_exp_f32_e32 v165, v165
	v_exp_f32_e32 v166, v166
	v_exp_f32_e32 v167, v167
	v_lshlrev_b32_e32 v172, 16, v120
	v_and_b32_e32 v173, s28, v120
	v_lshlrev_b32_e32 v174, 16, v121
	v_and_b32_e32 v175, s28, v121
	v_add_f32_e32 v164, 1.0, v164
	v_add_f32_e32 v165, 1.0, v165
	v_add_f32_e32 v166, 1.0, v166
	v_add_f32_e32 v167, 1.0, v167
	v_div_scale_f32 v0, vcc, v164, v164, 1.0
	v_rcp_f32_e32 v1, v0
	s_nop 0
	v_fma_f32 v3, -v0, v1, 1.0
	v_fmac_f32_e32 v1, v3, v1
	v_div_scale_f32 v3, vcc, 1.0, v164, 1.0
	v_mul_f32_e32 v152, v3, v1
	v_fma_f32 v153, -v0, v152, v3
	v_fmac_f32_e32 v152, v153, v1
	v_fma_f32 v0, -v0, v152, v3
	v_div_fmas_f32 v0, v0, v1, v152
	v_div_fixup_f32 v164, v0, v164, 1.0
	v_mul_f32_e32 v164, v164, v172
	v_div_scale_f32 v0, vcc, v165, v165, 1.0
	v_rcp_f32_e32 v1, v0
	s_nop 0
	v_fma_f32 v3, -v0, v1, 1.0
	v_fmac_f32_e32 v1, v3, v1
	v_div_scale_f32 v3, vcc, 1.0, v165, 1.0
	v_mul_f32_e32 v152, v3, v1
	v_fma_f32 v153, -v0, v152, v3
	v_fmac_f32_e32 v152, v153, v1
	v_fma_f32 v0, -v0, v152, v3
	v_div_fmas_f32 v0, v0, v1, v152
	v_div_fixup_f32 v165, v0, v165, 1.0
	v_mul_f32_e32 v165, v165, v173
	v_div_scale_f32 v0, vcc, v166, v166, 1.0
	v_rcp_f32_e32 v1, v0
	s_nop 0
	v_fma_f32 v3, -v0, v1, 1.0
	v_fmac_f32_e32 v1, v3, v1
	v_div_scale_f32 v3, vcc, 1.0, v166, 1.0
	v_mul_f32_e32 v152, v3, v1
	v_fma_f32 v153, -v0, v152, v3
	v_fmac_f32_e32 v152, v153, v1
	v_fma_f32 v0, -v0, v152, v3
	v_div_fmas_f32 v0, v0, v1, v152
	v_div_fixup_f32 v166, v0, v166, 1.0
	v_mul_f32_e32 v166, v166, v174
	v_div_scale_f32 v0, vcc, v167, v167, 1.0
	v_rcp_f32_e32 v1, v0
	s_nop 0
	v_fma_f32 v3, -v0, v1, 1.0
	v_fmac_f32_e32 v1, v3, v1
	v_div_scale_f32 v3, vcc, 1.0, v167, 1.0
	v_mul_f32_e32 v152, v3, v1
	v_fma_f32 v153, -v0, v152, v3
	v_fmac_f32_e32 v152, v153, v1
	v_fma_f32 v0, -v0, v152, v3
	v_div_fmas_f32 v0, v0, v1, v152
	v_div_fixup_f32 v167, v0, v167, 1.0
	v_mul_f32_e32 v167, v167, v175
	v_cvt_pk_bf16_f32 v176, v164, v165
	v_cvt_pk_bf16_f32 v177, v166, v167
	global_store_dwordx2 v197, v[176:177], s[56:57] sc0 sc1
	v_add_u32_e32 v197, 0x2000, v197
	s_waitcnt vmcnt(23)
	s_waitcnt lgkmcnt(0)
	v_add_f32_e32 v168, v168, v148
	v_add_f32_e32 v169, v169, v149
	v_add_f32_e32 v170, v170, v150
	v_add_f32_e32 v171, v171, v151
	v_mul_f32_e32 v168, 0xbfb8aa3b, v168
	v_mul_f32_e32 v169, 0xbfb8aa3b, v169
	v_mul_f32_e32 v170, 0xbfb8aa3b, v170
	v_mul_f32_e32 v171, 0xbfb8aa3b, v171
	v_exp_f32_e32 v168, v168
	v_exp_f32_e32 v169, v169
	v_exp_f32_e32 v170, v170
	v_exp_f32_e32 v171, v171
	v_lshlrev_b32_e32 v172, 16, v122
	v_and_b32_e32 v173, s28, v122
	v_lshlrev_b32_e32 v174, 16, v123
	v_and_b32_e32 v175, s28, v123
	v_add_f32_e32 v168, 1.0, v168
	v_add_f32_e32 v169, 1.0, v169
	v_add_f32_e32 v170, 1.0, v170
	v_add_f32_e32 v171, 1.0, v171
	v_div_scale_f32 v0, vcc, v168, v168, 1.0
	v_rcp_f32_e32 v1, v0
	s_nop 0
	v_fma_f32 v3, -v0, v1, 1.0
	v_fmac_f32_e32 v1, v3, v1
	v_div_scale_f32 v3, vcc, 1.0, v168, 1.0
	v_mul_f32_e32 v152, v3, v1
	v_fma_f32 v153, -v0, v152, v3
	v_fmac_f32_e32 v152, v153, v1
	v_fma_f32 v0, -v0, v152, v3
	v_div_fmas_f32 v0, v0, v1, v152
	v_div_fixup_f32 v168, v0, v168, 1.0
	v_mul_f32_e32 v168, v168, v172
	v_div_scale_f32 v0, vcc, v169, v169, 1.0
	v_rcp_f32_e32 v1, v0
	s_nop 0
	v_fma_f32 v3, -v0, v1, 1.0
	v_fmac_f32_e32 v1, v3, v1
	v_div_scale_f32 v3, vcc, 1.0, v169, 1.0
	v_mul_f32_e32 v152, v3, v1
	v_fma_f32 v153, -v0, v152, v3
	v_fmac_f32_e32 v152, v153, v1
	v_fma_f32 v0, -v0, v152, v3
	v_div_fmas_f32 v0, v0, v1, v152
	v_div_fixup_f32 v169, v0, v169, 1.0
	v_mul_f32_e32 v169, v169, v173
	v_div_scale_f32 v0, vcc, v170, v170, 1.0
	v_rcp_f32_e32 v1, v0
	s_nop 0
	v_fma_f32 v3, -v0, v1, 1.0
	v_fmac_f32_e32 v1, v3, v1
	v_div_scale_f32 v3, vcc, 1.0, v170, 1.0
	v_mul_f32_e32 v152, v3, v1
	v_fma_f32 v153, -v0, v152, v3
	v_fmac_f32_e32 v152, v153, v1
	v_fma_f32 v0, -v0, v152, v3
	v_div_fmas_f32 v0, v0, v1, v152
	v_div_fixup_f32 v170, v0, v170, 1.0
	v_mul_f32_e32 v170, v170, v174
	v_div_scale_f32 v0, vcc, v171, v171, 1.0
	v_rcp_f32_e32 v1, v0
	s_nop 0
	v_fma_f32 v3, -v0, v1, 1.0
	v_fmac_f32_e32 v1, v3, v1
	v_div_scale_f32 v3, vcc, 1.0, v171, 1.0
	v_mul_f32_e32 v152, v3, v1
	v_fma_f32 v153, -v0, v152, v3
	v_fmac_f32_e32 v152, v153, v1
	v_fma_f32 v0, -v0, v152, v3
	v_div_fmas_f32 v0, v0, v1, v152
	v_div_fixup_f32 v171, v0, v171, 1.0
	v_mul_f32_e32 v171, v171, v175
	v_cvt_pk_bf16_f32 v178, v168, v169
	v_cvt_pk_bf16_f32 v179, v170, v171
	global_store_dwordx2 v197, v[178:179], s[56:57] sc0 sc1
	v_add_u32_e32 v197, 0x2000, v197
	ds_write_b32 v203, v52 offset:0
	ds_write_b32 v203, v53 offset:272
	ds_write_b32 v203, v54 offset:544
	ds_write_b32 v203, v55 offset:816
	ds_write_b32 v203, v56 offset:64
	ds_write_b32 v203, v57 offset:336
	ds_write_b32 v203, v58 offset:608
	ds_write_b32 v203, v59 offset:880
	ds_write_b32 v203, v60 offset:128
	ds_write_b32 v203, v61 offset:400
	ds_write_b32 v203, v62 offset:672
	ds_write_b32 v203, v63 offset:944
	ds_write_b32 v203, v64 offset:192
	ds_write_b32 v203, v65 offset:464
	ds_write_b32 v203, v66 offset:736
	ds_write_b32 v203, v67 offset:1008
	s_waitcnt lgkmcnt(0)
	ds_read_b128 v[156:159], v204 offset:0
	ds_read_b128 v[160:163], v204 offset:1088
	ds_read_b128 v[164:167], v204 offset:2176
	ds_read_b128 v[168:171], v204 offset:3264
	s_waitcnt vmcnt(23)
	s_waitcnt lgkmcnt(3)
	v_add_f32_e32 v156, v156, v148
	v_add_f32_e32 v157, v157, v149
	v_add_f32_e32 v158, v158, v150
	v_add_f32_e32 v159, v159, v151
	v_mul_f32_e32 v156, 0xbfb8aa3b, v156
	v_mul_f32_e32 v157, 0xbfb8aa3b, v157
	v_mul_f32_e32 v158, 0xbfb8aa3b, v158
	v_mul_f32_e32 v159, 0xbfb8aa3b, v159
	v_exp_f32_e32 v156, v156
	v_exp_f32_e32 v157, v157
	v_exp_f32_e32 v158, v158
	v_exp_f32_e32 v159, v159
	v_lshlrev_b32_e32 v172, 16, v124
	v_and_b32_e32 v173, s28, v124
	v_lshlrev_b32_e32 v174, 16, v125
	v_and_b32_e32 v175, s28, v125
	v_add_f32_e32 v156, 1.0, v156
	v_add_f32_e32 v157, 1.0, v157
	v_add_f32_e32 v158, 1.0, v158
	v_add_f32_e32 v159, 1.0, v159
	v_div_scale_f32 v0, vcc, v156, v156, 1.0
	v_rcp_f32_e32 v1, v0
	s_nop 0
	v_fma_f32 v3, -v0, v1, 1.0
	v_fmac_f32_e32 v1, v3, v1
	v_div_scale_f32 v3, vcc, 1.0, v156, 1.0
	v_mul_f32_e32 v152, v3, v1
	v_fma_f32 v153, -v0, v152, v3
	v_fmac_f32_e32 v152, v153, v1
	v_fma_f32 v0, -v0, v152, v3
	v_div_fmas_f32 v0, v0, v1, v152
	v_div_fixup_f32 v156, v0, v156, 1.0
	v_mul_f32_e32 v156, v156, v172
	v_div_scale_f32 v0, vcc, v157, v157, 1.0
	v_rcp_f32_e32 v1, v0
	s_nop 0
	v_fma_f32 v3, -v0, v1, 1.0
	v_fmac_f32_e32 v1, v3, v1
	v_div_scale_f32 v3, vcc, 1.0, v157, 1.0
	v_mul_f32_e32 v152, v3, v1
	v_fma_f32 v153, -v0, v152, v3
	v_fmac_f32_e32 v152, v153, v1
	v_fma_f32 v0, -v0, v152, v3
	v_div_fmas_f32 v0, v0, v1, v152
	v_div_fixup_f32 v157, v0, v157, 1.0
	v_mul_f32_e32 v157, v157, v173
	v_div_scale_f32 v0, vcc, v158, v158, 1.0
	v_rcp_f32_e32 v1, v0
	s_nop 0
	v_fma_f32 v3, -v0, v1, 1.0
	v_fmac_f32_e32 v1, v3, v1
	v_div_scale_f32 v3, vcc, 1.0, v158, 1.0
	v_mul_f32_e32 v152, v3, v1
	v_fma_f32 v153, -v0, v152, v3
	v_fmac_f32_e32 v152, v153, v1
	v_fma_f32 v0, -v0, v152, v3
	v_div_fmas_f32 v0, v0, v1, v152
	v_div_fixup_f32 v158, v0, v158, 1.0
	v_mul_f32_e32 v158, v158, v174
	v_div_scale_f32 v0, vcc, v159, v159, 1.0
	v_rcp_f32_e32 v1, v0
	s_nop 0
	v_fma_f32 v3, -v0, v1, 1.0
	v_fmac_f32_e32 v1, v3, v1
	v_div_scale_f32 v3, vcc, 1.0, v159, 1.0
	v_mul_f32_e32 v152, v3, v1
	v_fma_f32 v153, -v0, v152, v3
	v_fmac_f32_e32 v152, v153, v1
	v_fma_f32 v0, -v0, v152, v3
	v_div_fmas_f32 v0, v0, v1, v152
	v_div_fixup_f32 v159, v0, v159, 1.0
	v_mul_f32_e32 v159, v159, v175
	v_cvt_pk_bf16_f32 v176, v156, v157
	v_cvt_pk_bf16_f32 v177, v158, v159
	global_store_dwordx2 v197, v[176:177], s[56:57] sc0 sc1
	v_add_u32_e32 v197, 0x2000, v197
	s_waitcnt vmcnt(23)
	s_waitcnt lgkmcnt(2)
	v_add_f32_e32 v160, v160, v148
	v_add_f32_e32 v161, v161, v149
	v_add_f32_e32 v162, v162, v150
	v_add_f32_e32 v163, v163, v151
	v_mul_f32_e32 v160, 0xbfb8aa3b, v160
	v_mul_f32_e32 v161, 0xbfb8aa3b, v161
	v_mul_f32_e32 v162, 0xbfb8aa3b, v162
	v_mul_f32_e32 v163, 0xbfb8aa3b, v163
	v_exp_f32_e32 v160, v160
	v_exp_f32_e32 v161, v161
	v_exp_f32_e32 v162, v162
	v_exp_f32_e32 v163, v163
	v_lshlrev_b32_e32 v172, 16, v126
	v_and_b32_e32 v173, s28, v126
	v_lshlrev_b32_e32 v174, 16, v127
	v_and_b32_e32 v175, s28, v127
	v_add_f32_e32 v160, 1.0, v160
	v_add_f32_e32 v161, 1.0, v161
	v_add_f32_e32 v162, 1.0, v162
	v_add_f32_e32 v163, 1.0, v163
	v_div_scale_f32 v0, vcc, v160, v160, 1.0
	v_rcp_f32_e32 v1, v0
	s_nop 0
	v_fma_f32 v3, -v0, v1, 1.0
	v_fmac_f32_e32 v1, v3, v1
	v_div_scale_f32 v3, vcc, 1.0, v160, 1.0
	v_mul_f32_e32 v152, v3, v1
	v_fma_f32 v153, -v0, v152, v3
	v_fmac_f32_e32 v152, v153, v1
	v_fma_f32 v0, -v0, v152, v3
	v_div_fmas_f32 v0, v0, v1, v152
	v_div_fixup_f32 v160, v0, v160, 1.0
	v_mul_f32_e32 v160, v160, v172
	v_div_scale_f32 v0, vcc, v161, v161, 1.0
	v_rcp_f32_e32 v1, v0
	s_nop 0
	v_fma_f32 v3, -v0, v1, 1.0
	v_fmac_f32_e32 v1, v3, v1
	v_div_scale_f32 v3, vcc, 1.0, v161, 1.0
	v_mul_f32_e32 v152, v3, v1
	v_fma_f32 v153, -v0, v152, v3
	v_fmac_f32_e32 v152, v153, v1
	v_fma_f32 v0, -v0, v152, v3
	v_div_fmas_f32 v0, v0, v1, v152
	v_div_fixup_f32 v161, v0, v161, 1.0
	v_mul_f32_e32 v161, v161, v173
	v_div_scale_f32 v0, vcc, v162, v162, 1.0
	v_rcp_f32_e32 v1, v0
	s_nop 0
	v_fma_f32 v3, -v0, v1, 1.0
	v_fmac_f32_e32 v1, v3, v1
	v_div_scale_f32 v3, vcc, 1.0, v162, 1.0
	v_mul_f32_e32 v152, v3, v1
	v_fma_f32 v153, -v0, v152, v3
	v_fmac_f32_e32 v152, v153, v1
	v_fma_f32 v0, -v0, v152, v3
	v_div_fmas_f32 v0, v0, v1, v152
	v_div_fixup_f32 v162, v0, v162, 1.0
	v_mul_f32_e32 v162, v162, v174
	v_div_scale_f32 v0, vcc, v163, v163, 1.0
	v_rcp_f32_e32 v1, v0
	s_nop 0
	v_fma_f32 v3, -v0, v1, 1.0
	v_fmac_f32_e32 v1, v3, v1
	v_div_scale_f32 v3, vcc, 1.0, v163, 1.0
	v_mul_f32_e32 v152, v3, v1
	v_fma_f32 v153, -v0, v152, v3
	v_fmac_f32_e32 v152, v153, v1
	v_fma_f32 v0, -v0, v152, v3
	v_div_fmas_f32 v0, v0, v1, v152
	v_div_fixup_f32 v163, v0, v163, 1.0
	v_mul_f32_e32 v163, v163, v175
	v_cvt_pk_bf16_f32 v178, v160, v161
	v_cvt_pk_bf16_f32 v179, v162, v163
	global_store_dwordx2 v197, v[178:179], s[56:57] sc0 sc1
	v_add_u32_e32 v197, 0x2000, v197
	s_waitcnt vmcnt(23)
	s_waitcnt lgkmcnt(1)
	v_add_f32_e32 v164, v164, v148
	v_add_f32_e32 v165, v165, v149
	v_add_f32_e32 v166, v166, v150
	v_add_f32_e32 v167, v167, v151
	v_mul_f32_e32 v164, 0xbfb8aa3b, v164
	v_mul_f32_e32 v165, 0xbfb8aa3b, v165
	v_mul_f32_e32 v166, 0xbfb8aa3b, v166
	v_mul_f32_e32 v167, 0xbfb8aa3b, v167
	v_exp_f32_e32 v164, v164
	v_exp_f32_e32 v165, v165
	v_exp_f32_e32 v166, v166
	v_exp_f32_e32 v167, v167
	v_lshlrev_b32_e32 v172, 16, v128
	v_and_b32_e32 v173, s28, v128
	v_lshlrev_b32_e32 v174, 16, v129
	v_and_b32_e32 v175, s28, v129
	v_add_f32_e32 v164, 1.0, v164
	v_add_f32_e32 v165, 1.0, v165
	v_add_f32_e32 v166, 1.0, v166
	v_add_f32_e32 v167, 1.0, v167
	v_div_scale_f32 v0, vcc, v164, v164, 1.0
	v_rcp_f32_e32 v1, v0
	s_nop 0
	v_fma_f32 v3, -v0, v1, 1.0
	v_fmac_f32_e32 v1, v3, v1
	v_div_scale_f32 v3, vcc, 1.0, v164, 1.0
	v_mul_f32_e32 v152, v3, v1
	v_fma_f32 v153, -v0, v152, v3
	v_fmac_f32_e32 v152, v153, v1
	v_fma_f32 v0, -v0, v152, v3
	v_div_fmas_f32 v0, v0, v1, v152
	v_div_fixup_f32 v164, v0, v164, 1.0
	v_mul_f32_e32 v164, v164, v172
	v_div_scale_f32 v0, vcc, v165, v165, 1.0
	v_rcp_f32_e32 v1, v0
	s_nop 0
	v_fma_f32 v3, -v0, v1, 1.0
	v_fmac_f32_e32 v1, v3, v1
	v_div_scale_f32 v3, vcc, 1.0, v165, 1.0
	v_mul_f32_e32 v152, v3, v1
	v_fma_f32 v153, -v0, v152, v3
	v_fmac_f32_e32 v152, v153, v1
	v_fma_f32 v0, -v0, v152, v3
	v_div_fmas_f32 v0, v0, v1, v152
	v_div_fixup_f32 v165, v0, v165, 1.0
	v_mul_f32_e32 v165, v165, v173
	v_div_scale_f32 v0, vcc, v166, v166, 1.0
	v_rcp_f32_e32 v1, v0
	s_nop 0
	v_fma_f32 v3, -v0, v1, 1.0
	v_fmac_f32_e32 v1, v3, v1
	v_div_scale_f32 v3, vcc, 1.0, v166, 1.0
	v_mul_f32_e32 v152, v3, v1
	v_fma_f32 v153, -v0, v152, v3
	v_fmac_f32_e32 v152, v153, v1
	v_fma_f32 v0, -v0, v152, v3
	v_div_fmas_f32 v0, v0, v1, v152
	v_div_fixup_f32 v166, v0, v166, 1.0
	v_mul_f32_e32 v166, v166, v174
	v_div_scale_f32 v0, vcc, v167, v167, 1.0
	v_rcp_f32_e32 v1, v0
	s_nop 0
	v_fma_f32 v3, -v0, v1, 1.0
	v_fmac_f32_e32 v1, v3, v1
	v_div_scale_f32 v3, vcc, 1.0, v167, 1.0
	v_mul_f32_e32 v152, v3, v1
	v_fma_f32 v153, -v0, v152, v3
	v_fmac_f32_e32 v152, v153, v1
	v_fma_f32 v0, -v0, v152, v3
	v_div_fmas_f32 v0, v0, v1, v152
	v_div_fixup_f32 v167, v0, v167, 1.0
	v_mul_f32_e32 v167, v167, v175
	v_cvt_pk_bf16_f32 v176, v164, v165
	v_cvt_pk_bf16_f32 v177, v166, v167
	global_store_dwordx2 v197, v[176:177], s[56:57] sc0 sc1
	v_add_u32_e32 v197, 0x2000, v197
	s_waitcnt vmcnt(23)
	s_waitcnt lgkmcnt(0)
	v_add_f32_e32 v168, v168, v148
	v_add_f32_e32 v169, v169, v149
	v_add_f32_e32 v170, v170, v150
	v_add_f32_e32 v171, v171, v151
	v_mul_f32_e32 v168, 0xbfb8aa3b, v168
	v_mul_f32_e32 v169, 0xbfb8aa3b, v169
	v_mul_f32_e32 v170, 0xbfb8aa3b, v170
	v_mul_f32_e32 v171, 0xbfb8aa3b, v171
	v_exp_f32_e32 v168, v168
	v_exp_f32_e32 v169, v169
	v_exp_f32_e32 v170, v170
	v_exp_f32_e32 v171, v171
	v_lshlrev_b32_e32 v172, 16, v130
	v_and_b32_e32 v173, s28, v130
	v_lshlrev_b32_e32 v174, 16, v131
	v_and_b32_e32 v175, s28, v131
	v_add_f32_e32 v168, 1.0, v168
	v_add_f32_e32 v169, 1.0, v169
	v_add_f32_e32 v170, 1.0, v170
	v_add_f32_e32 v171, 1.0, v171
	v_div_scale_f32 v0, vcc, v168, v168, 1.0
	v_rcp_f32_e32 v1, v0
	s_nop 0
	v_fma_f32 v3, -v0, v1, 1.0
	v_fmac_f32_e32 v1, v3, v1
	v_div_scale_f32 v3, vcc, 1.0, v168, 1.0
	v_mul_f32_e32 v152, v3, v1
	v_fma_f32 v153, -v0, v152, v3
	v_fmac_f32_e32 v152, v153, v1
	v_fma_f32 v0, -v0, v152, v3
	v_div_fmas_f32 v0, v0, v1, v152
	v_div_fixup_f32 v168, v0, v168, 1.0
	v_mul_f32_e32 v168, v168, v172
	v_div_scale_f32 v0, vcc, v169, v169, 1.0
	v_rcp_f32_e32 v1, v0
	s_nop 0
	v_fma_f32 v3, -v0, v1, 1.0
	v_fmac_f32_e32 v1, v3, v1
	v_div_scale_f32 v3, vcc, 1.0, v169, 1.0
	v_mul_f32_e32 v152, v3, v1
	v_fma_f32 v153, -v0, v152, v3
	v_fmac_f32_e32 v152, v153, v1
	v_fma_f32 v0, -v0, v152, v3
	v_div_fmas_f32 v0, v0, v1, v152
	v_div_fixup_f32 v169, v0, v169, 1.0
	v_mul_f32_e32 v169, v169, v173
	v_div_scale_f32 v0, vcc, v170, v170, 1.0
	v_rcp_f32_e32 v1, v0
	s_nop 0
	v_fma_f32 v3, -v0, v1, 1.0
	v_fmac_f32_e32 v1, v3, v1
	v_div_scale_f32 v3, vcc, 1.0, v170, 1.0
	v_mul_f32_e32 v152, v3, v1
	v_fma_f32 v153, -v0, v152, v3
	v_fmac_f32_e32 v152, v153, v1
	v_fma_f32 v0, -v0, v152, v3
	v_div_fmas_f32 v0, v0, v1, v152
	v_div_fixup_f32 v170, v0, v170, 1.0
	v_mul_f32_e32 v170, v170, v174
	v_div_scale_f32 v0, vcc, v171, v171, 1.0
	v_rcp_f32_e32 v1, v0
	s_nop 0
	v_fma_f32 v3, -v0, v1, 1.0
	v_fmac_f32_e32 v1, v3, v1
	v_div_scale_f32 v3, vcc, 1.0, v171, 1.0
	v_mul_f32_e32 v152, v3, v1
	v_fma_f32 v153, -v0, v152, v3
	v_fmac_f32_e32 v152, v153, v1
	v_fma_f32 v0, -v0, v152, v3
	v_div_fmas_f32 v0, v0, v1, v152
	v_div_fixup_f32 v171, v0, v171, 1.0
	v_mul_f32_e32 v171, v171, v175
	v_cvt_pk_bf16_f32 v178, v168, v169
	v_cvt_pk_bf16_f32 v179, v170, v171
	global_store_dwordx2 v197, v[178:179], s[56:57] sc0 sc1
	v_add_u32_e32 v197, 0x2000, v197
	ds_write_b32 v203, v68 offset:0
	ds_write_b32 v203, v69 offset:272
	ds_write_b32 v203, v70 offset:544
	ds_write_b32 v203, v71 offset:816
	ds_write_b32 v203, v72 offset:64
	ds_write_b32 v203, v73 offset:336
	ds_write_b32 v203, v74 offset:608
	ds_write_b32 v203, v75 offset:880
	ds_write_b32 v203, v76 offset:128
	ds_write_b32 v203, v77 offset:400
	ds_write_b32 v203, v78 offset:672
	ds_write_b32 v203, v79 offset:944
	ds_write_b32 v203, v80 offset:192
	ds_write_b32 v203, v81 offset:464
	ds_write_b32 v203, v82 offset:736
	ds_write_b32 v203, v83 offset:1008
	s_waitcnt lgkmcnt(0)
	ds_read_b128 v[156:159], v204 offset:0
	ds_read_b128 v[160:163], v204 offset:1088
	ds_read_b128 v[164:167], v204 offset:2176
	ds_read_b128 v[168:171], v204 offset:3264
	s_waitcnt vmcnt(23)
	s_waitcnt lgkmcnt(3)
	v_add_f32_e32 v156, v156, v148
	v_add_f32_e32 v157, v157, v149
	v_add_f32_e32 v158, v158, v150
	v_add_f32_e32 v159, v159, v151
	v_mul_f32_e32 v156, 0xbfb8aa3b, v156
	v_mul_f32_e32 v157, 0xbfb8aa3b, v157
	v_mul_f32_e32 v158, 0xbfb8aa3b, v158
	v_mul_f32_e32 v159, 0xbfb8aa3b, v159
	v_exp_f32_e32 v156, v156
	v_exp_f32_e32 v157, v157
	v_exp_f32_e32 v158, v158
	v_exp_f32_e32 v159, v159
	v_lshlrev_b32_e32 v172, 16, v132
	v_and_b32_e32 v173, s28, v132
	v_lshlrev_b32_e32 v174, 16, v133
	v_and_b32_e32 v175, s28, v133
	v_add_f32_e32 v156, 1.0, v156
	v_add_f32_e32 v157, 1.0, v157
	v_add_f32_e32 v158, 1.0, v158
	v_add_f32_e32 v159, 1.0, v159
	v_div_scale_f32 v0, vcc, v156, v156, 1.0
	v_rcp_f32_e32 v1, v0
	s_nop 0
	v_fma_f32 v3, -v0, v1, 1.0
	v_fmac_f32_e32 v1, v3, v1
	v_div_scale_f32 v3, vcc, 1.0, v156, 1.0
	v_mul_f32_e32 v152, v3, v1
	v_fma_f32 v153, -v0, v152, v3
	v_fmac_f32_e32 v152, v153, v1
	v_fma_f32 v0, -v0, v152, v3
	v_div_fmas_f32 v0, v0, v1, v152
	v_div_fixup_f32 v156, v0, v156, 1.0
	v_mul_f32_e32 v156, v156, v172
	v_div_scale_f32 v0, vcc, v157, v157, 1.0
	v_rcp_f32_e32 v1, v0
	s_nop 0
	v_fma_f32 v3, -v0, v1, 1.0
	v_fmac_f32_e32 v1, v3, v1
	v_div_scale_f32 v3, vcc, 1.0, v157, 1.0
	v_mul_f32_e32 v152, v3, v1
	v_fma_f32 v153, -v0, v152, v3
	v_fmac_f32_e32 v152, v153, v1
	v_fma_f32 v0, -v0, v152, v3
	v_div_fmas_f32 v0, v0, v1, v152
	v_div_fixup_f32 v157, v0, v157, 1.0
	v_mul_f32_e32 v157, v157, v173
	v_div_scale_f32 v0, vcc, v158, v158, 1.0
	v_rcp_f32_e32 v1, v0
	s_nop 0
	v_fma_f32 v3, -v0, v1, 1.0
	v_fmac_f32_e32 v1, v3, v1
	v_div_scale_f32 v3, vcc, 1.0, v158, 1.0
	v_mul_f32_e32 v152, v3, v1
	v_fma_f32 v153, -v0, v152, v3
	v_fmac_f32_e32 v152, v153, v1
	v_fma_f32 v0, -v0, v152, v3
	v_div_fmas_f32 v0, v0, v1, v152
	v_div_fixup_f32 v158, v0, v158, 1.0
	v_mul_f32_e32 v158, v158, v174
	v_div_scale_f32 v0, vcc, v159, v159, 1.0
	v_rcp_f32_e32 v1, v0
	s_nop 0
	v_fma_f32 v3, -v0, v1, 1.0
	v_fmac_f32_e32 v1, v3, v1
	v_div_scale_f32 v3, vcc, 1.0, v159, 1.0
	v_mul_f32_e32 v152, v3, v1
	v_fma_f32 v153, -v0, v152, v3
	v_fmac_f32_e32 v152, v153, v1
	v_fma_f32 v0, -v0, v152, v3
	v_div_fmas_f32 v0, v0, v1, v152
	v_div_fixup_f32 v159, v0, v159, 1.0
	v_mul_f32_e32 v159, v159, v175
	v_cvt_pk_bf16_f32 v176, v156, v157
	v_cvt_pk_bf16_f32 v177, v158, v159
	global_store_dwordx2 v197, v[176:177], s[56:57] sc0 sc1
	v_add_u32_e32 v197, 0x2000, v197
	s_waitcnt vmcnt(23)
	s_waitcnt lgkmcnt(2)
	v_add_f32_e32 v160, v160, v148
	v_add_f32_e32 v161, v161, v149
	v_add_f32_e32 v162, v162, v150
	v_add_f32_e32 v163, v163, v151
	v_mul_f32_e32 v160, 0xbfb8aa3b, v160
	v_mul_f32_e32 v161, 0xbfb8aa3b, v161
	v_mul_f32_e32 v162, 0xbfb8aa3b, v162
	v_mul_f32_e32 v163, 0xbfb8aa3b, v163
	v_exp_f32_e32 v160, v160
	v_exp_f32_e32 v161, v161
	v_exp_f32_e32 v162, v162
	v_exp_f32_e32 v163, v163
	v_lshlrev_b32_e32 v172, 16, v134
	v_and_b32_e32 v173, s28, v134
	v_lshlrev_b32_e32 v174, 16, v135
	v_and_b32_e32 v175, s28, v135
	v_add_f32_e32 v160, 1.0, v160
	v_add_f32_e32 v161, 1.0, v161
	v_add_f32_e32 v162, 1.0, v162
	v_add_f32_e32 v163, 1.0, v163
	v_div_scale_f32 v0, vcc, v160, v160, 1.0
	v_rcp_f32_e32 v1, v0
	s_nop 0
	v_fma_f32 v3, -v0, v1, 1.0
	v_fmac_f32_e32 v1, v3, v1
	v_div_scale_f32 v3, vcc, 1.0, v160, 1.0
	v_mul_f32_e32 v152, v3, v1
	v_fma_f32 v153, -v0, v152, v3
	v_fmac_f32_e32 v152, v153, v1
	v_fma_f32 v0, -v0, v152, v3
	v_div_fmas_f32 v0, v0, v1, v152
	v_div_fixup_f32 v160, v0, v160, 1.0
	v_mul_f32_e32 v160, v160, v172
	v_div_scale_f32 v0, vcc, v161, v161, 1.0
	v_rcp_f32_e32 v1, v0
	s_nop 0
	v_fma_f32 v3, -v0, v1, 1.0
	v_fmac_f32_e32 v1, v3, v1
	v_div_scale_f32 v3, vcc, 1.0, v161, 1.0
	v_mul_f32_e32 v152, v3, v1
	v_fma_f32 v153, -v0, v152, v3
	v_fmac_f32_e32 v152, v153, v1
	v_fma_f32 v0, -v0, v152, v3
	v_div_fmas_f32 v0, v0, v1, v152
	v_div_fixup_f32 v161, v0, v161, 1.0
	v_mul_f32_e32 v161, v161, v173
	v_div_scale_f32 v0, vcc, v162, v162, 1.0
	v_rcp_f32_e32 v1, v0
	s_nop 0
	v_fma_f32 v3, -v0, v1, 1.0
	v_fmac_f32_e32 v1, v3, v1
	v_div_scale_f32 v3, vcc, 1.0, v162, 1.0
	v_mul_f32_e32 v152, v3, v1
	v_fma_f32 v153, -v0, v152, v3
	v_fmac_f32_e32 v152, v153, v1
	v_fma_f32 v0, -v0, v152, v3
	v_div_fmas_f32 v0, v0, v1, v152
	v_div_fixup_f32 v162, v0, v162, 1.0
	v_mul_f32_e32 v162, v162, v174
	v_div_scale_f32 v0, vcc, v163, v163, 1.0
	v_rcp_f32_e32 v1, v0
	s_nop 0
	v_fma_f32 v3, -v0, v1, 1.0
	v_fmac_f32_e32 v1, v3, v1
	v_div_scale_f32 v3, vcc, 1.0, v163, 1.0
	v_mul_f32_e32 v152, v3, v1
	v_fma_f32 v153, -v0, v152, v3
	v_fmac_f32_e32 v152, v153, v1
	v_fma_f32 v0, -v0, v152, v3
	v_div_fmas_f32 v0, v0, v1, v152
	v_div_fixup_f32 v163, v0, v163, 1.0
	v_mul_f32_e32 v163, v163, v175
	v_cvt_pk_bf16_f32 v178, v160, v161
	v_cvt_pk_bf16_f32 v179, v162, v163
	global_store_dwordx2 v197, v[178:179], s[56:57] sc0 sc1
	v_add_u32_e32 v197, 0x2000, v197
	s_waitcnt vmcnt(23)
	s_waitcnt lgkmcnt(1)
	v_add_f32_e32 v164, v164, v148
	v_add_f32_e32 v165, v165, v149
	v_add_f32_e32 v166, v166, v150
	v_add_f32_e32 v167, v167, v151
	v_mul_f32_e32 v164, 0xbfb8aa3b, v164
	v_mul_f32_e32 v165, 0xbfb8aa3b, v165
	v_mul_f32_e32 v166, 0xbfb8aa3b, v166
	v_mul_f32_e32 v167, 0xbfb8aa3b, v167
	v_exp_f32_e32 v164, v164
	v_exp_f32_e32 v165, v165
	v_exp_f32_e32 v166, v166
	v_exp_f32_e32 v167, v167
	v_lshlrev_b32_e32 v172, 16, v136
	v_and_b32_e32 v173, s28, v136
	v_lshlrev_b32_e32 v174, 16, v137
	v_and_b32_e32 v175, s28, v137
	v_add_f32_e32 v164, 1.0, v164
	v_add_f32_e32 v165, 1.0, v165
	v_add_f32_e32 v166, 1.0, v166
	v_add_f32_e32 v167, 1.0, v167
	v_div_scale_f32 v0, vcc, v164, v164, 1.0
	v_rcp_f32_e32 v1, v0
	s_nop 0
	v_fma_f32 v3, -v0, v1, 1.0
	v_fmac_f32_e32 v1, v3, v1
	v_div_scale_f32 v3, vcc, 1.0, v164, 1.0
	v_mul_f32_e32 v152, v3, v1
	v_fma_f32 v153, -v0, v152, v3
	v_fmac_f32_e32 v152, v153, v1
	v_fma_f32 v0, -v0, v152, v3
	v_div_fmas_f32 v0, v0, v1, v152
	v_div_fixup_f32 v164, v0, v164, 1.0
	v_mul_f32_e32 v164, v164, v172
	v_div_scale_f32 v0, vcc, v165, v165, 1.0
	v_rcp_f32_e32 v1, v0
	s_nop 0
	v_fma_f32 v3, -v0, v1, 1.0
	v_fmac_f32_e32 v1, v3, v1
	v_div_scale_f32 v3, vcc, 1.0, v165, 1.0
	v_mul_f32_e32 v152, v3, v1
	v_fma_f32 v153, -v0, v152, v3
	v_fmac_f32_e32 v152, v153, v1
	v_fma_f32 v0, -v0, v152, v3
	v_div_fmas_f32 v0, v0, v1, v152
	v_div_fixup_f32 v165, v0, v165, 1.0
	v_mul_f32_e32 v165, v165, v173
	v_div_scale_f32 v0, vcc, v166, v166, 1.0
	v_rcp_f32_e32 v1, v0
	s_nop 0
	v_fma_f32 v3, -v0, v1, 1.0
	v_fmac_f32_e32 v1, v3, v1
	v_div_scale_f32 v3, vcc, 1.0, v166, 1.0
	v_mul_f32_e32 v152, v3, v1
	v_fma_f32 v153, -v0, v152, v3
	v_fmac_f32_e32 v152, v153, v1
	v_fma_f32 v0, -v0, v152, v3
	v_div_fmas_f32 v0, v0, v1, v152
	v_div_fixup_f32 v166, v0, v166, 1.0
	v_mul_f32_e32 v166, v166, v174
	v_div_scale_f32 v0, vcc, v167, v167, 1.0
	v_rcp_f32_e32 v1, v0
	s_nop 0
	v_fma_f32 v3, -v0, v1, 1.0
	v_fmac_f32_e32 v1, v3, v1
	v_div_scale_f32 v3, vcc, 1.0, v167, 1.0
	v_mul_f32_e32 v152, v3, v1
	v_fma_f32 v153, -v0, v152, v3
	v_fmac_f32_e32 v152, v153, v1
	v_fma_f32 v0, -v0, v152, v3
	v_div_fmas_f32 v0, v0, v1, v152
	v_div_fixup_f32 v167, v0, v167, 1.0
	v_mul_f32_e32 v167, v167, v175
	v_cvt_pk_bf16_f32 v176, v164, v165
	v_cvt_pk_bf16_f32 v177, v166, v167
	global_store_dwordx2 v197, v[176:177], s[56:57] sc0 sc1
	v_add_u32_e32 v197, 0x2000, v197
	s_waitcnt vmcnt(23)
	s_waitcnt lgkmcnt(0)
	v_add_f32_e32 v168, v168, v148
	v_add_f32_e32 v169, v169, v149
	v_add_f32_e32 v170, v170, v150
	v_add_f32_e32 v171, v171, v151
	v_mul_f32_e32 v168, 0xbfb8aa3b, v168
	v_mul_f32_e32 v169, 0xbfb8aa3b, v169
	v_mul_f32_e32 v170, 0xbfb8aa3b, v170
	v_mul_f32_e32 v171, 0xbfb8aa3b, v171
	v_exp_f32_e32 v168, v168
	v_exp_f32_e32 v169, v169
	v_exp_f32_e32 v170, v170
	v_exp_f32_e32 v171, v171
	v_lshlrev_b32_e32 v172, 16, v138
	v_and_b32_e32 v173, s28, v138
	v_lshlrev_b32_e32 v174, 16, v139
	v_and_b32_e32 v175, s28, v139
	v_add_f32_e32 v168, 1.0, v168
	v_add_f32_e32 v169, 1.0, v169
	v_add_f32_e32 v170, 1.0, v170
	v_add_f32_e32 v171, 1.0, v171
	v_div_scale_f32 v0, vcc, v168, v168, 1.0
	v_rcp_f32_e32 v1, v0
	s_nop 0
	v_fma_f32 v3, -v0, v1, 1.0
	v_fmac_f32_e32 v1, v3, v1
	v_div_scale_f32 v3, vcc, 1.0, v168, 1.0
	v_mul_f32_e32 v152, v3, v1
	v_fma_f32 v153, -v0, v152, v3
	v_fmac_f32_e32 v152, v153, v1
	v_fma_f32 v0, -v0, v152, v3
	v_div_fmas_f32 v0, v0, v1, v152
	v_div_fixup_f32 v168, v0, v168, 1.0
	v_mul_f32_e32 v168, v168, v172
	v_div_scale_f32 v0, vcc, v169, v169, 1.0
	v_rcp_f32_e32 v1, v0
	s_nop 0
	v_fma_f32 v3, -v0, v1, 1.0
	v_fmac_f32_e32 v1, v3, v1
	v_div_scale_f32 v3, vcc, 1.0, v169, 1.0
	v_mul_f32_e32 v152, v3, v1
	v_fma_f32 v153, -v0, v152, v3
	v_fmac_f32_e32 v152, v153, v1
	v_fma_f32 v0, -v0, v152, v3
	v_div_fmas_f32 v0, v0, v1, v152
	v_div_fixup_f32 v169, v0, v169, 1.0
	v_mul_f32_e32 v169, v169, v173
	v_div_scale_f32 v0, vcc, v170, v170, 1.0
	v_rcp_f32_e32 v1, v0
	s_nop 0
	v_fma_f32 v3, -v0, v1, 1.0
	v_fmac_f32_e32 v1, v3, v1
	v_div_scale_f32 v3, vcc, 1.0, v170, 1.0
	v_mul_f32_e32 v152, v3, v1
	v_fma_f32 v153, -v0, v152, v3
	v_fmac_f32_e32 v152, v153, v1
	v_fma_f32 v0, -v0, v152, v3
	v_div_fmas_f32 v0, v0, v1, v152
	v_div_fixup_f32 v170, v0, v170, 1.0
	v_mul_f32_e32 v170, v170, v174
	v_div_scale_f32 v0, vcc, v171, v171, 1.0
	v_rcp_f32_e32 v1, v0
	s_nop 0
	v_fma_f32 v3, -v0, v1, 1.0
	v_fmac_f32_e32 v1, v3, v1
	v_div_scale_f32 v3, vcc, 1.0, v171, 1.0
	v_mul_f32_e32 v152, v3, v1
	v_fma_f32 v153, -v0, v152, v3
	v_fmac_f32_e32 v152, v153, v1
	v_fma_f32 v0, -v0, v152, v3
	v_div_fmas_f32 v0, v0, v1, v152
	v_div_fixup_f32 v171, v0, v171, 1.0
	v_mul_f32_e32 v171, v171, v175
	v_cvt_pk_bf16_f32 v178, v168, v169
	v_cvt_pk_bf16_f32 v179, v170, v171
	global_store_dwordx2 v197, v[178:179], s[56:57] sc0 sc1
	v_add_u32_e32 v197, 0x2000, v197
	ds_write_b32 v203, v84 offset:0
	ds_write_b32 v203, v85 offset:272
	ds_write_b32 v203, v86 offset:544
	ds_write_b32 v203, v87 offset:816
	ds_write_b32 v203, v88 offset:64
	ds_write_b32 v203, v89 offset:336
	ds_write_b32 v203, v90 offset:608
	ds_write_b32 v203, v91 offset:880
	ds_write_b32 v203, v92 offset:128
	ds_write_b32 v203, v93 offset:400
	ds_write_b32 v203, v94 offset:672
	ds_write_b32 v203, v95 offset:944
	ds_write_b32 v203, v96 offset:192
	ds_write_b32 v203, v97 offset:464
	ds_write_b32 v203, v98 offset:736
	ds_write_b32 v203, v99 offset:1008
	s_waitcnt lgkmcnt(0)
	ds_read_b128 v[156:159], v204 offset:0
	ds_read_b128 v[160:163], v204 offset:1088
	ds_read_b128 v[164:167], v204 offset:2176
	ds_read_b128 v[168:171], v204 offset:3264
	s_waitcnt vmcnt(23)
	s_waitcnt lgkmcnt(3)
	v_add_f32_e32 v156, v156, v148
	v_add_f32_e32 v157, v157, v149
	v_add_f32_e32 v158, v158, v150
	v_add_f32_e32 v159, v159, v151
	v_mul_f32_e32 v156, 0xbfb8aa3b, v156
	v_mul_f32_e32 v157, 0xbfb8aa3b, v157
	v_mul_f32_e32 v158, 0xbfb8aa3b, v158
	v_mul_f32_e32 v159, 0xbfb8aa3b, v159
	v_exp_f32_e32 v156, v156
	v_exp_f32_e32 v157, v157
	v_exp_f32_e32 v158, v158
	v_exp_f32_e32 v159, v159
	v_lshlrev_b32_e32 v172, 16, v140
	v_and_b32_e32 v173, s28, v140
	v_lshlrev_b32_e32 v174, 16, v141
	v_and_b32_e32 v175, s28, v141
	v_add_f32_e32 v156, 1.0, v156
	v_add_f32_e32 v157, 1.0, v157
	v_add_f32_e32 v158, 1.0, v158
	v_add_f32_e32 v159, 1.0, v159
	v_div_scale_f32 v0, vcc, v156, v156, 1.0
	v_rcp_f32_e32 v1, v0
	s_nop 0
	v_fma_f32 v3, -v0, v1, 1.0
	v_fmac_f32_e32 v1, v3, v1
	v_div_scale_f32 v3, vcc, 1.0, v156, 1.0
	v_mul_f32_e32 v152, v3, v1
	v_fma_f32 v153, -v0, v152, v3
	v_fmac_f32_e32 v152, v153, v1
	v_fma_f32 v0, -v0, v152, v3
	v_div_fmas_f32 v0, v0, v1, v152
	v_div_fixup_f32 v156, v0, v156, 1.0
	v_mul_f32_e32 v156, v156, v172
	v_div_scale_f32 v0, vcc, v157, v157, 1.0
	v_rcp_f32_e32 v1, v0
	s_nop 0
	v_fma_f32 v3, -v0, v1, 1.0
	v_fmac_f32_e32 v1, v3, v1
	v_div_scale_f32 v3, vcc, 1.0, v157, 1.0
	v_mul_f32_e32 v152, v3, v1
	v_fma_f32 v153, -v0, v152, v3
	v_fmac_f32_e32 v152, v153, v1
	v_fma_f32 v0, -v0, v152, v3
	v_div_fmas_f32 v0, v0, v1, v152
	v_div_fixup_f32 v157, v0, v157, 1.0
	v_mul_f32_e32 v157, v157, v173
	v_div_scale_f32 v0, vcc, v158, v158, 1.0
	v_rcp_f32_e32 v1, v0
	s_nop 0
	v_fma_f32 v3, -v0, v1, 1.0
	v_fmac_f32_e32 v1, v3, v1
	v_div_scale_f32 v3, vcc, 1.0, v158, 1.0
	v_mul_f32_e32 v152, v3, v1
	v_fma_f32 v153, -v0, v152, v3
	v_fmac_f32_e32 v152, v153, v1
	v_fma_f32 v0, -v0, v152, v3
	v_div_fmas_f32 v0, v0, v1, v152
	v_div_fixup_f32 v158, v0, v158, 1.0
	v_mul_f32_e32 v158, v158, v174
	v_div_scale_f32 v0, vcc, v159, v159, 1.0
	v_rcp_f32_e32 v1, v0
	s_nop 0
	v_fma_f32 v3, -v0, v1, 1.0
	v_fmac_f32_e32 v1, v3, v1
	v_div_scale_f32 v3, vcc, 1.0, v159, 1.0
	v_mul_f32_e32 v152, v3, v1
	v_fma_f32 v153, -v0, v152, v3
	v_fmac_f32_e32 v152, v153, v1
	v_fma_f32 v0, -v0, v152, v3
	v_div_fmas_f32 v0, v0, v1, v152
	v_div_fixup_f32 v159, v0, v159, 1.0
	v_mul_f32_e32 v159, v159, v175
	v_cvt_pk_bf16_f32 v176, v156, v157
	v_cvt_pk_bf16_f32 v177, v158, v159
	global_store_dwordx2 v197, v[176:177], s[56:57] sc0 sc1
	v_add_u32_e32 v197, 0x2000, v197
	s_waitcnt vmcnt(23)
	s_waitcnt lgkmcnt(2)
	v_add_f32_e32 v160, v160, v148
	v_add_f32_e32 v161, v161, v149
	v_add_f32_e32 v162, v162, v150
	v_add_f32_e32 v163, v163, v151
	v_mul_f32_e32 v160, 0xbfb8aa3b, v160
	v_mul_f32_e32 v161, 0xbfb8aa3b, v161
	v_mul_f32_e32 v162, 0xbfb8aa3b, v162
	v_mul_f32_e32 v163, 0xbfb8aa3b, v163
	v_exp_f32_e32 v160, v160
	v_exp_f32_e32 v161, v161
	v_exp_f32_e32 v162, v162
	v_exp_f32_e32 v163, v163
	v_lshlrev_b32_e32 v172, 16, v142
	v_and_b32_e32 v173, s28, v142
	v_lshlrev_b32_e32 v174, 16, v143
	v_and_b32_e32 v175, s28, v143
	v_add_f32_e32 v160, 1.0, v160
	v_add_f32_e32 v161, 1.0, v161
	v_add_f32_e32 v162, 1.0, v162
	v_add_f32_e32 v163, 1.0, v163
	v_div_scale_f32 v0, vcc, v160, v160, 1.0
	v_rcp_f32_e32 v1, v0
	s_nop 0
	v_fma_f32 v3, -v0, v1, 1.0
	v_fmac_f32_e32 v1, v3, v1
	v_div_scale_f32 v3, vcc, 1.0, v160, 1.0
	v_mul_f32_e32 v152, v3, v1
	v_fma_f32 v153, -v0, v152, v3
	v_fmac_f32_e32 v152, v153, v1
	v_fma_f32 v0, -v0, v152, v3
	v_div_fmas_f32 v0, v0, v1, v152
	v_div_fixup_f32 v160, v0, v160, 1.0
	v_mul_f32_e32 v160, v160, v172
	v_div_scale_f32 v0, vcc, v161, v161, 1.0
	v_rcp_f32_e32 v1, v0
	s_nop 0
	v_fma_f32 v3, -v0, v1, 1.0
	v_fmac_f32_e32 v1, v3, v1
	v_div_scale_f32 v3, vcc, 1.0, v161, 1.0
	v_mul_f32_e32 v152, v3, v1
	v_fma_f32 v153, -v0, v152, v3
	v_fmac_f32_e32 v152, v153, v1
	v_fma_f32 v0, -v0, v152, v3
	v_div_fmas_f32 v0, v0, v1, v152
	v_div_fixup_f32 v161, v0, v161, 1.0
	v_mul_f32_e32 v161, v161, v173
	v_div_scale_f32 v0, vcc, v162, v162, 1.0
	v_rcp_f32_e32 v1, v0
	s_nop 0
	v_fma_f32 v3, -v0, v1, 1.0
	v_fmac_f32_e32 v1, v3, v1
	v_div_scale_f32 v3, vcc, 1.0, v162, 1.0
	v_mul_f32_e32 v152, v3, v1
	v_fma_f32 v153, -v0, v152, v3
	v_fmac_f32_e32 v152, v153, v1
	v_fma_f32 v0, -v0, v152, v3
	v_div_fmas_f32 v0, v0, v1, v152
	v_div_fixup_f32 v162, v0, v162, 1.0
	v_mul_f32_e32 v162, v162, v174
	v_div_scale_f32 v0, vcc, v163, v163, 1.0
	v_rcp_f32_e32 v1, v0
	s_nop 0
	v_fma_f32 v3, -v0, v1, 1.0
	v_fmac_f32_e32 v1, v3, v1
	v_div_scale_f32 v3, vcc, 1.0, v163, 1.0
	v_mul_f32_e32 v152, v3, v1
	v_fma_f32 v153, -v0, v152, v3
	v_fmac_f32_e32 v152, v153, v1
	v_fma_f32 v0, -v0, v152, v3
	v_div_fmas_f32 v0, v0, v1, v152
	v_div_fixup_f32 v163, v0, v163, 1.0
	v_mul_f32_e32 v163, v163, v175
	v_cvt_pk_bf16_f32 v178, v160, v161
	v_cvt_pk_bf16_f32 v179, v162, v163
	global_store_dwordx2 v197, v[178:179], s[56:57] sc0 sc1
	v_add_u32_e32 v197, 0x2000, v197
	s_waitcnt vmcnt(23)
	s_waitcnt lgkmcnt(1)
	v_add_f32_e32 v164, v164, v148
	v_add_f32_e32 v165, v165, v149
	v_add_f32_e32 v166, v166, v150
	v_add_f32_e32 v167, v167, v151
	v_mul_f32_e32 v164, 0xbfb8aa3b, v164
	v_mul_f32_e32 v165, 0xbfb8aa3b, v165
	v_mul_f32_e32 v166, 0xbfb8aa3b, v166
	v_mul_f32_e32 v167, 0xbfb8aa3b, v167
	v_exp_f32_e32 v164, v164
	v_exp_f32_e32 v165, v165
	v_exp_f32_e32 v166, v166
	v_exp_f32_e32 v167, v167
	v_lshlrev_b32_e32 v172, 16, v144
	v_and_b32_e32 v173, s28, v144
	v_lshlrev_b32_e32 v174, 16, v145
	v_and_b32_e32 v175, s28, v145
	v_add_f32_e32 v164, 1.0, v164
	v_add_f32_e32 v165, 1.0, v165
	v_add_f32_e32 v166, 1.0, v166
	v_add_f32_e32 v167, 1.0, v167
	v_div_scale_f32 v0, vcc, v164, v164, 1.0
	v_rcp_f32_e32 v1, v0
	s_nop 0
	v_fma_f32 v3, -v0, v1, 1.0
	v_fmac_f32_e32 v1, v3, v1
	v_div_scale_f32 v3, vcc, 1.0, v164, 1.0
	v_mul_f32_e32 v152, v3, v1
	v_fma_f32 v153, -v0, v152, v3
	v_fmac_f32_e32 v152, v153, v1
	v_fma_f32 v0, -v0, v152, v3
	v_div_fmas_f32 v0, v0, v1, v152
	v_div_fixup_f32 v164, v0, v164, 1.0
	v_mul_f32_e32 v164, v164, v172
	v_div_scale_f32 v0, vcc, v165, v165, 1.0
	v_rcp_f32_e32 v1, v0
	s_nop 0
	v_fma_f32 v3, -v0, v1, 1.0
	v_fmac_f32_e32 v1, v3, v1
	v_div_scale_f32 v3, vcc, 1.0, v165, 1.0
	v_mul_f32_e32 v152, v3, v1
	v_fma_f32 v153, -v0, v152, v3
	v_fmac_f32_e32 v152, v153, v1
	v_fma_f32 v0, -v0, v152, v3
	v_div_fmas_f32 v0, v0, v1, v152
	v_div_fixup_f32 v165, v0, v165, 1.0
	v_mul_f32_e32 v165, v165, v173
	v_div_scale_f32 v0, vcc, v166, v166, 1.0
	v_rcp_f32_e32 v1, v0
	s_nop 0
	v_fma_f32 v3, -v0, v1, 1.0
	v_fmac_f32_e32 v1, v3, v1
	v_div_scale_f32 v3, vcc, 1.0, v166, 1.0
	v_mul_f32_e32 v152, v3, v1
	v_fma_f32 v153, -v0, v152, v3
	v_fmac_f32_e32 v152, v153, v1
	v_fma_f32 v0, -v0, v152, v3
	v_div_fmas_f32 v0, v0, v1, v152
	v_div_fixup_f32 v166, v0, v166, 1.0
	v_mul_f32_e32 v166, v166, v174
	v_div_scale_f32 v0, vcc, v167, v167, 1.0
	v_rcp_f32_e32 v1, v0
	s_nop 0
	v_fma_f32 v3, -v0, v1, 1.0
	v_fmac_f32_e32 v1, v3, v1
	v_div_scale_f32 v3, vcc, 1.0, v167, 1.0
	v_mul_f32_e32 v152, v3, v1
	v_fma_f32 v153, -v0, v152, v3
	v_fmac_f32_e32 v152, v153, v1
	v_fma_f32 v0, -v0, v152, v3
	v_div_fmas_f32 v0, v0, v1, v152
	v_div_fixup_f32 v167, v0, v167, 1.0
	v_mul_f32_e32 v167, v167, v175
	v_cvt_pk_bf16_f32 v176, v164, v165
	v_cvt_pk_bf16_f32 v177, v166, v167
	global_store_dwordx2 v197, v[176:177], s[56:57] sc0 sc1
	v_add_u32_e32 v197, 0x2000, v197
	s_waitcnt vmcnt(23)
	s_waitcnt lgkmcnt(0)
	v_add_f32_e32 v168, v168, v148
	v_add_f32_e32 v169, v169, v149
	v_add_f32_e32 v170, v170, v150
	v_add_f32_e32 v171, v171, v151
	v_mul_f32_e32 v168, 0xbfb8aa3b, v168
	v_mul_f32_e32 v169, 0xbfb8aa3b, v169
	v_mul_f32_e32 v170, 0xbfb8aa3b, v170
	v_mul_f32_e32 v171, 0xbfb8aa3b, v171
	v_exp_f32_e32 v168, v168
	v_exp_f32_e32 v169, v169
	v_exp_f32_e32 v170, v170
	v_exp_f32_e32 v171, v171
	v_lshlrev_b32_e32 v172, 16, v146
	v_and_b32_e32 v173, s28, v146
	v_lshlrev_b32_e32 v174, 16, v147
	v_and_b32_e32 v175, s28, v147
	v_add_f32_e32 v168, 1.0, v168
	v_add_f32_e32 v169, 1.0, v169
	v_add_f32_e32 v170, 1.0, v170
	v_add_f32_e32 v171, 1.0, v171
	v_div_scale_f32 v0, vcc, v168, v168, 1.0
	v_rcp_f32_e32 v1, v0
	s_nop 0
	v_fma_f32 v3, -v0, v1, 1.0
	v_fmac_f32_e32 v1, v3, v1
	v_div_scale_f32 v3, vcc, 1.0, v168, 1.0
	v_mul_f32_e32 v152, v3, v1
	v_fma_f32 v153, -v0, v152, v3
	v_fmac_f32_e32 v152, v153, v1
	v_fma_f32 v0, -v0, v152, v3
	v_div_fmas_f32 v0, v0, v1, v152
	v_div_fixup_f32 v168, v0, v168, 1.0
	v_mul_f32_e32 v168, v168, v172
	v_div_scale_f32 v0, vcc, v169, v169, 1.0
	v_rcp_f32_e32 v1, v0
	s_nop 0
	v_fma_f32 v3, -v0, v1, 1.0
	v_fmac_f32_e32 v1, v3, v1
	v_div_scale_f32 v3, vcc, 1.0, v169, 1.0
	v_mul_f32_e32 v152, v3, v1
	v_fma_f32 v153, -v0, v152, v3
	v_fmac_f32_e32 v152, v153, v1
	v_fma_f32 v0, -v0, v152, v3
	v_div_fmas_f32 v0, v0, v1, v152
	v_div_fixup_f32 v169, v0, v169, 1.0
	v_mul_f32_e32 v169, v169, v173
	v_div_scale_f32 v0, vcc, v170, v170, 1.0
	v_rcp_f32_e32 v1, v0
	s_nop 0
	v_fma_f32 v3, -v0, v1, 1.0
	v_fmac_f32_e32 v1, v3, v1
	v_div_scale_f32 v3, vcc, 1.0, v170, 1.0
	v_mul_f32_e32 v152, v3, v1
	v_fma_f32 v153, -v0, v152, v3
	v_fmac_f32_e32 v152, v153, v1
	v_fma_f32 v0, -v0, v152, v3
	v_div_fmas_f32 v0, v0, v1, v152
	v_div_fixup_f32 v170, v0, v170, 1.0
	v_mul_f32_e32 v170, v170, v174
	v_div_scale_f32 v0, vcc, v171, v171, 1.0
	v_rcp_f32_e32 v1, v0
	s_nop 0
	v_fma_f32 v3, -v0, v1, 1.0
	v_fmac_f32_e32 v1, v3, v1
	v_div_scale_f32 v3, vcc, 1.0, v171, 1.0
	v_mul_f32_e32 v152, v3, v1
	v_fma_f32 v153, -v0, v152, v3
	v_fmac_f32_e32 v152, v153, v1
	v_fma_f32 v0, -v0, v152, v3
	v_div_fmas_f32 v0, v0, v1, v152
	v_div_fixup_f32 v171, v0, v171, 1.0
	v_mul_f32_e32 v171, v171, v175
	v_cvt_pk_bf16_f32 v178, v168, v169
	v_cvt_pk_bf16_f32 v179, v170, v171
	global_store_dwordx2 v197, v[178:179], s[56:57] sc0 sc1
	v_add_u32_e32 v197, 0x2000, v197
	v_mov_b32_e32 v4, 0
	v_mov_b32_e32 v5, 0
	v_mov_b32_e32 v6, 0
	v_mov_b32_e32 v7, 0
	v_mov_b32_e32 v8, 0
	v_mov_b32_e32 v9, 0
	v_mov_b32_e32 v10, 0
	v_mov_b32_e32 v11, 0
	v_mov_b32_e32 v12, 0
	v_mov_b32_e32 v13, 0
	v_mov_b32_e32 v14, 0
	v_mov_b32_e32 v15, 0
	v_mov_b32_e32 v16, 0
	v_mov_b32_e32 v17, 0
	v_mov_b32_e32 v18, 0
	v_mov_b32_e32 v19, 0
	v_mov_b32_e32 v20, 0
	v_mov_b32_e32 v21, 0
	v_mov_b32_e32 v22, 0
	v_mov_b32_e32 v23, 0
	v_mov_b32_e32 v24, 0
	v_mov_b32_e32 v25, 0
	v_mov_b32_e32 v26, 0
	v_mov_b32_e32 v27, 0
	v_mov_b32_e32 v28, 0
	v_mov_b32_e32 v29, 0
	v_mov_b32_e32 v30, 0
	v_mov_b32_e32 v31, 0
	v_mov_b32_e32 v32, 0
	v_mov_b32_e32 v33, 0
	v_mov_b32_e32 v34, 0
	v_mov_b32_e32 v35, 0
	v_mov_b32_e32 v36, 0
	v_mov_b32_e32 v37, 0
	v_mov_b32_e32 v38, 0
	v_mov_b32_e32 v39, 0
	v_mov_b32_e32 v40, 0
	v_mov_b32_e32 v41, 0
	v_mov_b32_e32 v42, 0
	v_mov_b32_e32 v43, 0
	v_mov_b32_e32 v44, 0
	v_mov_b32_e32 v45, 0
	v_mov_b32_e32 v46, 0
	v_mov_b32_e32 v47, 0
	v_mov_b32_e32 v48, 0
	v_mov_b32_e32 v49, 0
	v_mov_b32_e32 v50, 0
	v_mov_b32_e32 v51, 0
	v_mov_b32_e32 v52, 0
	v_mov_b32_e32 v53, 0
	v_mov_b32_e32 v54, 0
	v_mov_b32_e32 v55, 0
	v_mov_b32_e32 v56, 0
	v_mov_b32_e32 v57, 0
	v_mov_b32_e32 v58, 0
	v_mov_b32_e32 v59, 0
	v_mov_b32_e32 v60, 0
	v_mov_b32_e32 v61, 0
	v_mov_b32_e32 v62, 0
	v_mov_b32_e32 v63, 0
	v_mov_b32_e32 v64, 0
	v_mov_b32_e32 v65, 0
	v_mov_b32_e32 v66, 0
	v_mov_b32_e32 v67, 0
	v_mov_b32_e32 v68, 0
	v_mov_b32_e32 v69, 0
	v_mov_b32_e32 v70, 0
	v_mov_b32_e32 v71, 0
	v_mov_b32_e32 v72, 0
	v_mov_b32_e32 v73, 0
	v_mov_b32_e32 v74, 0
	v_mov_b32_e32 v75, 0
	v_mov_b32_e32 v76, 0
	v_mov_b32_e32 v77, 0
	v_mov_b32_e32 v78, 0
	v_mov_b32_e32 v79, 0
	v_mov_b32_e32 v80, 0
	v_mov_b32_e32 v81, 0
	v_mov_b32_e32 v82, 0
	v_mov_b32_e32 v83, 0
	v_mov_b32_e32 v84, 0
	v_mov_b32_e32 v85, 0
	v_mov_b32_e32 v86, 0
	v_mov_b32_e32 v87, 0
	v_mov_b32_e32 v88, 0
	v_mov_b32_e32 v89, 0
	v_mov_b32_e32 v90, 0
	v_mov_b32_e32 v91, 0
	v_mov_b32_e32 v92, 0
	v_mov_b32_e32 v93, 0
	v_mov_b32_e32 v94, 0
	v_mov_b32_e32 v95, 0
	v_mov_b32_e32 v96, 0
	v_mov_b32_e32 v97, 0
	v_mov_b32_e32 v98, 0
	v_mov_b32_e32 v99, 0
	s_mov_b32 s34, 0
	s_add_u32 s35, s35, s52
	s_cmp_ge_u32 s31, s30
	s_cbranch_scc1 .Lgm_glu_exit

.LBB0_312:
	s_andn2_b64 vcc, exec, s[38:39]
	s_cbranch_vccnz .LBB0_560
	v_readlane_b32 s4, v235, 63
	s_cmp_eq_u32 s4, 4
	s_cbranch_scc0 .LBB0_560
	s_branch .LBB0_560
